# v30: v23 with the per-cluster s_setprio toggles of the 8-phase GEMM main loops removed (static priority experiment)
# baseline (speedup 1.0000x reference)
; #define G8_STAGE(bufoff, gbase, voff) do { _Pragma("unroll") for (int _i = 0; _i < 2; ++_i) \
;         __builtin_amdgcn_global_load_lds((const unsigned*)((const char*)(gbase) + (voff)[_i]), (LAS unsigned*)(lds + (bufoff) + ldsw + _i * 8192), 16, 0, 0); } while (0)
; #define G8_LDA(dst, b, h) do { _Pragma("unroll") for (int m = 0; m < 4; ++m) _Pragma("unroll") for (int k = 0; k < 2; ++k) dst[m][k] = *(const LAS bf16x8*)(lds + G8_SA(b, h) + aoff + m * 2048 + k * 1024); } while (0)
; #define G8_LDB(dst, b, h) do { _Pragma("unroll") for (int n = 0; n < 2; ++n) _Pragma("unroll") for (int k = 0; k < 2; ++k) dst[n][k] = *(const LAS bf16x8*)(lds + G8_SB(b, h) + boff + n * 2048 + k * 1024); } while (0)
; #define G8_MMA(ai, bj, At, Bt) do { __builtin_amdgcn_s_setprio(1); _Pragma("unroll") for (int m = 0; m < 4; ++m) _Pragma("unroll") for (int n = 0; n < 2; ++n) _Pragma("unroll") for (int k = 0; k < 2; ++k) \
;         acc[ai][bj][m][n] = __builtin_amdgcn_mfma_f32_16x16x32_bf16(Bt[n][k], At[m][k], acc[ai][bj][m][n], 0, 0, 0); __builtin_amdgcn_s_setprio(0); } while (0)
; #define G8_WAIT_V(n) asm volatile("s_waitcnt vmcnt(" #n ")" ::: "memory")
; #define G8_WAIT_L(n) asm volatile("s_waitcnt lgkmcnt(" #n ")" ::: "memory")
; #define G8_BAR __builtin_amdgcn_s_barrier()
; #define G8_SCHED __builtin_amdgcn_sched_barrier(0)
; template <class Epi, class Sched>
; DEV void gemm_phase(LAS char* lds, const Sched& S, const Epi& E) {
;     ...
;             G8_LDB(B0, 0, 0); G8_LDB(B1, 0, 1); G8_SCHED; G8_LDA(At, 0, 0); G8_STAGE(G8_SA(1, 1), a1 + hstepA, voffA);
;             G8_WAIT_V(8); G8_WAIT_L(0); G8_BAR; G8_MMA(0, 0, At, B0); G8_MMA(0, 1, At, B1); G8_BAR; G8_SCHED;
;             G8_LDA(At, 0, 1); G8_STAGE(G8_SB(0, 0), b2, voffB); G8_STAGE(G8_SB(0, 1), b2 + hstepB, voffB); G8_STAGE(G8_SA(0, 0), a2, voffA);
;             G8_WAIT_V(8); G8_WAIT_L(0); G8_BAR; G8_MMA(1, 0, At, B0); G8_MMA(1, 1, At, B1); G8_BAR; G8_SCHED;
.LBB0_211:
	ds_read_b128 v[150:153], v165
	ds_read_b128 v[154:157], v165 offset:1024
	ds_read_b128 v[158:161], v165 offset:2048
	ds_read_b128 v[168:171], v165 offset:3072
	ds_read_b128 v[172:175], v166
	ds_read_b128 v[176:179], v166 offset:1024
	ds_read_b128 v[180:183], v166 offset:2048
	ds_read_b128 v[184:187], v166 offset:3072
	s_add_u32 s26, s22, s24
	s_addc_u32 s27, s23, s25
	s_add_u32 s30, s26, 0x100
	s_addc_u32 s31, s27, 0
	s_add_u32 s28, s55, s24
	s_addc_u32 s29, s56, s25
	s_add_u32 s26, s26, 0x180
	s_addc_u32 s27, s27, 0
	s_cmpk_eq_i32 s24, 0x700
	s_cselect_b32 s27, s54, s27
	s_cselect_b32 s26, s15, s26
	s_cselect_b32 s29, s19, s29
	s_cselect_b32 s28, s18, s28
	s_cselect_b32 s31, s17, s31
	s_cselect_b32 s30, s16, s30
	v_lshl_add_u64 v[220:221], v[148:149], 0, s[24:25]
	s_add_i32 m0, s40, 0xc000
	ds_read_b128 v[188:191], v167
	ds_read_b128 v[192:195], v167 offset:1024
	ds_read_b128 v[196:199], v167 offset:2048
	ds_read_b128 v[200:203], v167 offset:3072
	ds_read_b128 v[204:207], v167 offset:4096
	ds_read_b128 v[208:211], v167 offset:5120
	ds_read_b128 v[212:215], v167 offset:6144
	ds_read_b128 v[216:219], v167 offset:7168
	global_load_lds_dwordx4 v[220:221], off
	v_lshl_add_u64 v[220:221], v[146:147], 0, s[24:25]
	s_add_i32 m0, s40, 0xe000
	s_nop 0
	global_load_lds_dwordx4 v[220:221], off
	s_waitcnt vmcnt(8)
	s_waitcnt lgkmcnt(0)
	s_barrier
	s_nop 0
	s_waitcnt lgkmcnt(0)
	v_mfma_f32_16x16x32_bf16 v[126:129], v[150:153], v[188:191], v[126:129]
	v_mfma_f32_16x16x32_bf16 v[122:125], v[158:161], v[188:191], v[122:125]
	v_mfma_f32_16x16x32_bf16 v[118:121], v[150:153], v[196:199], v[118:121]
	v_mfma_f32_16x16x32_bf16 v[114:117], v[158:161], v[196:199], v[114:117]
	v_mfma_f32_16x16x32_bf16 v[110:113], v[150:153], v[204:207], v[110:113]
	v_mfma_f32_16x16x32_bf16 v[102:105], v[158:161], v[204:207], v[102:105]
	v_mfma_f32_16x16x32_bf16 v[94:97], v[150:153], v[212:215], v[94:97]
	v_mfma_f32_16x16x32_bf16 v[86:89], v[158:161], v[212:215], v[86:89]
	v_mfma_f32_16x16x32_bf16 v[126:129], v[154:157], v[192:195], v[126:129]
	v_mfma_f32_16x16x32_bf16 v[122:125], v[168:171], v[192:195], v[122:125]
	v_mfma_f32_16x16x32_bf16 v[118:121], v[154:157], v[200:203], v[118:121]
	v_mfma_f32_16x16x32_bf16 v[114:117], v[168:171], v[200:203], v[114:117]
	v_mfma_f32_16x16x32_bf16 v[110:113], v[154:157], v[208:211], v[110:113]
	v_mfma_f32_16x16x32_bf16 v[102:105], v[168:171], v[208:211], v[102:105]
	v_mfma_f32_16x16x32_bf16 v[94:97], v[154:157], v[216:219], v[94:97]
	v_mfma_f32_16x16x32_bf16 v[86:89], v[168:171], v[216:219], v[86:89]
	s_nop 0
	s_nop 0
	v_mfma_f32_16x16x32_bf16 v[106:109], v[172:175], v[188:191], v[106:109]
	v_mfma_f32_16x16x32_bf16 v[98:101], v[180:183], v[188:191], v[98:101]
	v_mfma_f32_16x16x32_bf16 v[90:93], v[172:175], v[196:199], v[90:93]
	v_mfma_f32_16x16x32_bf16 v[82:85], v[180:183], v[196:199], v[82:85]
	v_mfma_f32_16x16x32_bf16 v[78:81], v[172:175], v[204:207], v[78:81]
	v_mfma_f32_16x16x32_bf16 v[74:77], v[180:183], v[204:207], v[74:77]
	v_mfma_f32_16x16x32_bf16 v[70:73], v[172:175], v[212:215], v[70:73]
	v_mfma_f32_16x16x32_bf16 v[66:69], v[180:183], v[212:215], v[66:69]
	v_mfma_f32_16x16x32_bf16 v[106:109], v[176:179], v[192:195], v[106:109]
	v_mfma_f32_16x16x32_bf16 v[98:101], v[184:187], v[192:195], v[98:101]
	v_mfma_f32_16x16x32_bf16 v[90:93], v[176:179], v[200:203], v[90:93]
	v_mfma_f32_16x16x32_bf16 v[82:85], v[184:187], v[200:203], v[82:85]
	v_mfma_f32_16x16x32_bf16 v[78:81], v[176:179], v[208:211], v[78:81]
	v_mfma_f32_16x16x32_bf16 v[74:77], v[184:187], v[208:211], v[74:77]
	v_mfma_f32_16x16x32_bf16 v[70:73], v[176:179], v[216:219], v[70:73]
	v_mfma_f32_16x16x32_bf16 v[66:69], v[184:187], v[216:219], v[66:69]
	s_nop 0
	s_barrier
	s_add_i32 s58, s47, s39
	v_lshl_add_u64 v[220:221], s[28:29], 0, v[132:133]
	s_mov_b32 m0, s58
	ds_read_b128 v[188:191], v167 offset:16384
	ds_read_b128 v[192:195], v167 offset:17408
	ds_read_b128 v[196:199], v167 offset:18432
	ds_read_b128 v[200:203], v167 offset:19456
	ds_read_b128 v[204:207], v167 offset:20480
	ds_read_b128 v[208:211], v167 offset:21504
	ds_read_b128 v[212:215], v167 offset:22528
	ds_read_b128 v[216:219], v167 offset:23552
	global_load_lds_dwordx4 v[220:221], off
	s_add_i32 m0, s58, 0x2000
	s_add_u32 s58, s28, 0x40000
	v_lshl_add_u64 v[222:223], s[28:29], 0, v[136:137]
	s_addc_u32 s59, s29, 0
	s_add_i32 s60, s50, s39
	global_load_lds_dwordx4 v[222:223], off
	v_lshl_add_u64 v[224:225], s[58:59], 0, v[132:133]
	s_mov_b32 m0, s60
	s_nop 0
	global_load_lds_dwordx4 v[224:225], off
	v_lshl_add_u64 v[224:225], s[58:59], 0, v[136:137]
	s_add_i32 m0, s60, 0x2000
	s_nop 0
	global_load_lds_dwordx4 v[224:225], off
	v_lshl_add_u64 v[224:225], s[30:31], 0, v[130:131]
	s_mov_b32 m0, s40
	s_nop 0
	global_load_lds_dwordx4 v[224:225], off
	v_lshl_add_u64 v[224:225], s[30:31], 0, v[134:135]
	s_mov_b32 m0, s41
	s_nop 0
	global_load_lds_dwordx4 v[224:225], off
	s_waitcnt vmcnt(8)
	s_waitcnt lgkmcnt(0)
	s_barrier
; #define G8_STAGE(bufoff, gbase, voff) do { _Pragma("unroll") for (int _i = 0; _i < 2; ++_i) \
;         __builtin_amdgcn_global_load_lds((const unsigned*)((const char*)(gbase) + (voff)[_i]), (LAS unsigned*)(lds + (bufoff) + ldsw + _i * 8192), 16, 0, 0); } while (0)
; #define G8_LDA(dst, b, h) do { _Pragma("unroll") for (int m = 0; m < 4; ++m) _Pragma("unroll") for (int k = 0; k < 2; ++k) dst[m][k] = *(const LAS bf16x8*)(lds + G8_SA(b, h) + aoff + m * 2048 + k * 1024); } while (0)
; #define G8_LDB(dst, b, h) do { _Pragma("unroll") for (int n = 0; n < 2; ++n) _Pragma("unroll") for (int k = 0; k < 2; ++k) dst[n][k] = *(const LAS bf16x8*)(lds + G8_SB(b, h) + boff + n * 2048 + k * 1024); } while (0)
; #define G8_MMA(ai, bj, At, Bt) do { __builtin_amdgcn_s_setprio(1); _Pragma("unroll") for (int m = 0; m < 4; ++m) _Pragma("unroll") for (int n = 0; n < 2; ++n) _Pragma("unroll") for (int k = 0; k < 2; ++k) \
;         acc[ai][bj][m][n] = __builtin_amdgcn_mfma_f32_16x16x32_bf16(Bt[n][k], At[m][k], acc[ai][bj][m][n], 0, 0, 0); __builtin_amdgcn_s_setprio(0); } while (0)
; #define G8_WAIT_V(n) asm volatile("s_waitcnt vmcnt(" #n ")" ::: "memory")
; #define G8_WAIT_L(n) asm volatile("s_waitcnt lgkmcnt(" #n ")" ::: "memory")
; #define G8_BAR __builtin_amdgcn_s_barrier()
; #define G8_SCHED __builtin_amdgcn_sched_barrier(0)
; template <class Epi, class Sched>
; DEV void gemm_phase(LAS char* lds, const Sched& S, const Epi& E) {
;     ...
;             G8_WAIT_V(8); G8_WAIT_L(0); G8_BAR; G8_MMA(1, 0, At, B0); G8_MMA(1, 1, At, B1); G8_BAR; G8_SCHED;
;             G8_LDB(B0, 1, 0); G8_LDB(B1, 1, 1); G8_SCHED; G8_LDA(At, 1, 0); G8_STAGE(G8_SA(0, 1), a2 + hstepA, voffA);
;             G8_WAIT_V(8); G8_WAIT_L(0); G8_BAR; G8_MMA(0, 0, At, B0); G8_MMA(0, 1, At, B1); G8_BAR; G8_SCHED;
	s_nop 0
	s_waitcnt lgkmcnt(0)
	v_mfma_f32_16x16x32_bf16 v[62:65], v[150:153], v[188:191], v[62:65]
	v_mfma_f32_16x16x32_bf16 v[58:61], v[158:161], v[188:191], v[58:61]
	v_mfma_f32_16x16x32_bf16 v[54:57], v[150:153], v[196:199], v[54:57]
	v_mfma_f32_16x16x32_bf16 v[50:53], v[158:161], v[196:199], v[50:53]
	v_mfma_f32_16x16x32_bf16 v[46:49], v[150:153], v[204:207], v[46:49]
	v_mfma_f32_16x16x32_bf16 v[38:41], v[158:161], v[204:207], v[38:41]
	v_mfma_f32_16x16x32_bf16 v[30:33], v[150:153], v[212:215], v[30:33]
	v_mfma_f32_16x16x32_bf16 v[22:25], v[158:161], v[212:215], v[22:25]
	v_mfma_f32_16x16x32_bf16 v[62:65], v[154:157], v[192:195], v[62:65]
	v_mfma_f32_16x16x32_bf16 v[58:61], v[168:171], v[192:195], v[58:61]
	v_mfma_f32_16x16x32_bf16 v[54:57], v[154:157], v[200:203], v[54:57]
	v_mfma_f32_16x16x32_bf16 v[50:53], v[168:171], v[200:203], v[50:53]
	v_mfma_f32_16x16x32_bf16 v[46:49], v[154:157], v[208:211], v[46:49]
	v_mfma_f32_16x16x32_bf16 v[38:41], v[168:171], v[208:211], v[38:41]
	v_mfma_f32_16x16x32_bf16 v[30:33], v[154:157], v[216:219], v[30:33]
	v_mfma_f32_16x16x32_bf16 v[22:25], v[168:171], v[216:219], v[22:25]
	s_nop 0
	s_nop 0
	v_mfma_f32_16x16x32_bf16 v[42:45], v[172:175], v[188:191], v[42:45]
	v_mfma_f32_16x16x32_bf16 v[34:37], v[180:183], v[188:191], v[34:37]
	v_mfma_f32_16x16x32_bf16 v[26:29], v[172:175], v[196:199], v[26:29]
	v_mfma_f32_16x16x32_bf16 v[18:21], v[180:183], v[196:199], v[18:21]
	v_mfma_f32_16x16x32_bf16 v[14:17], v[172:175], v[204:207], v[14:17]
	v_mfma_f32_16x16x32_bf16 v[10:13], v[180:183], v[204:207], v[10:13]
	v_mfma_f32_16x16x32_bf16 v[6:9], v[172:175], v[212:215], v[6:9]
	v_mfma_f32_16x16x32_bf16 v[2:5], v[180:183], v[212:215], v[2:5]
	v_mfma_f32_16x16x32_bf16 v[42:45], v[176:179], v[192:195], v[42:45]
	v_mfma_f32_16x16x32_bf16 v[34:37], v[184:187], v[192:195], v[34:37]
	v_mfma_f32_16x16x32_bf16 v[26:29], v[176:179], v[200:203], v[26:29]
	v_mfma_f32_16x16x32_bf16 v[18:21], v[184:187], v[200:203], v[18:21]
	v_mfma_f32_16x16x32_bf16 v[14:17], v[176:179], v[208:211], v[14:17]
	v_mfma_f32_16x16x32_bf16 v[10:13], v[184:187], v[208:211], v[10:13]
	v_mfma_f32_16x16x32_bf16 v[6:9], v[176:179], v[216:219], v[6:9]
	v_mfma_f32_16x16x32_bf16 v[2:5], v[184:187], v[216:219], v[2:5]
	s_nop 0
	s_barrier
	s_add_i32 s58, 0, 0x18000
	v_add_u32_e32 v0, s58, v163
	s_add_i32 s59, 0, 0x1c000
	ds_read_b128 v[150:153], v0
	ds_read_b128 v[154:157], v0 offset:1024
	ds_read_b128 v[158:161], v0 offset:2048
	ds_read_b128 v[168:171], v0 offset:3072
	v_add_u32_e32 v0, s59, v163
	ds_read_b128 v[172:175], v0
	ds_read_b128 v[176:179], v0 offset:1024
	ds_read_b128 v[180:183], v0 offset:2048
	ds_read_b128 v[184:187], v0 offset:3072
	s_add_u32 s30, s30, 0x40000
	s_addc_u32 s31, s31, 0
	s_mov_b32 m0, s42
	v_lshl_add_u64 v[224:225], s[30:31], 0, v[130:131]
	ds_read_b128 v[188:191], v167 offset:32768
	ds_read_b128 v[192:195], v167 offset:33792
	ds_read_b128 v[196:199], v167 offset:34816
	ds_read_b128 v[200:203], v167 offset:35840
	ds_read_b128 v[204:207], v167 offset:36864
	ds_read_b128 v[208:211], v167 offset:37888
	ds_read_b128 v[212:215], v167 offset:38912
	ds_read_b128 v[216:219], v167 offset:39936
	global_load_lds_dwordx4 v[224:225], off
	v_lshl_add_u64 v[224:225], s[30:31], 0, v[134:135]
	s_mov_b32 m0, s43
	s_nop 0
	global_load_lds_dwordx4 v[224:225], off
	s_waitcnt vmcnt(8)
	s_waitcnt lgkmcnt(0)
	s_barrier
	s_nop 0
	s_waitcnt lgkmcnt(0)
	v_mfma_f32_16x16x32_bf16 v[126:129], v[150:153], v[188:191], v[126:129]
	v_mfma_f32_16x16x32_bf16 v[122:125], v[158:161], v[188:191], v[122:125]
	v_mfma_f32_16x16x32_bf16 v[118:121], v[150:153], v[196:199], v[118:121]
	v_mfma_f32_16x16x32_bf16 v[114:117], v[158:161], v[196:199], v[114:117]
	v_mfma_f32_16x16x32_bf16 v[110:113], v[150:153], v[204:207], v[110:113]
	v_mfma_f32_16x16x32_bf16 v[102:105], v[158:161], v[204:207], v[102:105]
	v_mfma_f32_16x16x32_bf16 v[94:97], v[150:153], v[212:215], v[94:97]
	v_mfma_f32_16x16x32_bf16 v[86:89], v[158:161], v[212:215], v[86:89]
	v_mfma_f32_16x16x32_bf16 v[126:129], v[154:157], v[192:195], v[126:129]
	v_mfma_f32_16x16x32_bf16 v[122:125], v[168:171], v[192:195], v[122:125]
	v_mfma_f32_16x16x32_bf16 v[118:121], v[154:157], v[200:203], v[118:121]
	v_mfma_f32_16x16x32_bf16 v[114:117], v[168:171], v[200:203], v[114:117]
	v_mfma_f32_16x16x32_bf16 v[110:113], v[154:157], v[208:211], v[110:113]
	v_mfma_f32_16x16x32_bf16 v[102:105], v[168:171], v[208:211], v[102:105]
	v_mfma_f32_16x16x32_bf16 v[94:97], v[154:157], v[216:219], v[94:97]
	v_mfma_f32_16x16x32_bf16 v[86:89], v[168:171], v[216:219], v[86:89]
	s_nop 0
	s_nop 0
	v_mfma_f32_16x16x32_bf16 v[106:109], v[172:175], v[188:191], v[106:109]
	v_mfma_f32_16x16x32_bf16 v[98:101], v[180:183], v[188:191], v[98:101]
	v_mfma_f32_16x16x32_bf16 v[90:93], v[172:175], v[196:199], v[90:93]
	v_mfma_f32_16x16x32_bf16 v[82:85], v[180:183], v[196:199], v[82:85]
	v_mfma_f32_16x16x32_bf16 v[78:81], v[172:175], v[204:207], v[78:81]
	v_mfma_f32_16x16x32_bf16 v[74:77], v[180:183], v[204:207], v[74:77]
	v_mfma_f32_16x16x32_bf16 v[70:73], v[172:175], v[212:215], v[70:73]
	v_mfma_f32_16x16x32_bf16 v[66:69], v[180:183], v[212:215], v[66:69]
	v_mfma_f32_16x16x32_bf16 v[106:109], v[176:179], v[192:195], v[106:109]
	v_mfma_f32_16x16x32_bf16 v[98:101], v[184:187], v[192:195], v[98:101]
	v_mfma_f32_16x16x32_bf16 v[90:93], v[176:179], v[200:203], v[90:93]
	v_mfma_f32_16x16x32_bf16 v[82:85], v[184:187], v[200:203], v[82:85]
	v_mfma_f32_16x16x32_bf16 v[78:81], v[176:179], v[208:211], v[78:81]
	v_mfma_f32_16x16x32_bf16 v[74:77], v[184:187], v[208:211], v[74:77]
	v_mfma_f32_16x16x32_bf16 v[70:73], v[176:179], v[216:219], v[70:73]
	v_mfma_f32_16x16x32_bf16 v[66:69], v[184:187], v[216:219], v[66:69]
	s_nop 0
	s_barrier
; #define G8_STAGE(bufoff, gbase, voff) do { _Pragma("unroll") for (int _i = 0; _i < 2; ++_i) \
;         __builtin_amdgcn_global_load_lds((const unsigned*)((const char*)(gbase) + (voff)[_i]), (LAS unsigned*)(lds + (bufoff) + ldsw + _i * 8192), 16, 0, 0); } while (0)
; #define G8_LDA(dst, b, h) do { _Pragma("unroll") for (int m = 0; m < 4; ++m) _Pragma("unroll") for (int k = 0; k < 2; ++k) dst[m][k] = *(const LAS bf16x8*)(lds + G8_SA(b, h) + aoff + m * 2048 + k * 1024); } while (0)
; #define G8_MMA(ai, bj, At, Bt) do { __builtin_amdgcn_s_setprio(1); _Pragma("unroll") for (int m = 0; m < 4; ++m) _Pragma("unroll") for (int n = 0; n < 2; ++n) _Pragma("unroll") for (int k = 0; k < 2; ++k) \
;         acc[ai][bj][m][n] = __builtin_amdgcn_mfma_f32_16x16x32_bf16(Bt[n][k], At[m][k], acc[ai][bj][m][n], 0, 0, 0); __builtin_amdgcn_s_setprio(0); } while (0)
; #define G8_WAIT_V(n) asm volatile("s_waitcnt vmcnt(" #n ")" ::: "memory")
; #define G8_WAIT_L(n) asm volatile("s_waitcnt lgkmcnt(" #n ")" ::: "memory")
; #define G8_BAR __builtin_amdgcn_s_barrier()
; #define G8_SCHED __builtin_amdgcn_sched_barrier(0)
; template <class Epi, class Sched>
; DEV void gemm_phase(LAS char* lds, const Sched& S, const Epi& E) {
;     ...
;             G8_LDA(At, 1, 1); G8_STAGE(G8_SB(1, 0), b3, voffB); G8_STAGE(G8_SB(1, 1), b3 + hstepB, voffB); G8_STAGE(G8_SA(1, 0), a3, voffA);
;             G8_WAIT_V(8); G8_WAIT_L(0); G8_BAR; G8_MMA(1, 0, At, B0); G8_MMA(1, 1, At, B1); G8_BAR; G8_SCHED;
;         }
;         if (wr == 0) G8_BAR;
	s_add_i32 s30, s58, s39
	v_lshl_add_u64 v[220:221], v[220:221], 0, s[8:9]
	s_mov_b32 m0, s30
	ds_read_b128 v[188:191], v167 offset:49152
	ds_read_b128 v[192:195], v167 offset:50176
	ds_read_b128 v[196:199], v167 offset:51200
	ds_read_b128 v[200:203], v167 offset:52224
	ds_read_b128 v[204:207], v167 offset:53248
	ds_read_b128 v[208:211], v167 offset:54272
	ds_read_b128 v[212:215], v167 offset:55296
	ds_read_b128 v[216:219], v167 offset:56320
	global_load_lds_dwordx4 v[220:221], off
	s_add_i32 m0, s30, 0x2000
	s_add_u32 s28, s28, 0x40080
	v_lshl_add_u64 v[220:221], v[222:223], 0, s[8:9]
	s_addc_u32 s29, s29, 0
	s_add_i32 s30, s59, s39
	global_load_lds_dwordx4 v[220:221], off
	v_lshl_add_u64 v[220:221], s[28:29], 0, v[132:133]
	s_mov_b32 m0, s30
	s_nop 0
	global_load_lds_dwordx4 v[220:221], off
	v_lshl_add_u64 v[220:221], s[28:29], 0, v[136:137]
	s_add_i32 m0, s30, 0x2000
	s_nop 0
	global_load_lds_dwordx4 v[220:221], off
	v_lshl_add_u64 v[220:221], s[26:27], 0, v[130:131]
	s_mov_b32 m0, s44
	s_nop 0
	global_load_lds_dwordx4 v[220:221], off
	v_lshl_add_u64 v[220:221], s[26:27], 0, v[134:135]
	s_mov_b32 m0, s45
	s_nop 0
	global_load_lds_dwordx4 v[220:221], off
	s_waitcnt vmcnt(8)
	s_waitcnt lgkmcnt(0)
	s_barrier
	s_nop 0
	s_waitcnt lgkmcnt(0)
	v_mfma_f32_16x16x32_bf16 v[62:65], v[150:153], v[188:191], v[62:65]
	v_mfma_f32_16x16x32_bf16 v[58:61], v[158:161], v[188:191], v[58:61]
	v_mfma_f32_16x16x32_bf16 v[54:57], v[150:153], v[196:199], v[54:57]
	v_mfma_f32_16x16x32_bf16 v[50:53], v[158:161], v[196:199], v[50:53]
	v_mfma_f32_16x16x32_bf16 v[46:49], v[150:153], v[204:207], v[46:49]
	v_mfma_f32_16x16x32_bf16 v[38:41], v[158:161], v[204:207], v[38:41]
	v_mfma_f32_16x16x32_bf16 v[30:33], v[150:153], v[212:215], v[30:33]
	v_mfma_f32_16x16x32_bf16 v[22:25], v[158:161], v[212:215], v[22:25]
	v_mfma_f32_16x16x32_bf16 v[62:65], v[154:157], v[192:195], v[62:65]
	v_mfma_f32_16x16x32_bf16 v[58:61], v[168:171], v[192:195], v[58:61]
	v_mfma_f32_16x16x32_bf16 v[54:57], v[154:157], v[200:203], v[54:57]
	v_mfma_f32_16x16x32_bf16 v[50:53], v[168:171], v[200:203], v[50:53]
	v_mfma_f32_16x16x32_bf16 v[46:49], v[154:157], v[208:211], v[46:49]
	v_mfma_f32_16x16x32_bf16 v[38:41], v[168:171], v[208:211], v[38:41]
	v_mfma_f32_16x16x32_bf16 v[30:33], v[154:157], v[216:219], v[30:33]
	v_mfma_f32_16x16x32_bf16 v[22:25], v[168:171], v[216:219], v[22:25]
	s_nop 0
	s_nop 0
	v_mfma_f32_16x16x32_bf16 v[42:45], v[172:175], v[188:191], v[42:45]
	v_mfma_f32_16x16x32_bf16 v[34:37], v[180:183], v[188:191], v[34:37]
	v_mfma_f32_16x16x32_bf16 v[26:29], v[172:175], v[196:199], v[26:29]
	v_mfma_f32_16x16x32_bf16 v[18:21], v[180:183], v[196:199], v[18:21]
	v_mfma_f32_16x16x32_bf16 v[14:17], v[172:175], v[204:207], v[14:17]
	v_mfma_f32_16x16x32_bf16 v[10:13], v[180:183], v[204:207], v[10:13]
	v_mfma_f32_16x16x32_bf16 v[6:9], v[172:175], v[212:215], v[6:9]
	v_mfma_f32_16x16x32_bf16 v[2:5], v[180:183], v[212:215], v[2:5]
	v_mfma_f32_16x16x32_bf16 v[42:45], v[176:179], v[192:195], v[42:45]
	v_mfma_f32_16x16x32_bf16 v[34:37], v[184:187], v[192:195], v[34:37]
	v_mfma_f32_16x16x32_bf16 v[26:29], v[176:179], v[200:203], v[26:29]
	v_mfma_f32_16x16x32_bf16 v[18:21], v[184:187], v[200:203], v[18:21]
	v_mfma_f32_16x16x32_bf16 v[14:17], v[176:179], v[208:211], v[14:17]
	v_mfma_f32_16x16x32_bf16 v[10:13], v[184:187], v[208:211], v[10:13]
	v_mfma_f32_16x16x32_bf16 v[6:9], v[176:179], v[216:219], v[6:9]
	v_mfma_f32_16x16x32_bf16 v[2:5], v[184:187], v[216:219], v[2:5]
	s_nop 0
	s_barrier
	s_add_i32 s57, s57, 2
	s_add_u32 s24, s24, 0x100
	s_addc_u32 s25, s25, 0
	s_cmp_gt_u32 s57, 13
	s_cbranch_scc0 .LBB0_211
	s_and_b64 vcc, exec, s[10:11]
	s_cbranch_vccz .LBB0_214
	s_barrier

; #define G8_STAGE(bufoff, gbase, voff) do { _Pragma("unroll") for (int _i = 0; _i < 2; ++_i) \
;         __builtin_amdgcn_global_load_lds((const unsigned*)((const char*)(gbase) + (voff)[_i]), (LAS unsigned*)(lds + (bufoff) + ldsw + _i * 8192), 16, 0, 0); } while (0)
; #define G8_LDA(dst, b, h) do { _Pragma("unroll") for (int m = 0; m < 4; ++m) _Pragma("unroll") for (int k = 0; k < 2; ++k) dst[m][k] = *(const LAS bf16x8*)(lds + G8_SA(b, h) + aoff + m * 2048 + k * 1024); } while (0)
; #define G8_LDB(dst, b, h) do { _Pragma("unroll") for (int n = 0; n < 2; ++n) _Pragma("unroll") for (int k = 0; k < 2; ++k) dst[n][k] = *(const LAS bf16x8*)(lds + G8_SB(b, h) + boff + n * 2048 + k * 1024); } while (0)
; #define G8_MMA(ai, bj, At, Bt) do { __builtin_amdgcn_s_setprio(1); _Pragma("unroll") for (int m = 0; m < 4; ++m) _Pragma("unroll") for (int n = 0; n < 2; ++n) _Pragma("unroll") for (int k = 0; k < 2; ++k) \
;         acc[ai][bj][m][n] = __builtin_amdgcn_mfma_f32_16x16x32_bf16(Bt[n][k], At[m][k], acc[ai][bj][m][n], 0, 0, 0); __builtin_amdgcn_s_setprio(0); } while (0)
; #define G8_WAIT_V(n) asm volatile("s_waitcnt vmcnt(" #n ")" ::: "memory")
; #define G8_WAIT_L(n) asm volatile("s_waitcnt lgkmcnt(" #n ")" ::: "memory")
; #define G8_BAR __builtin_amdgcn_s_barrier()
; #define G8_SCHED __builtin_amdgcn_sched_barrier(0)
; template <class Epi, class Sched>
; DEV void gemm_phase(LAS char* lds, const Sched& S, const Epi& E) {
;     ...
;             G8_LDB(B0, 0, 0); G8_LDB(B1, 0, 1); G8_SCHED; G8_LDA(At, 0, 0); G8_STAGE(G8_SA(1, 1), a1 + hstepA, voffA);
;             G8_WAIT_V(8); G8_WAIT_L(0); G8_BAR; G8_MMA(0, 0, At, B0); G8_MMA(0, 1, At, B1); G8_BAR; G8_SCHED;
;             G8_LDA(At, 0, 1); G8_STAGE(G8_SB(0, 0), b2, voffB); G8_STAGE(G8_SB(0, 1), b2 + hstepB, voffB); G8_STAGE(G8_SA(0, 0), a2, voffA);
;             G8_WAIT_V(8); G8_WAIT_L(0); G8_BAR; G8_MMA(1, 0, At, B0); G8_MMA(1, 1, At, B1); G8_BAR; G8_SCHED;
.LBB0_464:
	ds_read_b128 v[62:65], v245
	ds_read_b128 v[70:73], v245 offset:1024
	ds_read_b128 v[78:81], v245 offset:2048
	ds_read_b128 v[82:85], v245 offset:3072
	ds_read_b128 v[90:93], v246
	ds_read_b128 v[98:101], v246 offset:1024
	ds_read_b128 v[110:113], v246 offset:2048
	ds_read_b128 v[122:125], v246 offset:3072
	s_add_u32 s42, s38, s40
	s_addc_u32 s43, s39, s41
	s_add_u32 s60, s42, 0x400000
	s_addc_u32 s61, s43, 0
	s_add_u32 s42, s42, 0x600000
	s_addc_u32 s43, s43, 0
	s_cmp_eq_u32 s40, 0x1c00000
	s_cselect_b32 s43, s1, s43
	s_cselect_b32 s42, s0, s42
	s_cselect_b32 s59, s31, s27
	s_cselect_b32 s58, s30, s15
	s_cselect_b32 s61, s29, s61
	s_cselect_b32 s60, s28, s60
	v_lshl_add_u64 v[198:199], v[60:61], 0, s[40:41]
	s_add_i32 m0, s51, 0xc000
	ds_read_b128 v[134:137], v247
	ds_read_b128 v[146:149], v247 offset:1024
	ds_read_b128 v[158:161], v247 offset:2048
	ds_read_b128 v[166:169], v247 offset:3072
	ds_read_b128 v[174:177], v247 offset:4096
	ds_read_b128 v[182:185], v247 offset:5120
	ds_read_b128 v[190:193], v247 offset:6144
	ds_read_b128 v[194:197], v247 offset:7168
	global_load_lds_dwordx4 v[198:199], off
	v_lshl_add_u64 v[198:199], v[58:59], 0, s[40:41]
	s_add_i32 m0, s51, 0xe000
	s_nop 0
	global_load_lds_dwordx4 v[198:199], off
	s_waitcnt vmcnt(8)
	s_waitcnt lgkmcnt(0)
	s_barrier
	s_nop 0
	s_waitcnt lgkmcnt(0)
	v_mfma_f32_16x16x32_bf16 v[186:189], v[62:65], v[134:137], v[186:189]
	v_mfma_f32_16x16x32_bf16 v[178:181], v[78:81], v[134:137], v[178:181]
	v_mfma_f32_16x16x32_bf16 v[154:157], v[62:65], v[158:161], v[154:157]
	v_mfma_f32_16x16x32_bf16 v[150:153], v[78:81], v[158:161], v[150:153]
	v_mfma_f32_16x16x32_bf16 v[130:133], v[62:65], v[174:177], v[130:133]
	v_mfma_f32_16x16x32_bf16 v[126:129], v[78:81], v[174:177], v[126:129]
	v_mfma_f32_16x16x32_bf16 v[106:109], v[62:65], v[190:193], v[106:109]
	v_mfma_f32_16x16x32_bf16 v[102:105], v[78:81], v[190:193], v[102:105]
	v_mfma_f32_16x16x32_bf16 v[186:189], v[70:73], v[146:149], v[186:189]
	v_mfma_f32_16x16x32_bf16 v[178:181], v[82:85], v[146:149], v[178:181]
	v_mfma_f32_16x16x32_bf16 v[154:157], v[70:73], v[166:169], v[154:157]
	v_mfma_f32_16x16x32_bf16 v[150:153], v[82:85], v[166:169], v[150:153]
	v_mfma_f32_16x16x32_bf16 v[130:133], v[70:73], v[182:185], v[130:133]
	v_mfma_f32_16x16x32_bf16 v[126:129], v[82:85], v[182:185], v[126:129]
	v_mfma_f32_16x16x32_bf16 v[106:109], v[70:73], v[194:197], v[106:109]
	v_mfma_f32_16x16x32_bf16 v[102:105], v[82:85], v[194:197], v[102:105]
	s_nop 0
	s_nop 0
	v_mfma_f32_16x16x32_bf16 v[170:173], v[90:93], v[134:137], v[170:173]
	v_mfma_f32_16x16x32_bf16 v[142:145], v[90:93], v[158:161], v[142:145]
	v_mfma_f32_16x16x32_bf16 v[138:141], v[110:113], v[158:161], v[138:141]
	v_mfma_f32_16x16x32_bf16 v[118:121], v[90:93], v[174:177], v[118:121]
	v_mfma_f32_16x16x32_bf16 v[114:117], v[110:113], v[174:177], v[114:117]
	v_mfma_f32_16x16x32_bf16 v[94:97], v[90:93], v[190:193], v[94:97]
	v_mfma_f32_16x16x32_bf16 v[86:89], v[110:113], v[190:193], v[86:89]
	v_mfma_f32_16x16x32_bf16 v[170:173], v[98:101], v[146:149], v[170:173]
	v_mfma_f32_16x16x32_bf16 v[134:137], v[110:113], v[134:137], v[162:165]
	v_mfma_f32_16x16x32_bf16 v[142:145], v[98:101], v[166:169], v[142:145]
	v_mfma_f32_16x16x32_bf16 v[138:141], v[122:125], v[166:169], v[138:141]
	v_mfma_f32_16x16x32_bf16 v[118:121], v[98:101], v[182:185], v[118:121]
	v_mfma_f32_16x16x32_bf16 v[114:117], v[122:125], v[182:185], v[114:117]
	v_mfma_f32_16x16x32_bf16 v[94:97], v[98:101], v[194:197], v[94:97]
	v_mfma_f32_16x16x32_bf16 v[86:89], v[122:125], v[194:197], v[86:89]
	v_mfma_f32_16x16x32_bf16 v[134:137], v[122:125], v[146:149], v[134:137]
	s_nop 0
	s_barrier
	s_add_i32 s72, s68, s13
	v_lshl_add_u64 v[202:203], s[58:59], 0, v[212:213]
	s_mov_b32 m0, s72
	ds_read_b128 v[146:149], v247 offset:16384
	ds_read_b128 v[158:161], v247 offset:17408
	ds_read_b128 v[162:165], v247 offset:18432
	ds_read_b128 v[166:169], v247 offset:19456
	ds_read_b128 v[174:177], v247 offset:20480
	ds_read_b128 v[182:185], v247 offset:21504
	ds_read_b128 v[190:193], v247 offset:22528
	ds_read_b128 v[194:197], v247 offset:23552
	global_load_lds_dwordx4 v[202:203], off
	s_add_i32 m0, s72, 0x2000
	s_add_u32 s72, s58, 0x40000
	v_lshl_add_u64 v[204:205], s[58:59], 0, v[216:217]
	s_addc_u32 s73, s59, 0
	s_add_i32 s74, s69, s13
	global_load_lds_dwordx4 v[204:205], off
	v_lshl_add_u64 v[198:199], s[72:73], 0, v[212:213]
	s_mov_b32 m0, s74
	s_nop 0
	global_load_lds_dwordx4 v[198:199], off
	v_lshl_add_u64 v[198:199], s[72:73], 0, v[216:217]
	s_add_i32 m0, s74, 0x2000
	s_nop 0
	global_load_lds_dwordx4 v[198:199], off
	v_lshl_add_u64 v[198:199], s[60:61], 0, v[210:211]
	s_mov_b32 m0, s51
	s_nop 0
	global_load_lds_dwordx4 v[198:199], off
	v_lshl_add_u64 v[198:199], s[60:61], 0, v[214:215]
	s_mov_b32 m0, s54
	s_nop 0
	global_load_lds_dwordx4 v[198:199], off
	s_waitcnt vmcnt(8)
	s_waitcnt lgkmcnt(0)
	s_barrier
; #define G8_STAGE(bufoff, gbase, voff) do { _Pragma("unroll") for (int _i = 0; _i < 2; ++_i) \
;         __builtin_amdgcn_global_load_lds((const unsigned*)((const char*)(gbase) + (voff)[_i]), (LAS unsigned*)(lds + (bufoff) + ldsw + _i * 8192), 16, 0, 0); } while (0)
; #define G8_LDA(dst, b, h) do { _Pragma("unroll") for (int m = 0; m < 4; ++m) _Pragma("unroll") for (int k = 0; k < 2; ++k) dst[m][k] = *(const LAS bf16x8*)(lds + G8_SA(b, h) + aoff + m * 2048 + k * 1024); } while (0)
; #define G8_LDB(dst, b, h) do { _Pragma("unroll") for (int n = 0; n < 2; ++n) _Pragma("unroll") for (int k = 0; k < 2; ++k) dst[n][k] = *(const LAS bf16x8*)(lds + G8_SB(b, h) + boff + n * 2048 + k * 1024); } while (0)
; #define G8_MMA(ai, bj, At, Bt) do { __builtin_amdgcn_s_setprio(1); _Pragma("unroll") for (int m = 0; m < 4; ++m) _Pragma("unroll") for (int n = 0; n < 2; ++n) _Pragma("unroll") for (int k = 0; k < 2; ++k) \
;         acc[ai][bj][m][n] = __builtin_amdgcn_mfma_f32_16x16x32_bf16(Bt[n][k], At[m][k], acc[ai][bj][m][n], 0, 0, 0); __builtin_amdgcn_s_setprio(0); } while (0)
; #define G8_WAIT_V(n) asm volatile("s_waitcnt vmcnt(" #n ")" ::: "memory")
; #define G8_WAIT_L(n) asm volatile("s_waitcnt lgkmcnt(" #n ")" ::: "memory")
; #define G8_BAR __builtin_amdgcn_s_barrier()
; #define G8_SCHED __builtin_amdgcn_sched_barrier(0)
; template <class Epi, class Sched>
; DEV void gemm_phase(LAS char* lds, const Sched& S, const Epi& E) {
;     ...
;             G8_WAIT_V(8); G8_WAIT_L(0); G8_BAR; G8_MMA(1, 0, At, B0); G8_MMA(1, 1, At, B1); G8_BAR; G8_SCHED;
;             G8_LDB(B0, 1, 0); G8_LDB(B1, 1, 1); G8_SCHED; G8_LDA(At, 1, 0); G8_STAGE(G8_SA(0, 1), a2 + hstepA, voffA);
;             G8_WAIT_V(8); G8_WAIT_L(0); G8_BAR; G8_MMA(0, 0, At, B0); G8_MMA(0, 1, At, B1); G8_BAR; G8_SCHED;
	s_nop 0
	s_waitcnt lgkmcnt(0)
	v_mfma_f32_16x16x32_bf16 v[74:77], v[62:65], v[146:149], v[74:77]
	v_mfma_f32_16x16x32_bf16 v[66:69], v[78:81], v[146:149], v[66:69]
	v_mfma_f32_16x16x32_bf16 v[46:49], v[62:65], v[162:165], v[46:49]
	v_mfma_f32_16x16x32_bf16 v[42:45], v[78:81], v[162:165], v[42:45]
	v_mfma_f32_16x16x32_bf16 v[30:33], v[62:65], v[174:177], v[30:33]
	v_mfma_f32_16x16x32_bf16 v[26:29], v[78:81], v[174:177], v[26:29]
	v_mfma_f32_16x16x32_bf16 v[14:17], v[62:65], v[190:193], v[14:17]
	v_mfma_f32_16x16x32_bf16 v[10:13], v[78:81], v[190:193], v[10:13]
	v_mfma_f32_16x16x32_bf16 v[74:77], v[70:73], v[158:161], v[74:77]
	v_mfma_f32_16x16x32_bf16 v[66:69], v[82:85], v[158:161], v[66:69]
	v_mfma_f32_16x16x32_bf16 v[46:49], v[70:73], v[166:169], v[46:49]
	v_mfma_f32_16x16x32_bf16 v[42:45], v[82:85], v[166:169], v[42:45]
	v_mfma_f32_16x16x32_bf16 v[30:33], v[70:73], v[182:185], v[30:33]
	v_mfma_f32_16x16x32_bf16 v[26:29], v[82:85], v[182:185], v[26:29]
	v_mfma_f32_16x16x32_bf16 v[14:17], v[70:73], v[194:197], v[14:17]
	v_mfma_f32_16x16x32_bf16 v[10:13], v[82:85], v[194:197], v[10:13]
	s_nop 0
	s_nop 0
	v_mfma_f32_16x16x32_bf16 v[54:57], v[90:93], v[146:149], v[54:57]
	v_mfma_f32_16x16x32_bf16 v[50:53], v[110:113], v[146:149], v[50:53]
	v_mfma_f32_16x16x32_bf16 v[38:41], v[90:93], v[162:165], v[38:41]
	v_mfma_f32_16x16x32_bf16 v[34:37], v[110:113], v[162:165], v[34:37]
	v_mfma_f32_16x16x32_bf16 v[22:25], v[90:93], v[174:177], v[22:25]
	v_mfma_f32_16x16x32_bf16 v[18:21], v[110:113], v[174:177], v[18:21]
	v_mfma_f32_16x16x32_bf16 v[6:9], v[90:93], v[190:193], v[6:9]
	v_mfma_f32_16x16x32_bf16 v[2:5], v[110:113], v[190:193], v[2:5]
	v_mfma_f32_16x16x32_bf16 v[54:57], v[98:101], v[158:161], v[54:57]
	v_mfma_f32_16x16x32_bf16 v[50:53], v[122:125], v[158:161], v[50:53]
	v_mfma_f32_16x16x32_bf16 v[38:41], v[98:101], v[166:169], v[38:41]
	v_mfma_f32_16x16x32_bf16 v[34:37], v[122:125], v[166:169], v[34:37]
	v_mfma_f32_16x16x32_bf16 v[22:25], v[98:101], v[182:185], v[22:25]
	v_mfma_f32_16x16x32_bf16 v[18:21], v[122:125], v[182:185], v[18:21]
	v_mfma_f32_16x16x32_bf16 v[6:9], v[98:101], v[194:197], v[6:9]
	v_mfma_f32_16x16x32_bf16 v[2:5], v[122:125], v[194:197], v[2:5]
	s_nop 0
	s_barrier
	s_add_i32 s72, 0, 0x18000
	s_add_i32 s73, 0, 0x1c000
	v_add_u32_e32 v82, s72, v242
	v_add_u32_e32 v122, s73, v242
	ds_read_b128 v[62:65], v82
	ds_read_b128 v[70:73], v82 offset:1024
	ds_read_b128 v[78:81], v82 offset:2048
	ds_read_b128 v[82:85], v82 offset:3072
	ds_read_b128 v[90:93], v122
	ds_read_b128 v[98:101], v122 offset:1024
	ds_read_b128 v[110:113], v122 offset:2048
	ds_read_b128 v[122:125], v122 offset:3072
	s_add_u32 s60, s60, 0x1000
	s_addc_u32 s61, s61, 0
	s_mov_b32 m0, s55
	v_lshl_add_u64 v[162:163], s[60:61], 0, v[210:211]
	ds_read_b128 v[146:149], v247 offset:32768
	ds_read_b128 v[158:161], v247 offset:33792
	ds_read_b128 v[166:169], v247 offset:34816
	ds_read_b128 v[174:177], v247 offset:35840
	ds_read_b128 v[182:185], v247 offset:36864
	ds_read_b128 v[190:193], v247 offset:37888
	ds_read_b128 v[194:197], v247 offset:38912
	ds_read_b128 v[198:201], v247 offset:39936
	global_load_lds_dwordx4 v[162:163], off
	v_lshl_add_u64 v[162:163], s[60:61], 0, v[214:215]
	s_mov_b32 m0, s56
	s_nop 0
	global_load_lds_dwordx4 v[162:163], off
	s_waitcnt vmcnt(8)
	s_waitcnt lgkmcnt(0)
	s_barrier
	s_nop 0
	s_waitcnt lgkmcnt(0)
	v_mfma_f32_16x16x32_bf16 v[162:165], v[62:65], v[146:149], v[186:189]
	v_mfma_f32_16x16x32_bf16 v[186:189], v[70:73], v[158:161], v[162:165]
	v_mfma_f32_16x16x32_bf16 v[162:165], v[78:81], v[146:149], v[178:181]
	v_mfma_f32_16x16x32_bf16 v[154:157], v[62:65], v[166:169], v[154:157]
	v_mfma_f32_16x16x32_bf16 v[150:153], v[78:81], v[166:169], v[150:153]
	v_mfma_f32_16x16x32_bf16 v[130:133], v[62:65], v[182:185], v[130:133]
	v_mfma_f32_16x16x32_bf16 v[126:129], v[78:81], v[182:185], v[126:129]
	v_mfma_f32_16x16x32_bf16 v[106:109], v[62:65], v[194:197], v[106:109]
	v_mfma_f32_16x16x32_bf16 v[102:105], v[78:81], v[194:197], v[102:105]
	v_mfma_f32_16x16x32_bf16 v[178:181], v[82:85], v[158:161], v[162:165]
	v_mfma_f32_16x16x32_bf16 v[154:157], v[70:73], v[174:177], v[154:157]
	v_mfma_f32_16x16x32_bf16 v[150:153], v[82:85], v[174:177], v[150:153]
	v_mfma_f32_16x16x32_bf16 v[130:133], v[70:73], v[190:193], v[130:133]
	v_mfma_f32_16x16x32_bf16 v[126:129], v[82:85], v[190:193], v[126:129]
	v_mfma_f32_16x16x32_bf16 v[106:109], v[70:73], v[198:201], v[106:109]
	v_mfma_f32_16x16x32_bf16 v[102:105], v[82:85], v[198:201], v[102:105]
	s_nop 0
	s_nop 0
	v_mfma_f32_16x16x32_bf16 v[162:165], v[90:93], v[146:149], v[170:173]
	v_mfma_f32_16x16x32_bf16 v[134:137], v[110:113], v[146:149], v[134:137]
	v_mfma_f32_16x16x32_bf16 v[170:173], v[98:101], v[158:161], v[162:165]
	v_mfma_f32_16x16x32_bf16 v[162:165], v[122:125], v[158:161], v[134:137]
	v_mfma_f32_16x16x32_bf16 v[134:137], v[90:93], v[166:169], v[142:145]
	v_mfma_f32_16x16x32_bf16 v[142:145], v[98:101], v[174:177], v[134:137]
	v_mfma_f32_16x16x32_bf16 v[134:137], v[110:113], v[166:169], v[138:141]
	v_mfma_f32_16x16x32_bf16 v[118:121], v[90:93], v[182:185], v[118:121]
	v_mfma_f32_16x16x32_bf16 v[114:117], v[110:113], v[182:185], v[114:117]
	v_mfma_f32_16x16x32_bf16 v[94:97], v[90:93], v[194:197], v[94:97]
	v_mfma_f32_16x16x32_bf16 v[86:89], v[110:113], v[194:197], v[86:89]
	v_mfma_f32_16x16x32_bf16 v[138:141], v[122:125], v[174:177], v[134:137]
	v_mfma_f32_16x16x32_bf16 v[118:121], v[98:101], v[190:193], v[118:121]
	v_mfma_f32_16x16x32_bf16 v[114:117], v[122:125], v[190:193], v[114:117]
	v_mfma_f32_16x16x32_bf16 v[94:97], v[98:101], v[198:201], v[94:97]
	v_mfma_f32_16x16x32_bf16 v[86:89], v[122:125], v[198:201], v[86:89]
	s_nop 0
	s_barrier
; #define G8_STAGE(bufoff, gbase, voff) do { _Pragma("unroll") for (int _i = 0; _i < 2; ++_i) \
;         __builtin_amdgcn_global_load_lds((const unsigned*)((const char*)(gbase) + (voff)[_i]), (LAS unsigned*)(lds + (bufoff) + ldsw + _i * 8192), 16, 0, 0); } while (0)
; #define G8_LDA(dst, b, h) do { _Pragma("unroll") for (int m = 0; m < 4; ++m) _Pragma("unroll") for (int k = 0; k < 2; ++k) dst[m][k] = *(const LAS bf16x8*)(lds + G8_SA(b, h) + aoff + m * 2048 + k * 1024); } while (0)
; #define G8_MMA(ai, bj, At, Bt) do { __builtin_amdgcn_s_setprio(1); _Pragma("unroll") for (int m = 0; m < 4; ++m) _Pragma("unroll") for (int n = 0; n < 2; ++n) _Pragma("unroll") for (int k = 0; k < 2; ++k) \
;         acc[ai][bj][m][n] = __builtin_amdgcn_mfma_f32_16x16x32_bf16(Bt[n][k], At[m][k], acc[ai][bj][m][n], 0, 0, 0); __builtin_amdgcn_s_setprio(0); } while (0)
; #define G8_WAIT_V(n) asm volatile("s_waitcnt vmcnt(" #n ")" ::: "memory")
; #define G8_WAIT_L(n) asm volatile("s_waitcnt lgkmcnt(" #n ")" ::: "memory")
; #define G8_BAR __builtin_amdgcn_s_barrier()
; #define G8_SCHED __builtin_amdgcn_sched_barrier(0)
; template <class Epi, class Sched>
; DEV void gemm_phase(LAS char* lds, const Sched& S, const Epi& E) {
;     ...
;             G8_LDA(At, 1, 1); G8_STAGE(G8_SB(1, 0), b3, voffB); G8_STAGE(G8_SB(1, 1), b3 + hstepB, voffB); G8_STAGE(G8_SA(1, 0), a3, voffA);
;             G8_WAIT_V(8); G8_WAIT_L(0); G8_BAR; G8_MMA(1, 0, At, B0); G8_MMA(1, 1, At, B1); G8_BAR; G8_SCHED;
;         }
;         if (wr == 0) G8_BAR;
	s_add_i32 s60, s72, s13
	v_lshl_add_u64 v[198:199], v[202:203], 0, s[22:23]
	s_mov_b32 m0, s60
	ds_read_b128 v[134:137], v247 offset:49152
	ds_read_b128 v[146:149], v247 offset:50176
	ds_read_b128 v[158:161], v247 offset:51200
	ds_read_b128 v[166:169], v247 offset:52224
	ds_read_b128 v[174:177], v247 offset:53248
	ds_read_b128 v[182:185], v247 offset:54272
	ds_read_b128 v[190:193], v247 offset:55296
	ds_read_b128 v[194:197], v247 offset:56320
	global_load_lds_dwordx4 v[198:199], off
	s_add_i32 m0, s60, 0x2000
	s_add_u32 s58, s58, 0x40080
	v_lshl_add_u64 v[198:199], v[204:205], 0, s[22:23]
	s_addc_u32 s59, s59, 0
	s_add_i32 s60, s73, s13
	global_load_lds_dwordx4 v[198:199], off
	v_lshl_add_u64 v[198:199], s[58:59], 0, v[212:213]
	s_mov_b32 m0, s60
	s_nop 0
	global_load_lds_dwordx4 v[198:199], off
	v_lshl_add_u64 v[198:199], s[58:59], 0, v[216:217]
	s_add_i32 m0, s60, 0x2000
	s_nop 0
	global_load_lds_dwordx4 v[198:199], off
	v_lshl_add_u64 v[198:199], s[42:43], 0, v[210:211]
	s_mov_b32 m0, s65
	s_nop 0
	global_load_lds_dwordx4 v[198:199], off
	v_lshl_add_u64 v[198:199], s[42:43], 0, v[214:215]
	s_mov_b32 m0, s66
	s_nop 0
	global_load_lds_dwordx4 v[198:199], off
	s_waitcnt vmcnt(8)
	s_waitcnt lgkmcnt(0)
	s_barrier
	s_nop 0
	s_waitcnt lgkmcnt(0)
	v_mfma_f32_16x16x32_bf16 v[74:77], v[62:65], v[134:137], v[74:77]
	v_mfma_f32_16x16x32_bf16 v[66:69], v[78:81], v[134:137], v[66:69]
	v_mfma_f32_16x16x32_bf16 v[46:49], v[62:65], v[158:161], v[46:49]
	v_mfma_f32_16x16x32_bf16 v[42:45], v[78:81], v[158:161], v[42:45]
	v_mfma_f32_16x16x32_bf16 v[30:33], v[62:65], v[174:177], v[30:33]
	v_mfma_f32_16x16x32_bf16 v[26:29], v[78:81], v[174:177], v[26:29]
	v_mfma_f32_16x16x32_bf16 v[14:17], v[62:65], v[190:193], v[14:17]
	v_mfma_f32_16x16x32_bf16 v[10:13], v[78:81], v[190:193], v[10:13]
	v_mfma_f32_16x16x32_bf16 v[74:77], v[70:73], v[146:149], v[74:77]
	v_mfma_f32_16x16x32_bf16 v[66:69], v[82:85], v[146:149], v[66:69]
	v_mfma_f32_16x16x32_bf16 v[46:49], v[70:73], v[166:169], v[46:49]
	v_mfma_f32_16x16x32_bf16 v[42:45], v[82:85], v[166:169], v[42:45]
	v_mfma_f32_16x16x32_bf16 v[30:33], v[70:73], v[182:185], v[30:33]
	v_mfma_f32_16x16x32_bf16 v[26:29], v[82:85], v[182:185], v[26:29]
	v_mfma_f32_16x16x32_bf16 v[14:17], v[70:73], v[194:197], v[14:17]
	v_mfma_f32_16x16x32_bf16 v[10:13], v[82:85], v[194:197], v[10:13]
	s_nop 0
	s_nop 0
	v_mfma_f32_16x16x32_bf16 v[54:57], v[90:93], v[134:137], v[54:57]
	v_mfma_f32_16x16x32_bf16 v[50:53], v[110:113], v[134:137], v[50:53]
	v_mfma_f32_16x16x32_bf16 v[38:41], v[90:93], v[158:161], v[38:41]
	v_mfma_f32_16x16x32_bf16 v[34:37], v[110:113], v[158:161], v[34:37]
	v_mfma_f32_16x16x32_bf16 v[22:25], v[90:93], v[174:177], v[22:25]
	v_mfma_f32_16x16x32_bf16 v[18:21], v[110:113], v[174:177], v[18:21]
	v_mfma_f32_16x16x32_bf16 v[6:9], v[90:93], v[190:193], v[6:9]
	v_mfma_f32_16x16x32_bf16 v[2:5], v[110:113], v[190:193], v[2:5]
	v_mfma_f32_16x16x32_bf16 v[54:57], v[98:101], v[146:149], v[54:57]
	v_mfma_f32_16x16x32_bf16 v[50:53], v[122:125], v[146:149], v[50:53]
	v_mfma_f32_16x16x32_bf16 v[38:41], v[98:101], v[166:169], v[38:41]
	v_mfma_f32_16x16x32_bf16 v[34:37], v[122:125], v[166:169], v[34:37]
	v_mfma_f32_16x16x32_bf16 v[22:25], v[98:101], v[182:185], v[22:25]
	v_mfma_f32_16x16x32_bf16 v[18:21], v[122:125], v[182:185], v[18:21]
	v_mfma_f32_16x16x32_bf16 v[6:9], v[98:101], v[194:197], v[6:9]
	v_mfma_f32_16x16x32_bf16 v[2:5], v[122:125], v[194:197], v[2:5]
	s_nop 0
	s_barrier
	s_add_i32 s52, s52, 2
	s_add_u32 s15, s15, 0x100
	s_addc_u32 s27, s27, 0
	s_add_u32 s40, s40, 0x400000
	s_addc_u32 s41, s41, 0
	s_cmp_gt_u32 s52, 13
	s_cbranch_scc0 .LBB0_464
	s_and_b64 vcc, exec, s[24:25]
	s_cbranch_vccz .LBB0_467
	s_barrier

; #define G8_STAGE(bufoff, gbase, voff) do { _Pragma("unroll") for (int _i = 0; _i < 2; ++_i) \
;         __builtin_amdgcn_global_load_lds((const unsigned*)((const char*)(gbase) + (voff)[_i]), (LAS unsigned*)(lds + (bufoff) + ldsw + _i * 8192), 16, 0, 0); } while (0)
; #define G8_LDA(dst, b, h) do { _Pragma("unroll") for (int m = 0; m < 4; ++m) _Pragma("unroll") for (int k = 0; k < 2; ++k) dst[m][k] = *(const LAS bf16x8*)(lds + G8_SA(b, h) + aoff + m * 2048 + k * 1024); } while (0)
; #define G8_LDB(dst, b, h) do { _Pragma("unroll") for (int n = 0; n < 2; ++n) _Pragma("unroll") for (int k = 0; k < 2; ++k) dst[n][k] = *(const LAS bf16x8*)(lds + G8_SB(b, h) + boff + n * 2048 + k * 1024); } while (0)
; #define G8_MMA(ai, bj, At, Bt) do { __builtin_amdgcn_s_setprio(1); _Pragma("unroll") for (int m = 0; m < 4; ++m) _Pragma("unroll") for (int n = 0; n < 2; ++n) _Pragma("unroll") for (int k = 0; k < 2; ++k) \
;         acc[ai][bj][m][n] = __builtin_amdgcn_mfma_f32_16x16x32_bf16(Bt[n][k], At[m][k], acc[ai][bj][m][n], 0, 0, 0); __builtin_amdgcn_s_setprio(0); } while (0)
; #define G8_WAIT_V(n) asm volatile("s_waitcnt vmcnt(" #n ")" ::: "memory")
; #define G8_WAIT_L(n) asm volatile("s_waitcnt lgkmcnt(" #n ")" ::: "memory")
; #define G8_BAR __builtin_amdgcn_s_barrier()
; #define G8_SCHED __builtin_amdgcn_sched_barrier(0)
; template <class Epi, class Sched>
; DEV void gemm_phase(LAS char* lds, const Sched& S, const Epi& E) {
;     ...
;             G8_LDB(B0, 0, 0); G8_LDB(B1, 0, 1); G8_SCHED; G8_LDA(At, 0, 0); G8_STAGE(G8_SA(1, 1), a1 + hstepA, voffA);
;             G8_WAIT_V(8); G8_WAIT_L(0); G8_BAR; G8_MMA(0, 0, At, B0); G8_MMA(0, 1, At, B1); G8_BAR; G8_SCHED;
;             G8_LDA(At, 0, 1); G8_STAGE(G8_SB(0, 0), b2, voffB); G8_STAGE(G8_SB(0, 1), b2 + hstepB, voffB); G8_STAGE(G8_SA(0, 0), a2, voffA);
;             G8_WAIT_V(8); G8_WAIT_L(0); G8_BAR; G8_MMA(1, 0, At, B0); G8_MMA(1, 1, At, B1); G8_BAR; G8_SCHED;
.LBB0_495:
	ds_read_b128 v[126:129], v116
	ds_read_b128 v[142:145], v116 offset:1024
	ds_read_b128 v[150:153], v116 offset:2048
	ds_read_b128 v[162:165], v116 offset:3072
	ds_read_b128 v[166:169], v117
	ds_read_b128 v[170:173], v117 offset:1024
	ds_read_b128 v[174:177], v117 offset:2048
	ds_read_b128 v[178:181], v117 offset:3072
	s_add_u32 s16, s10, s14
	s_addc_u32 s17, s11, s15
	s_add_u32 s20, s16, 0x100
	s_addc_u32 s21, s17, 0
	s_add_u32 s18, s39, s14
	s_addc_u32 s19, s40, s15
	s_add_u32 s16, s16, 0x180
	s_addc_u32 s17, s17, 0
	s_cmpk_eq_i32 s14, 0x700
	s_cselect_b32 s17, s34, s17
	s_cselect_b32 s16, s31, s16
	s_cselect_b32 s19, s7, s19
	s_cselect_b32 s18, s6, s18
	s_cselect_b32 s21, s11, s21
	s_cselect_b32 s20, s10, s20
	s_mov_b32 m0, s42
	v_lshl_add_u64 v[214:215], v[112:113], 0, s[14:15]
	ds_read_b128 v[182:185], v118
	ds_read_b128 v[186:189], v118 offset:1024
	ds_read_b128 v[190:193], v118 offset:2048
	ds_read_b128 v[194:197], v118 offset:3072
	ds_read_b128 v[198:201], v118 offset:4096
	ds_read_b128 v[202:205], v118 offset:5120
	ds_read_b128 v[206:209], v118 offset:6144
	ds_read_b128 v[210:213], v118 offset:7168
	global_load_lds_dwordx4 v[214:215], off
	v_lshl_add_u64 v[214:215], v[110:111], 0, s[14:15]
	s_mov_b32 m0, s43
	s_nop 0
	global_load_lds_dwordx4 v[214:215], off
	s_waitcnt vmcnt(8)
	s_waitcnt lgkmcnt(0)
	s_barrier
	s_nop 0
	s_waitcnt lgkmcnt(0)
	v_mfma_f32_16x16x32_bf16 v[158:161], v[126:129], v[182:185], v[158:161]
	v_mfma_f32_16x16x32_bf16 v[154:157], v[150:153], v[182:185], v[154:157]
	v_mfma_f32_16x16x32_bf16 v[134:137], v[126:129], v[190:193], v[134:137]
	v_mfma_f32_16x16x32_bf16 v[130:133], v[150:153], v[190:193], v[130:133]
	v_mfma_f32_16x16x32_bf16 v[98:101], v[126:129], v[198:201], v[98:101]
	v_mfma_f32_16x16x32_bf16 v[90:93], v[150:153], v[198:201], v[90:93]
	v_mfma_f32_16x16x32_bf16 v[78:81], v[126:129], v[206:209], v[78:81]
	v_mfma_f32_16x16x32_bf16 v[74:77], v[150:153], v[206:209], v[74:77]
	v_mfma_f32_16x16x32_bf16 v[158:161], v[142:145], v[186:189], v[158:161]
	v_mfma_f32_16x16x32_bf16 v[154:157], v[162:165], v[186:189], v[154:157]
	v_mfma_f32_16x16x32_bf16 v[134:137], v[142:145], v[194:197], v[134:137]
	v_mfma_f32_16x16x32_bf16 v[130:133], v[162:165], v[194:197], v[130:133]
	v_mfma_f32_16x16x32_bf16 v[98:101], v[142:145], v[202:205], v[98:101]
	v_mfma_f32_16x16x32_bf16 v[90:93], v[162:165], v[202:205], v[90:93]
	v_mfma_f32_16x16x32_bf16 v[78:81], v[142:145], v[210:213], v[78:81]
	v_mfma_f32_16x16x32_bf16 v[74:77], v[162:165], v[210:213], v[74:77]
	s_nop 0
	s_nop 0
	v_mfma_f32_16x16x32_bf16 v[146:149], v[166:169], v[182:185], v[146:149]
	v_mfma_f32_16x16x32_bf16 v[138:141], v[174:177], v[182:185], v[138:141]
	v_mfma_f32_16x16x32_bf16 v[122:125], v[166:169], v[190:193], v[122:125]
	v_mfma_f32_16x16x32_bf16 v[106:109], v[174:177], v[190:193], v[106:109]
	v_mfma_f32_16x16x32_bf16 v[86:89], v[166:169], v[198:201], v[86:89]
	v_mfma_f32_16x16x32_bf16 v[82:85], v[174:177], v[198:201], v[82:85]
	v_mfma_f32_16x16x32_bf16 v[70:73], v[166:169], v[206:209], v[70:73]
	v_mfma_f32_16x16x32_bf16 v[66:69], v[174:177], v[206:209], v[66:69]
	v_mfma_f32_16x16x32_bf16 v[146:149], v[170:173], v[186:189], v[146:149]
	v_mfma_f32_16x16x32_bf16 v[138:141], v[178:181], v[186:189], v[138:141]
	v_mfma_f32_16x16x32_bf16 v[122:125], v[170:173], v[194:197], v[122:125]
	v_mfma_f32_16x16x32_bf16 v[106:109], v[178:181], v[194:197], v[106:109]
	v_mfma_f32_16x16x32_bf16 v[86:89], v[170:173], v[202:205], v[86:89]
	v_mfma_f32_16x16x32_bf16 v[82:85], v[178:181], v[202:205], v[82:85]
	v_mfma_f32_16x16x32_bf16 v[70:73], v[170:173], v[210:213], v[70:73]
	v_mfma_f32_16x16x32_bf16 v[66:69], v[178:181], v[210:213], v[66:69]
	s_nop 0
	s_barrier
	s_mov_b32 m0, s45
	v_lshl_add_u64 v[214:215], s[18:19], 0, v[96:97]
	s_add_u32 s58, s18, 0x40000
	ds_read_b128 v[182:185], v118 offset:16384
	ds_read_b128 v[186:189], v118 offset:17408
	ds_read_b128 v[190:193], v118 offset:18432
	ds_read_b128 v[194:197], v118 offset:19456
	ds_read_b128 v[198:201], v118 offset:20480
	ds_read_b128 v[202:205], v118 offset:21504
	ds_read_b128 v[206:209], v118 offset:22528
	ds_read_b128 v[210:213], v118 offset:23552
	global_load_lds_dwordx4 v[214:215], off
	v_lshl_add_u64 v[216:217], s[18:19], 0, v[104:105]
	s_mov_b32 m0, s46
	s_addc_u32 s59, s19, 0
	global_load_lds_dwordx4 v[216:217], off
	v_lshl_add_u64 v[218:219], s[58:59], 0, v[96:97]
	s_mov_b32 m0, s47
	s_nop 0
	global_load_lds_dwordx4 v[218:219], off
	v_lshl_add_u64 v[218:219], s[58:59], 0, v[104:105]
	s_mov_b32 m0, s52
	s_nop 0
	global_load_lds_dwordx4 v[218:219], off
	v_lshl_add_u64 v[218:219], s[20:21], 0, v[94:95]
	s_mov_b32 m0, s1
	s_nop 0
	global_load_lds_dwordx4 v[218:219], off
	v_lshl_add_u64 v[218:219], s[20:21], 0, v[102:103]
	s_mov_b32 m0, s28
	s_nop 0
	global_load_lds_dwordx4 v[218:219], off
	s_waitcnt vmcnt(8)
	s_waitcnt lgkmcnt(0)
	s_barrier
; #define G8_STAGE(bufoff, gbase, voff) do { _Pragma("unroll") for (int _i = 0; _i < 2; ++_i) \
;         __builtin_amdgcn_global_load_lds((const unsigned*)((const char*)(gbase) + (voff)[_i]), (LAS unsigned*)(lds + (bufoff) + ldsw + _i * 8192), 16, 0, 0); } while (0)
; #define G8_LDA(dst, b, h) do { _Pragma("unroll") for (int m = 0; m < 4; ++m) _Pragma("unroll") for (int k = 0; k < 2; ++k) dst[m][k] = *(const LAS bf16x8*)(lds + G8_SA(b, h) + aoff + m * 2048 + k * 1024); } while (0)
; #define G8_LDB(dst, b, h) do { _Pragma("unroll") for (int n = 0; n < 2; ++n) _Pragma("unroll") for (int k = 0; k < 2; ++k) dst[n][k] = *(const LAS bf16x8*)(lds + G8_SB(b, h) + boff + n * 2048 + k * 1024); } while (0)
; #define G8_MMA(ai, bj, At, Bt) do { __builtin_amdgcn_s_setprio(1); _Pragma("unroll") for (int m = 0; m < 4; ++m) _Pragma("unroll") for (int n = 0; n < 2; ++n) _Pragma("unroll") for (int k = 0; k < 2; ++k) \
;         acc[ai][bj][m][n] = __builtin_amdgcn_mfma_f32_16x16x32_bf16(Bt[n][k], At[m][k], acc[ai][bj][m][n], 0, 0, 0); __builtin_amdgcn_s_setprio(0); } while (0)
; #define G8_WAIT_V(n) asm volatile("s_waitcnt vmcnt(" #n ")" ::: "memory")
; #define G8_WAIT_L(n) asm volatile("s_waitcnt lgkmcnt(" #n ")" ::: "memory")
; #define G8_BAR __builtin_amdgcn_s_barrier()
; #define G8_SCHED __builtin_amdgcn_sched_barrier(0)
; template <class Epi, class Sched>
; DEV void gemm_phase(LAS char* lds, const Sched& S, const Epi& E) {
;     ...
;             G8_WAIT_V(8); G8_WAIT_L(0); G8_BAR; G8_MMA(0, 0, At, B0); G8_MMA(0, 1, At, B1); G8_BAR; G8_SCHED;
;             G8_LDA(At, 0, 1); G8_STAGE(G8_SB(0, 0), b2, voffB); G8_STAGE(G8_SB(0, 1), b2 + hstepB, voffB); G8_STAGE(G8_SA(0, 0), a2, voffA);
;             G8_WAIT_V(8); G8_WAIT_L(0); G8_BAR; G8_MMA(1, 0, At, B0); G8_MMA(1, 1, At, B1); G8_BAR; G8_SCHED;
;             G8_LDB(B0, 1, 0); G8_LDB(B1, 1, 1); G8_SCHED; G8_LDA(At, 1, 0); G8_STAGE(G8_SA(0, 1), a2 + hstepA, voffA);
;             G8_WAIT_V(8); G8_WAIT_L(0); G8_BAR; G8_MMA(0, 0, At, B0); G8_MMA(0, 1, At, B1); G8_BAR; G8_SCHED;
	s_nop 0
	s_waitcnt lgkmcnt(0)
	v_mfma_f32_16x16x32_bf16 v[62:65], v[126:129], v[182:185], v[62:65]
	v_mfma_f32_16x16x32_bf16 v[58:61], v[150:153], v[182:185], v[58:61]
	v_mfma_f32_16x16x32_bf16 v[46:49], v[126:129], v[190:193], v[46:49]
	v_mfma_f32_16x16x32_bf16 v[42:45], v[150:153], v[190:193], v[42:45]
	v_mfma_f32_16x16x32_bf16 v[30:33], v[126:129], v[198:201], v[30:33]
	v_mfma_f32_16x16x32_bf16 v[26:29], v[150:153], v[198:201], v[26:29]
	v_mfma_f32_16x16x32_bf16 v[14:17], v[126:129], v[206:209], v[14:17]
	v_mfma_f32_16x16x32_bf16 v[10:13], v[150:153], v[206:209], v[10:13]
	v_mfma_f32_16x16x32_bf16 v[62:65], v[142:145], v[186:189], v[62:65]
	v_mfma_f32_16x16x32_bf16 v[58:61], v[162:165], v[186:189], v[58:61]
	v_mfma_f32_16x16x32_bf16 v[46:49], v[142:145], v[194:197], v[46:49]
	v_mfma_f32_16x16x32_bf16 v[42:45], v[162:165], v[194:197], v[42:45]
	v_mfma_f32_16x16x32_bf16 v[30:33], v[142:145], v[202:205], v[30:33]
	v_mfma_f32_16x16x32_bf16 v[26:29], v[162:165], v[202:205], v[26:29]
	v_mfma_f32_16x16x32_bf16 v[14:17], v[142:145], v[210:213], v[14:17]
	v_mfma_f32_16x16x32_bf16 v[10:13], v[162:165], v[210:213], v[10:13]
	s_nop 0
	s_nop 0
	v_mfma_f32_16x16x32_bf16 v[54:57], v[166:169], v[182:185], v[54:57]
	v_mfma_f32_16x16x32_bf16 v[50:53], v[174:177], v[182:185], v[50:53]
	v_mfma_f32_16x16x32_bf16 v[38:41], v[166:169], v[190:193], v[38:41]
	v_mfma_f32_16x16x32_bf16 v[34:37], v[174:177], v[190:193], v[34:37]
	v_mfma_f32_16x16x32_bf16 v[22:25], v[166:169], v[198:201], v[22:25]
	v_mfma_f32_16x16x32_bf16 v[18:21], v[174:177], v[198:201], v[18:21]
	v_mfma_f32_16x16x32_bf16 v[6:9], v[166:169], v[206:209], v[6:9]
	v_mfma_f32_16x16x32_bf16 v[2:5], v[174:177], v[206:209], v[2:5]
	v_mfma_f32_16x16x32_bf16 v[54:57], v[170:173], v[186:189], v[54:57]
	v_mfma_f32_16x16x32_bf16 v[50:53], v[178:181], v[186:189], v[50:53]
	v_mfma_f32_16x16x32_bf16 v[38:41], v[170:173], v[194:197], v[38:41]
	v_mfma_f32_16x16x32_bf16 v[34:37], v[178:181], v[194:197], v[34:37]
	v_mfma_f32_16x16x32_bf16 v[22:25], v[170:173], v[202:205], v[22:25]
	v_mfma_f32_16x16x32_bf16 v[18:21], v[178:181], v[202:205], v[18:21]
	v_mfma_f32_16x16x32_bf16 v[6:9], v[170:173], v[210:213], v[6:9]
	v_mfma_f32_16x16x32_bf16 v[2:5], v[178:181], v[210:213], v[2:5]
	s_nop 0
	s_barrier
	ds_read_b128 v[126:129], v119
	ds_read_b128 v[142:145], v119 offset:1024
	ds_read_b128 v[150:153], v119 offset:2048
	ds_read_b128 v[162:165], v119 offset:3072
	ds_read_b128 v[166:169], v120
	ds_read_b128 v[170:173], v120 offset:1024
	ds_read_b128 v[174:177], v120 offset:2048
	ds_read_b128 v[178:181], v120 offset:3072
	s_add_u32 s20, s20, 0x40000
	s_addc_u32 s21, s21, 0
	s_mov_b32 m0, s29
	v_lshl_add_u64 v[218:219], s[20:21], 0, v[94:95]
	ds_read_b128 v[182:185], v118 offset:32768
	ds_read_b128 v[186:189], v118 offset:33792
	ds_read_b128 v[190:193], v118 offset:34816
	ds_read_b128 v[194:197], v118 offset:35840
	ds_read_b128 v[198:201], v118 offset:36864
	ds_read_b128 v[202:205], v118 offset:37888
	ds_read_b128 v[206:209], v118 offset:38912
	ds_read_b128 v[210:213], v118 offset:39936
	global_load_lds_dwordx4 v[218:219], off
	v_lshl_add_u64 v[218:219], s[20:21], 0, v[102:103]
	s_mov_b32 m0, s30
	s_nop 0
	global_load_lds_dwordx4 v[218:219], off
	s_waitcnt vmcnt(8)
	s_waitcnt lgkmcnt(0)
	s_barrier
	s_nop 0
	s_waitcnt lgkmcnt(0)
	v_mfma_f32_16x16x32_bf16 v[158:161], v[126:129], v[182:185], v[158:161]
	v_mfma_f32_16x16x32_bf16 v[154:157], v[150:153], v[182:185], v[154:157]
	v_mfma_f32_16x16x32_bf16 v[134:137], v[126:129], v[190:193], v[134:137]
	v_mfma_f32_16x16x32_bf16 v[130:133], v[150:153], v[190:193], v[130:133]
	v_mfma_f32_16x16x32_bf16 v[98:101], v[126:129], v[198:201], v[98:101]
	v_mfma_f32_16x16x32_bf16 v[90:93], v[150:153], v[198:201], v[90:93]
	v_mfma_f32_16x16x32_bf16 v[78:81], v[126:129], v[206:209], v[78:81]
	v_mfma_f32_16x16x32_bf16 v[74:77], v[150:153], v[206:209], v[74:77]
	v_mfma_f32_16x16x32_bf16 v[158:161], v[142:145], v[186:189], v[158:161]
	v_mfma_f32_16x16x32_bf16 v[154:157], v[162:165], v[186:189], v[154:157]
	v_mfma_f32_16x16x32_bf16 v[134:137], v[142:145], v[194:197], v[134:137]
	v_mfma_f32_16x16x32_bf16 v[130:133], v[162:165], v[194:197], v[130:133]
	v_mfma_f32_16x16x32_bf16 v[98:101], v[142:145], v[202:205], v[98:101]
	v_mfma_f32_16x16x32_bf16 v[90:93], v[162:165], v[202:205], v[90:93]
	v_mfma_f32_16x16x32_bf16 v[78:81], v[142:145], v[210:213], v[78:81]
	v_mfma_f32_16x16x32_bf16 v[74:77], v[162:165], v[210:213], v[74:77]
	s_nop 0
	s_nop 0
	v_mfma_f32_16x16x32_bf16 v[146:149], v[166:169], v[182:185], v[146:149]
	v_mfma_f32_16x16x32_bf16 v[138:141], v[174:177], v[182:185], v[138:141]
	v_mfma_f32_16x16x32_bf16 v[122:125], v[166:169], v[190:193], v[122:125]
	v_mfma_f32_16x16x32_bf16 v[106:109], v[174:177], v[190:193], v[106:109]
	v_mfma_f32_16x16x32_bf16 v[86:89], v[166:169], v[198:201], v[86:89]
	v_mfma_f32_16x16x32_bf16 v[82:85], v[174:177], v[198:201], v[82:85]
	v_mfma_f32_16x16x32_bf16 v[70:73], v[166:169], v[206:209], v[70:73]
	v_mfma_f32_16x16x32_bf16 v[66:69], v[174:177], v[206:209], v[66:69]
	v_mfma_f32_16x16x32_bf16 v[146:149], v[170:173], v[186:189], v[146:149]
	v_mfma_f32_16x16x32_bf16 v[138:141], v[178:181], v[186:189], v[138:141]
	v_mfma_f32_16x16x32_bf16 v[122:125], v[170:173], v[194:197], v[122:125]
	v_mfma_f32_16x16x32_bf16 v[106:109], v[178:181], v[194:197], v[106:109]
	v_mfma_f32_16x16x32_bf16 v[86:89], v[170:173], v[202:205], v[86:89]
	v_mfma_f32_16x16x32_bf16 v[82:85], v[178:181], v[202:205], v[82:85]
	v_mfma_f32_16x16x32_bf16 v[70:73], v[170:173], v[210:213], v[70:73]
	v_mfma_f32_16x16x32_bf16 v[66:69], v[178:181], v[210:213], v[66:69]
	s_nop 0
	s_barrier
; #define G8_STAGE(bufoff, gbase, voff) do { _Pragma("unroll") for (int _i = 0; _i < 2; ++_i) \
;         __builtin_amdgcn_global_load_lds((const unsigned*)((const char*)(gbase) + (voff)[_i]), (LAS unsigned*)(lds + (bufoff) + ldsw + _i * 8192), 16, 0, 0); } while (0)
; #define G8_LDA(dst, b, h) do { _Pragma("unroll") for (int m = 0; m < 4; ++m) _Pragma("unroll") for (int k = 0; k < 2; ++k) dst[m][k] = *(const LAS bf16x8*)(lds + G8_SA(b, h) + aoff + m * 2048 + k * 1024); } while (0)
; #define G8_MMA(ai, bj, At, Bt) do { __builtin_amdgcn_s_setprio(1); _Pragma("unroll") for (int m = 0; m < 4; ++m) _Pragma("unroll") for (int n = 0; n < 2; ++n) _Pragma("unroll") for (int k = 0; k < 2; ++k) \
;         acc[ai][bj][m][n] = __builtin_amdgcn_mfma_f32_16x16x32_bf16(Bt[n][k], At[m][k], acc[ai][bj][m][n], 0, 0, 0); __builtin_amdgcn_s_setprio(0); } while (0)
; #define G8_WAIT_V(n) asm volatile("s_waitcnt vmcnt(" #n ")" ::: "memory")
; #define G8_WAIT_L(n) asm volatile("s_waitcnt lgkmcnt(" #n ")" ::: "memory")
; #define G8_BAR __builtin_amdgcn_s_barrier()
; #define G8_SCHED __builtin_amdgcn_sched_barrier(0)
; template <class Epi, class Sched>
; DEV void gemm_phase(LAS char* lds, const Sched& S, const Epi& E) {
;     ...
;             G8_LDA(At, 1, 1); G8_STAGE(G8_SB(1, 0), b3, voffB); G8_STAGE(G8_SB(1, 1), b3 + hstepB, voffB); G8_STAGE(G8_SA(1, 0), a3, voffA);
;             G8_WAIT_V(8); G8_WAIT_L(0); G8_BAR; G8_MMA(1, 0, At, B0); G8_MMA(1, 1, At, B1); G8_BAR; G8_SCHED;
;         }
;         if (wr == 0) G8_BAR;
	s_mov_b32 m0, s54
	v_lshl_add_u64 v[214:215], v[214:215], 0, s[12:13]
	s_add_u32 s18, s18, 0x40080
	ds_read_b128 v[182:185], v118 offset:49152
	ds_read_b128 v[186:189], v118 offset:50176
	ds_read_b128 v[190:193], v118 offset:51200
	ds_read_b128 v[194:197], v118 offset:52224
	ds_read_b128 v[198:201], v118 offset:53248
	ds_read_b128 v[202:205], v118 offset:54272
	ds_read_b128 v[206:209], v118 offset:55296
	ds_read_b128 v[210:213], v118 offset:56320
	global_load_lds_dwordx4 v[214:215], off
	v_lshl_add_u64 v[214:215], v[216:217], 0, s[12:13]
	s_mov_b32 m0, s55
	s_addc_u32 s19, s19, 0
	global_load_lds_dwordx4 v[214:215], off
	v_lshl_add_u64 v[214:215], s[18:19], 0, v[96:97]
	s_mov_b32 m0, s56
	s_nop 0
	global_load_lds_dwordx4 v[214:215], off
	v_lshl_add_u64 v[214:215], s[18:19], 0, v[104:105]
	s_mov_b32 m0, s57
	s_nop 0
	global_load_lds_dwordx4 v[214:215], off
	v_lshl_add_u64 v[214:215], s[16:17], 0, v[94:95]
	s_mov_b32 m0, s35
	s_nop 0
	global_load_lds_dwordx4 v[214:215], off
	v_lshl_add_u64 v[214:215], s[16:17], 0, v[102:103]
	s_mov_b32 m0, s38
	s_nop 0
	global_load_lds_dwordx4 v[214:215], off
	s_waitcnt vmcnt(8)
	s_waitcnt lgkmcnt(0)
	s_barrier
	s_nop 0
	s_waitcnt lgkmcnt(0)
	v_mfma_f32_16x16x32_bf16 v[62:65], v[126:129], v[182:185], v[62:65]
	v_mfma_f32_16x16x32_bf16 v[58:61], v[150:153], v[182:185], v[58:61]
	v_mfma_f32_16x16x32_bf16 v[46:49], v[126:129], v[190:193], v[46:49]
	v_mfma_f32_16x16x32_bf16 v[42:45], v[150:153], v[190:193], v[42:45]
	v_mfma_f32_16x16x32_bf16 v[30:33], v[126:129], v[198:201], v[30:33]
	v_mfma_f32_16x16x32_bf16 v[26:29], v[150:153], v[198:201], v[26:29]
	v_mfma_f32_16x16x32_bf16 v[14:17], v[126:129], v[206:209], v[14:17]
	v_mfma_f32_16x16x32_bf16 v[10:13], v[150:153], v[206:209], v[10:13]
	v_mfma_f32_16x16x32_bf16 v[62:65], v[142:145], v[186:189], v[62:65]
	v_mfma_f32_16x16x32_bf16 v[58:61], v[162:165], v[186:189], v[58:61]
	v_mfma_f32_16x16x32_bf16 v[46:49], v[142:145], v[194:197], v[46:49]
	v_mfma_f32_16x16x32_bf16 v[42:45], v[162:165], v[194:197], v[42:45]
	v_mfma_f32_16x16x32_bf16 v[30:33], v[142:145], v[202:205], v[30:33]
	v_mfma_f32_16x16x32_bf16 v[26:29], v[162:165], v[202:205], v[26:29]
	v_mfma_f32_16x16x32_bf16 v[14:17], v[142:145], v[210:213], v[14:17]
	v_mfma_f32_16x16x32_bf16 v[10:13], v[162:165], v[210:213], v[10:13]
	s_nop 0
	s_nop 0
	v_mfma_f32_16x16x32_bf16 v[54:57], v[166:169], v[182:185], v[54:57]
	v_mfma_f32_16x16x32_bf16 v[50:53], v[174:177], v[182:185], v[50:53]
	v_mfma_f32_16x16x32_bf16 v[38:41], v[166:169], v[190:193], v[38:41]
	v_mfma_f32_16x16x32_bf16 v[34:37], v[174:177], v[190:193], v[34:37]
	v_mfma_f32_16x16x32_bf16 v[22:25], v[166:169], v[198:201], v[22:25]
	v_mfma_f32_16x16x32_bf16 v[18:21], v[174:177], v[198:201], v[18:21]
	v_mfma_f32_16x16x32_bf16 v[6:9], v[166:169], v[206:209], v[6:9]
	v_mfma_f32_16x16x32_bf16 v[2:5], v[174:177], v[206:209], v[2:5]
	v_mfma_f32_16x16x32_bf16 v[54:57], v[170:173], v[186:189], v[54:57]
	v_mfma_f32_16x16x32_bf16 v[50:53], v[178:181], v[186:189], v[50:53]
	v_mfma_f32_16x16x32_bf16 v[38:41], v[170:173], v[194:197], v[38:41]
	v_mfma_f32_16x16x32_bf16 v[34:37], v[178:181], v[194:197], v[34:37]
	v_mfma_f32_16x16x32_bf16 v[22:25], v[170:173], v[202:205], v[22:25]
	v_mfma_f32_16x16x32_bf16 v[18:21], v[178:181], v[202:205], v[18:21]
	v_mfma_f32_16x16x32_bf16 v[6:9], v[170:173], v[210:213], v[6:9]
	v_mfma_f32_16x16x32_bf16 v[2:5], v[178:181], v[210:213], v[2:5]
	s_nop 0
	s_barrier
	s_add_i32 s41, s41, 2
	s_add_u32 s14, s14, 0x100
	s_addc_u32 s15, s15, 0
	s_cmp_gt_u32 s41, 13
	s_cbranch_scc0 .LBB0_495
	s_cmpk_lt_u32 s0, 0x100
	s_cbranch_scc0 .LBB0_498
	s_barrier

; #define G8_STAGE(bufoff, gbase, voff) do { _Pragma("unroll") for (int _i = 0; _i < 2; ++_i) \
;         __builtin_amdgcn_global_load_lds((const unsigned*)((const char*)(gbase) + (voff)[_i]), (LAS unsigned*)(lds + (bufoff) + ldsw + _i * 8192), 16, 0, 0); } while (0)
; #define G8_LDA(dst, b, h) do { _Pragma("unroll") for (int m = 0; m < 4; ++m) _Pragma("unroll") for (int k = 0; k < 2; ++k) dst[m][k] = *(const LAS bf16x8*)(lds + G8_SA(b, h) + aoff + m * 2048 + k * 1024); } while (0)
; #define G8_LDB(dst, b, h) do { _Pragma("unroll") for (int n = 0; n < 2; ++n) _Pragma("unroll") for (int k = 0; k < 2; ++k) dst[n][k] = *(const LAS bf16x8*)(lds + G8_SB(b, h) + boff + n * 2048 + k * 1024); } while (0)
; #define G8_MMA(ai, bj, At, Bt) do { __builtin_amdgcn_s_setprio(1); _Pragma("unroll") for (int m = 0; m < 4; ++m) _Pragma("unroll") for (int n = 0; n < 2; ++n) _Pragma("unroll") for (int k = 0; k < 2; ++k) \
;         acc[ai][bj][m][n] = __builtin_amdgcn_mfma_f32_16x16x32_bf16(Bt[n][k], At[m][k], acc[ai][bj][m][n], 0, 0, 0); __builtin_amdgcn_s_setprio(0); } while (0)
; #define G8_WAIT_V(n) asm volatile("s_waitcnt vmcnt(" #n ")" ::: "memory")
; #define G8_WAIT_L(n) asm volatile("s_waitcnt lgkmcnt(" #n ")" ::: "memory")
; #define G8_BAR __builtin_amdgcn_s_barrier()
; #define G8_SCHED __builtin_amdgcn_sched_barrier(0)
; template <class Epi, class Sched>
; DEV void gemm_phase(LAS char* lds, const Sched& S, const Epi& E) {
;     ...
;         for (int t = 0; t < nt; t += 2) {
;             const bool last = (t == nt - 2);
;             const char* a1 = G8_AK(t + 1);
;             const char* a2 = last ? nA : G8_AK(t + 2); const char* b2 = last ? nB : cB + (size_t)(t + 2) * kstep;
;             const char* a3 = last ? nA + kstepA : G8_AK(t + 3); const char* b3 = b2 + kstep;
;             G8_LDB(B0, 0, 0); G8_LDB(B1, 0, 1); G8_SCHED; G8_LDA(At, 0, 0); G8_STAGE(G8_SA(1, 1), a1 + hstepA, voffA);
;             G8_WAIT_V(8); G8_WAIT_L(0); G8_BAR; G8_MMA(0, 0, At, B0); G8_MMA(0, 1, At, B1); G8_BAR; G8_SCHED;
;             G8_LDA(At, 0, 1); G8_STAGE(G8_SB(0, 0), b2, voffB); G8_STAGE(G8_SB(0, 1), b2 + hstepB, voffB); G8_STAGE(G8_SA(0, 0), a2, voffA);
.LBB0_521:
	s_add_u32 s15, s24, s34
	s_addc_u32 s17, s25, s35
	s_add_u32 s38, s15, 0x100
	s_addc_u32 s39, s17, 0
	s_add_u32 s34, s26, s34
	s_addc_u32 s35, s27, s35
	s_add_u32 s34, s34, 0x100
	s_addc_u32 s35, s35, 0
	s_add_u32 s40, s15, 0x180
	s_addc_u32 s41, s17, 0
	s_and_b64 s[30:31], s[30:31], exec
	s_cselect_b32 s30, s0, s40
	s_cselect_b32 s31, s1, s41
	s_cselect_b32 s43, s23, s35
	s_cselect_b32 s42, s22, s34
	s_cselect_b32 s41, s19, s39
	s_cselect_b32 s40, s18, s38
	s_add_u32 s76, s15, 0x40080
	ds_read_b128 v[144:147], v151
	ds_read_b128 v[156:159], v151 offset:1024
	ds_read_b128 v[160:163], v151 offset:2048
	ds_read_b128 v[164:167], v151 offset:3072
	ds_read_b128 v[168:171], v152
	ds_read_b128 v[172:175], v152 offset:1024
	ds_read_b128 v[176:179], v152 offset:2048
	ds_read_b128 v[180:183], v152 offset:3072
	s_addc_u32 s77, s17, 0
	s_add_i32 s81, s62, s55
	s_add_i32 m0, s56, 0xc000
	s_add_i32 s82, s56, 0xe000
	s_add_i32 s78, s81, 0x2000
	s_add_u32 s74, s42, 0x10000
	s_addc_u32 s75, s43, 0
	s_add_i32 s80, s63, s55
	s_add_i32 s79, s80, 0x2000
	s_add_u32 s38, s40, 0x40000
	s_addc_u32 s39, s41, 0
	s_add_i32 s59, s50, s55
	s_add_i32 s17, s59, 0x2000
	s_add_u32 s34, s42, 0x10080
	s_addc_u32 s35, s43, 0
	s_add_i32 s58, s51, s55
	s_add_i32 s15, s58, 0x2000
	v_lshl_add_u64 v[0:1], s[76:77], 0, v[130:131]
	ds_read_b128 v[184:187], v153
	ds_read_b128 v[188:191], v153 offset:1024
	ds_read_b128 v[192:195], v153 offset:2048
	ds_read_b128 v[196:199], v153 offset:3072
	ds_read_b128 v[200:203], v153 offset:4096
	ds_read_b128 v[204:207], v153 offset:5120
	ds_read_b128 v[208:211], v153 offset:6144
	ds_read_b128 v[212:215], v153 offset:7168
	global_load_lds_dwordx4 v[0:1], off
	v_lshl_add_u64 v[0:1], s[76:77], 0, v[134:135]
	s_mov_b32 m0, s82
	s_nop 0
	global_load_lds_dwordx4 v[0:1], off
	s_waitcnt vmcnt(8)
	s_waitcnt lgkmcnt(0)
	s_barrier
	s_nop 0
	s_waitcnt lgkmcnt(0)
	v_mfma_f32_16x16x32_bf16 v[126:129], v[144:147], v[184:187], v[126:129]
	v_mfma_f32_16x16x32_bf16 v[122:125], v[160:163], v[184:187], v[122:125]
	v_mfma_f32_16x16x32_bf16 v[118:121], v[144:147], v[192:195], v[118:121]
	v_mfma_f32_16x16x32_bf16 v[114:117], v[160:163], v[192:195], v[114:117]
	v_mfma_f32_16x16x32_bf16 v[102:105], v[144:147], v[200:203], v[102:105]
	v_mfma_f32_16x16x32_bf16 v[98:101], v[160:163], v[200:203], v[98:101]
	v_mfma_f32_16x16x32_bf16 v[86:89], v[144:147], v[208:211], v[86:89]
	v_mfma_f32_16x16x32_bf16 v[82:85], v[160:163], v[208:211], v[82:85]
	v_mfma_f32_16x16x32_bf16 v[126:129], v[156:159], v[188:191], v[126:129]
	v_mfma_f32_16x16x32_bf16 v[122:125], v[164:167], v[188:191], v[122:125]
	v_mfma_f32_16x16x32_bf16 v[118:121], v[156:159], v[196:199], v[118:121]
	v_mfma_f32_16x16x32_bf16 v[114:117], v[164:167], v[196:199], v[114:117]
	v_mfma_f32_16x16x32_bf16 v[102:105], v[156:159], v[204:207], v[102:105]
	v_mfma_f32_16x16x32_bf16 v[98:101], v[164:167], v[204:207], v[98:101]
	v_mfma_f32_16x16x32_bf16 v[86:89], v[156:159], v[212:215], v[86:89]
	v_mfma_f32_16x16x32_bf16 v[82:85], v[164:167], v[212:215], v[82:85]
	s_nop 0
	s_nop 0
	v_mfma_f32_16x16x32_bf16 v[110:113], v[168:171], v[184:187], v[110:113]
	v_mfma_f32_16x16x32_bf16 v[106:109], v[176:179], v[184:187], v[106:109]
	v_mfma_f32_16x16x32_bf16 v[94:97], v[168:171], v[192:195], v[94:97]
	v_mfma_f32_16x16x32_bf16 v[90:93], v[176:179], v[192:195], v[90:93]
	v_mfma_f32_16x16x32_bf16 v[78:81], v[168:171], v[200:203], v[78:81]
	v_mfma_f32_16x16x32_bf16 v[74:77], v[176:179], v[200:203], v[74:77]
	v_mfma_f32_16x16x32_bf16 v[70:73], v[168:171], v[208:211], v[70:73]
	v_mfma_f32_16x16x32_bf16 v[66:69], v[176:179], v[208:211], v[66:69]
	v_mfma_f32_16x16x32_bf16 v[110:113], v[172:175], v[188:191], v[110:113]
	v_mfma_f32_16x16x32_bf16 v[106:109], v[180:183], v[188:191], v[106:109]
	v_mfma_f32_16x16x32_bf16 v[94:97], v[172:175], v[196:199], v[94:97]
	v_mfma_f32_16x16x32_bf16 v[90:93], v[180:183], v[196:199], v[90:93]
	v_mfma_f32_16x16x32_bf16 v[78:81], v[172:175], v[204:207], v[78:81]
	v_mfma_f32_16x16x32_bf16 v[74:77], v[180:183], v[204:207], v[74:77]
	v_mfma_f32_16x16x32_bf16 v[70:73], v[172:175], v[212:215], v[70:73]
	v_mfma_f32_16x16x32_bf16 v[66:69], v[180:183], v[212:215], v[66:69]
	s_nop 0
	s_barrier
	s_mov_b32 m0, s81
	v_lshl_add_u64 v[0:1], s[42:43], 0, v[132:133]
	ds_read_b128 v[184:187], v153 offset:16384
	ds_read_b128 v[188:191], v153 offset:17408
	ds_read_b128 v[192:195], v153 offset:18432
	ds_read_b128 v[196:199], v153 offset:19456
	ds_read_b128 v[200:203], v153 offset:20480
	ds_read_b128 v[204:207], v153 offset:21504
	ds_read_b128 v[208:211], v153 offset:22528
	ds_read_b128 v[212:215], v153 offset:23552
	global_load_lds_dwordx4 v[0:1], off
	v_lshl_add_u64 v[216:217], s[42:43], 0, v[136:137]
	s_mov_b32 m0, s78
	v_lshl_add_u64 v[218:219], s[74:75], 0, v[132:133]
	global_load_lds_dwordx4 v[216:217], off
	s_mov_b32 m0, s80
	s_nop 0
	global_load_lds_dwordx4 v[218:219], off
	v_lshl_add_u64 v[218:219], s[74:75], 0, v[136:137]
	s_mov_b32 m0, s79
	s_nop 0
	global_load_lds_dwordx4 v[218:219], off
	v_lshl_add_u64 v[218:219], s[40:41], 0, v[130:131]
	s_mov_b32 m0, s56
	s_nop 0
	global_load_lds_dwordx4 v[218:219], off
	v_lshl_add_u64 v[218:219], s[40:41], 0, v[134:135]
	s_mov_b32 m0, s57
	s_nop 0
	global_load_lds_dwordx4 v[218:219], off
	s_waitcnt vmcnt(8)
	s_waitcnt lgkmcnt(0)
	s_barrier
; #define G8_STAGE(bufoff, gbase, voff) do { _Pragma("unroll") for (int _i = 0; _i < 2; ++_i) \
;         __builtin_amdgcn_global_load_lds((const unsigned*)((const char*)(gbase) + (voff)[_i]), (LAS unsigned*)(lds + (bufoff) + ldsw + _i * 8192), 16, 0, 0); } while (0)
; #define G8_LDA(dst, b, h) do { _Pragma("unroll") for (int m = 0; m < 4; ++m) _Pragma("unroll") for (int k = 0; k < 2; ++k) dst[m][k] = *(const LAS bf16x8*)(lds + G8_SA(b, h) + aoff + m * 2048 + k * 1024); } while (0)
; #define G8_LDB(dst, b, h) do { _Pragma("unroll") for (int n = 0; n < 2; ++n) _Pragma("unroll") for (int k = 0; k < 2; ++k) dst[n][k] = *(const LAS bf16x8*)(lds + G8_SB(b, h) + boff + n * 2048 + k * 1024); } while (0)
; #define G8_MMA(ai, bj, At, Bt) do { __builtin_amdgcn_s_setprio(1); _Pragma("unroll") for (int m = 0; m < 4; ++m) _Pragma("unroll") for (int n = 0; n < 2; ++n) _Pragma("unroll") for (int k = 0; k < 2; ++k) \
;         acc[ai][bj][m][n] = __builtin_amdgcn_mfma_f32_16x16x32_bf16(Bt[n][k], At[m][k], acc[ai][bj][m][n], 0, 0, 0); __builtin_amdgcn_s_setprio(0); } while (0)
; #define G8_WAIT_V(n) asm volatile("s_waitcnt vmcnt(" #n ")" ::: "memory")
; #define G8_WAIT_L(n) asm volatile("s_waitcnt lgkmcnt(" #n ")" ::: "memory")
; #define G8_BAR __builtin_amdgcn_s_barrier()
; #define G8_SCHED __builtin_amdgcn_sched_barrier(0)
; template <class Epi, class Sched>
; DEV void gemm_phase(LAS char* lds, const Sched& S, const Epi& E) {
;     ...
;             G8_WAIT_V(8); G8_WAIT_L(0); G8_BAR; G8_MMA(1, 0, At, B0); G8_MMA(1, 1, At, B1); G8_BAR; G8_SCHED;
;             G8_LDB(B0, 1, 0); G8_LDB(B1, 1, 1); G8_SCHED; G8_LDA(At, 1, 0); G8_STAGE(G8_SA(0, 1), a2 + hstepA, voffA);
;             G8_WAIT_V(8); G8_WAIT_L(0); G8_BAR; G8_MMA(0, 0, At, B0); G8_MMA(0, 1, At, B1); G8_BAR; G8_SCHED;
	s_nop 0
	s_waitcnt lgkmcnt(0)
	v_mfma_f32_16x16x32_bf16 v[62:65], v[144:147], v[184:187], v[62:65]
	v_mfma_f32_16x16x32_bf16 v[58:61], v[160:163], v[184:187], v[58:61]
	v_mfma_f32_16x16x32_bf16 v[54:57], v[144:147], v[192:195], v[54:57]
	v_mfma_f32_16x16x32_bf16 v[46:49], v[160:163], v[192:195], v[46:49]
	v_mfma_f32_16x16x32_bf16 v[38:41], v[144:147], v[200:203], v[38:41]
	v_mfma_f32_16x16x32_bf16 v[30:33], v[160:163], v[200:203], v[30:33]
	v_mfma_f32_16x16x32_bf16 v[22:25], v[144:147], v[208:211], v[22:25]
	v_mfma_f32_16x16x32_bf16 v[14:17], v[160:163], v[208:211], v[14:17]
	v_mfma_f32_16x16x32_bf16 v[62:65], v[156:159], v[188:191], v[62:65]
	v_mfma_f32_16x16x32_bf16 v[58:61], v[164:167], v[188:191], v[58:61]
	v_mfma_f32_16x16x32_bf16 v[54:57], v[156:159], v[196:199], v[54:57]
	v_mfma_f32_16x16x32_bf16 v[46:49], v[164:167], v[196:199], v[46:49]
	v_mfma_f32_16x16x32_bf16 v[38:41], v[156:159], v[204:207], v[38:41]
	v_mfma_f32_16x16x32_bf16 v[30:33], v[164:167], v[204:207], v[30:33]
	v_mfma_f32_16x16x32_bf16 v[22:25], v[156:159], v[212:215], v[22:25]
	v_mfma_f32_16x16x32_bf16 v[14:17], v[164:167], v[212:215], v[14:17]
	s_nop 0
	s_nop 0
	v_mfma_f32_16x16x32_bf16 v[50:53], v[168:171], v[184:187], v[50:53]
	v_mfma_f32_16x16x32_bf16 v[42:45], v[176:179], v[184:187], v[42:45]
	v_mfma_f32_16x16x32_bf16 v[34:37], v[168:171], v[192:195], v[34:37]
	v_mfma_f32_16x16x32_bf16 v[26:29], v[176:179], v[192:195], v[26:29]
	v_mfma_f32_16x16x32_bf16 v[18:21], v[168:171], v[200:203], v[18:21]
	v_mfma_f32_16x16x32_bf16 v[10:13], v[176:179], v[200:203], v[10:13]
	v_mfma_f32_16x16x32_bf16 v[6:9], v[168:171], v[208:211], v[6:9]
	v_mfma_f32_16x16x32_bf16 v[2:5], v[176:179], v[208:211], v[2:5]
	v_mfma_f32_16x16x32_bf16 v[50:53], v[172:175], v[188:191], v[50:53]
	v_mfma_f32_16x16x32_bf16 v[42:45], v[180:183], v[188:191], v[42:45]
	v_mfma_f32_16x16x32_bf16 v[34:37], v[172:175], v[196:199], v[34:37]
	v_mfma_f32_16x16x32_bf16 v[26:29], v[180:183], v[196:199], v[26:29]
	v_mfma_f32_16x16x32_bf16 v[18:21], v[172:175], v[204:207], v[18:21]
	v_mfma_f32_16x16x32_bf16 v[10:13], v[180:183], v[204:207], v[10:13]
	v_mfma_f32_16x16x32_bf16 v[6:9], v[172:175], v[212:215], v[6:9]
	v_mfma_f32_16x16x32_bf16 v[2:5], v[180:183], v[212:215], v[2:5]
	s_nop 0
	s_barrier
	v_add_u32_e32 v138, s50, v149
	ds_read_b128 v[144:147], v138
	ds_read_b128 v[156:159], v138 offset:1024
	ds_read_b128 v[160:163], v138 offset:2048
	ds_read_b128 v[164:167], v138 offset:3072
	v_add_u32_e32 v138, s51, v149
	ds_read_b128 v[168:171], v138
	ds_read_b128 v[172:175], v138 offset:1024
	ds_read_b128 v[176:179], v138 offset:2048
	ds_read_b128 v[180:183], v138 offset:3072
	s_mov_b32 m0, s60
	v_lshl_add_u64 v[218:219], s[38:39], 0, v[130:131]
	ds_read_b128 v[184:187], v153 offset:32768
	ds_read_b128 v[188:191], v153 offset:33792
	ds_read_b128 v[192:195], v153 offset:34816
	ds_read_b128 v[196:199], v153 offset:35840
	ds_read_b128 v[200:203], v153 offset:36864
	ds_read_b128 v[204:207], v153 offset:37888
	ds_read_b128 v[208:211], v153 offset:38912
	ds_read_b128 v[212:215], v153 offset:39936
	global_load_lds_dwordx4 v[218:219], off
	v_lshl_add_u64 v[218:219], s[38:39], 0, v[134:135]
	s_mov_b32 m0, s61
	s_nop 0
	global_load_lds_dwordx4 v[218:219], off
	s_waitcnt vmcnt(8)
	s_waitcnt lgkmcnt(0)
	s_barrier
	s_nop 0
	s_waitcnt lgkmcnt(0)
	v_mfma_f32_16x16x32_bf16 v[126:129], v[144:147], v[184:187], v[126:129]
	v_mfma_f32_16x16x32_bf16 v[122:125], v[160:163], v[184:187], v[122:125]
	v_mfma_f32_16x16x32_bf16 v[118:121], v[144:147], v[192:195], v[118:121]
	v_mfma_f32_16x16x32_bf16 v[114:117], v[160:163], v[192:195], v[114:117]
	v_mfma_f32_16x16x32_bf16 v[102:105], v[144:147], v[200:203], v[102:105]
	v_mfma_f32_16x16x32_bf16 v[98:101], v[160:163], v[200:203], v[98:101]
	v_mfma_f32_16x16x32_bf16 v[86:89], v[144:147], v[208:211], v[86:89]
	v_mfma_f32_16x16x32_bf16 v[82:85], v[160:163], v[208:211], v[82:85]
	v_mfma_f32_16x16x32_bf16 v[126:129], v[156:159], v[188:191], v[126:129]
	v_mfma_f32_16x16x32_bf16 v[122:125], v[164:167], v[188:191], v[122:125]
	v_mfma_f32_16x16x32_bf16 v[118:121], v[156:159], v[196:199], v[118:121]
	v_mfma_f32_16x16x32_bf16 v[114:117], v[164:167], v[196:199], v[114:117]
	v_mfma_f32_16x16x32_bf16 v[102:105], v[156:159], v[204:207], v[102:105]
	v_mfma_f32_16x16x32_bf16 v[98:101], v[164:167], v[204:207], v[98:101]
	v_mfma_f32_16x16x32_bf16 v[86:89], v[156:159], v[212:215], v[86:89]
	v_mfma_f32_16x16x32_bf16 v[82:85], v[164:167], v[212:215], v[82:85]
	s_nop 0
	s_nop 0
	v_mfma_f32_16x16x32_bf16 v[110:113], v[168:171], v[184:187], v[110:113]
	v_mfma_f32_16x16x32_bf16 v[106:109], v[176:179], v[184:187], v[106:109]
	v_mfma_f32_16x16x32_bf16 v[94:97], v[168:171], v[192:195], v[94:97]
	v_mfma_f32_16x16x32_bf16 v[90:93], v[176:179], v[192:195], v[90:93]
	v_mfma_f32_16x16x32_bf16 v[78:81], v[168:171], v[200:203], v[78:81]
	v_mfma_f32_16x16x32_bf16 v[74:77], v[176:179], v[200:203], v[74:77]
	v_mfma_f32_16x16x32_bf16 v[70:73], v[168:171], v[208:211], v[70:73]
	v_mfma_f32_16x16x32_bf16 v[66:69], v[176:179], v[208:211], v[66:69]
	v_mfma_f32_16x16x32_bf16 v[110:113], v[172:175], v[188:191], v[110:113]
	v_mfma_f32_16x16x32_bf16 v[106:109], v[180:183], v[188:191], v[106:109]
	v_mfma_f32_16x16x32_bf16 v[94:97], v[172:175], v[196:199], v[94:97]
	v_mfma_f32_16x16x32_bf16 v[90:93], v[180:183], v[196:199], v[90:93]
	v_mfma_f32_16x16x32_bf16 v[78:81], v[172:175], v[204:207], v[78:81]
	v_mfma_f32_16x16x32_bf16 v[74:77], v[180:183], v[204:207], v[74:77]
	v_mfma_f32_16x16x32_bf16 v[70:73], v[172:175], v[212:215], v[70:73]
	v_mfma_f32_16x16x32_bf16 v[66:69], v[180:183], v[212:215], v[66:69]
	s_nop 0
	s_barrier
; #define G8_STAGE(bufoff, gbase, voff) do { _Pragma("unroll") for (int _i = 0; _i < 2; ++_i) \
;         __builtin_amdgcn_global_load_lds((const unsigned*)((const char*)(gbase) + (voff)[_i]), (LAS unsigned*)(lds + (bufoff) + ldsw + _i * 8192), 16, 0, 0); } while (0)
; #define G8_LDA(dst, b, h) do { _Pragma("unroll") for (int m = 0; m < 4; ++m) _Pragma("unroll") for (int k = 0; k < 2; ++k) dst[m][k] = *(const LAS bf16x8*)(lds + G8_SA(b, h) + aoff + m * 2048 + k * 1024); } while (0)
; #define G8_MMA(ai, bj, At, Bt) do { __builtin_amdgcn_s_setprio(1); _Pragma("unroll") for (int m = 0; m < 4; ++m) _Pragma("unroll") for (int n = 0; n < 2; ++n) _Pragma("unroll") for (int k = 0; k < 2; ++k) \
;         acc[ai][bj][m][n] = __builtin_amdgcn_mfma_f32_16x16x32_bf16(Bt[n][k], At[m][k], acc[ai][bj][m][n], 0, 0, 0); __builtin_amdgcn_s_setprio(0); } while (0)
; #define G8_WAIT_V(n) asm volatile("s_waitcnt vmcnt(" #n ")" ::: "memory")
; #define G8_WAIT_L(n) asm volatile("s_waitcnt lgkmcnt(" #n ")" ::: "memory")
; #define G8_BAR __builtin_amdgcn_s_barrier()
; #define G8_SCHED __builtin_amdgcn_sched_barrier(0)
; template <class Epi, class Sched>
; DEV void gemm_phase(LAS char* lds, const Sched& S, const Epi& E) {
;     ...
;             G8_LDA(At, 1, 1); G8_STAGE(G8_SB(1, 0), b3, voffB); G8_STAGE(G8_SB(1, 1), b3 + hstepB, voffB); G8_STAGE(G8_SA(1, 0), a3, voffA);
;             G8_WAIT_V(8); G8_WAIT_L(0); G8_BAR; G8_MMA(1, 0, At, B0); G8_MMA(1, 1, At, B1); G8_BAR; G8_SCHED;
;         }
;         if (wr == 0) G8_BAR;
;         E(lds, acc, cur, wr, wc, fr, fq, wid, lane);
;         if (!has_next) break;
	s_mov_b32 m0, s59
	v_lshl_add_u64 v[0:1], v[0:1], 0, s[6:7]
	ds_read_b128 v[184:187], v153 offset:49152
	ds_read_b128 v[188:191], v153 offset:50176
	ds_read_b128 v[192:195], v153 offset:51200
	ds_read_b128 v[196:199], v153 offset:52224
	ds_read_b128 v[200:203], v153 offset:53248
	ds_read_b128 v[204:207], v153 offset:54272
	ds_read_b128 v[208:211], v153 offset:55296
	ds_read_b128 v[212:215], v153 offset:56320
	global_load_lds_dwordx4 v[0:1], off
	v_lshl_add_u64 v[0:1], v[216:217], 0, s[6:7]
	s_mov_b32 m0, s17
	s_nop 0
	global_load_lds_dwordx4 v[0:1], off
	v_lshl_add_u64 v[0:1], s[34:35], 0, v[132:133]
	s_mov_b32 m0, s58
	s_nop 0
	global_load_lds_dwordx4 v[0:1], off
	v_lshl_add_u64 v[0:1], s[34:35], 0, v[136:137]
	s_mov_b32 m0, s15
	s_nop 0
	global_load_lds_dwordx4 v[0:1], off
	v_lshl_add_u64 v[0:1], s[30:31], 0, v[130:131]
	s_mov_b32 m0, s52
	s_nop 0
	global_load_lds_dwordx4 v[0:1], off
	v_lshl_add_u64 v[0:1], s[30:31], 0, v[134:135]
	s_mov_b32 m0, s71
	s_nop 0
	global_load_lds_dwordx4 v[0:1], off
	s_waitcnt vmcnt(8)
	s_waitcnt lgkmcnt(0)
	s_barrier
	s_nop 0
	s_waitcnt lgkmcnt(0)
	v_mfma_f32_16x16x32_bf16 v[62:65], v[144:147], v[184:187], v[62:65]
	v_mfma_f32_16x16x32_bf16 v[58:61], v[160:163], v[184:187], v[58:61]
	v_mfma_f32_16x16x32_bf16 v[54:57], v[144:147], v[192:195], v[54:57]
	v_mfma_f32_16x16x32_bf16 v[46:49], v[160:163], v[192:195], v[46:49]
	v_mfma_f32_16x16x32_bf16 v[38:41], v[144:147], v[200:203], v[38:41]
	v_mfma_f32_16x16x32_bf16 v[30:33], v[160:163], v[200:203], v[30:33]
	v_mfma_f32_16x16x32_bf16 v[22:25], v[144:147], v[208:211], v[22:25]
	v_mfma_f32_16x16x32_bf16 v[14:17], v[160:163], v[208:211], v[14:17]
	v_mfma_f32_16x16x32_bf16 v[62:65], v[156:159], v[188:191], v[62:65]
	v_mfma_f32_16x16x32_bf16 v[58:61], v[164:167], v[188:191], v[58:61]
	v_mfma_f32_16x16x32_bf16 v[54:57], v[156:159], v[196:199], v[54:57]
	v_mfma_f32_16x16x32_bf16 v[46:49], v[164:167], v[196:199], v[46:49]
	v_mfma_f32_16x16x32_bf16 v[38:41], v[156:159], v[204:207], v[38:41]
	v_mfma_f32_16x16x32_bf16 v[30:33], v[164:167], v[204:207], v[30:33]
	v_mfma_f32_16x16x32_bf16 v[22:25], v[156:159], v[212:215], v[22:25]
	v_mfma_f32_16x16x32_bf16 v[14:17], v[164:167], v[212:215], v[14:17]
	s_nop 0
	s_nop 0
	v_mfma_f32_16x16x32_bf16 v[50:53], v[168:171], v[184:187], v[50:53]
	v_mfma_f32_16x16x32_bf16 v[42:45], v[176:179], v[184:187], v[42:45]
	v_mfma_f32_16x16x32_bf16 v[34:37], v[168:171], v[192:195], v[34:37]
	v_mfma_f32_16x16x32_bf16 v[26:29], v[176:179], v[192:195], v[26:29]
	v_mfma_f32_16x16x32_bf16 v[18:21], v[168:171], v[200:203], v[18:21]
	v_mfma_f32_16x16x32_bf16 v[10:13], v[176:179], v[200:203], v[10:13]
	v_mfma_f32_16x16x32_bf16 v[6:9], v[168:171], v[208:211], v[6:9]
	v_mfma_f32_16x16x32_bf16 v[2:5], v[176:179], v[208:211], v[2:5]
	v_mfma_f32_16x16x32_bf16 v[50:53], v[172:175], v[188:191], v[50:53]
	v_mfma_f32_16x16x32_bf16 v[42:45], v[180:183], v[188:191], v[42:45]
	v_mfma_f32_16x16x32_bf16 v[34:37], v[172:175], v[196:199], v[34:37]
	v_mfma_f32_16x16x32_bf16 v[26:29], v[180:183], v[196:199], v[26:29]
	v_mfma_f32_16x16x32_bf16 v[18:21], v[172:175], v[204:207], v[18:21]
	v_mfma_f32_16x16x32_bf16 v[10:13], v[180:183], v[204:207], v[10:13]
	v_mfma_f32_16x16x32_bf16 v[6:9], v[172:175], v[212:215], v[6:9]
	v_mfma_f32_16x16x32_bf16 v[2:5], v[180:183], v[212:215], v[2:5]
	s_nop 0
	s_barrier
	s_andn2_b64 vcc, exec, s[28:29]
	s_mov_b64 s[30:31], -1
	s_mov_b64 s[28:29], 0
	s_mov_b64 s[34:35], 0x100
	s_cbranch_vccz .LBB0_521
	s_and_b64 vcc, exec, s[10:11]
	s_cbranch_vccnz .LBB0_526
	s_cmp_gt_u32 s73, 3
	s_mov_b64 s[0:1], -1
	s_cbranch_scc1 .LBB0_527

; #define G8_STAGE(bufoff, gbase, voff) do { _Pragma("unroll") for (int _i = 0; _i < 2; ++_i) \
;         __builtin_amdgcn_global_load_lds((const unsigned*)((const char*)(gbase) + (voff)[_i]), (LAS unsigned*)(lds + (bufoff) + ldsw + _i * 8192), 16, 0, 0); } while (0)
; #define G8_LDA(dst, b, h) do { _Pragma("unroll") for (int m = 0; m < 4; ++m) _Pragma("unroll") for (int k = 0; k < 2; ++k) dst[m][k] = *(const LAS bf16x8*)(lds + G8_SA(b, h) + aoff + m * 2048 + k * 1024); } while (0)
; #define G8_LDB(dst, b, h) do { _Pragma("unroll") for (int n = 0; n < 2; ++n) _Pragma("unroll") for (int k = 0; k < 2; ++k) dst[n][k] = *(const LAS bf16x8*)(lds + G8_SB(b, h) + boff + n * 2048 + k * 1024); } while (0)
; #define G8_MMA(ai, bj, At, Bt) do { __builtin_amdgcn_s_setprio(1); _Pragma("unroll") for (int m = 0; m < 4; ++m) _Pragma("unroll") for (int n = 0; n < 2; ++n) _Pragma("unroll") for (int k = 0; k < 2; ++k) \
;         acc[ai][bj][m][n] = __builtin_amdgcn_mfma_f32_16x16x32_bf16(Bt[n][k], At[m][k], acc[ai][bj][m][n], 0, 0, 0); __builtin_amdgcn_s_setprio(0); } while (0)
; #define G8_WAIT_V(n) asm volatile("s_waitcnt vmcnt(" #n ")" ::: "memory")
; #define G8_WAIT_L(n) asm volatile("s_waitcnt lgkmcnt(" #n ")" ::: "memory")
; #define G8_BAR __builtin_amdgcn_s_barrier()
; #define G8_SCHED __builtin_amdgcn_sched_barrier(0)
; template <class Epi, class Sched>
; DEV void gemm_phase(LAS char* lds, const Sched& S, const Epi& E) {
;     ...
;         for (int t = 0; t < nt; t += 2) {
;             const bool last = (t == nt - 2);
;             const char* a1 = G8_AK(t + 1);
;             const char* a2 = last ? nA : G8_AK(t + 2); const char* b2 = last ? nB : cB + (size_t)(t + 2) * kstep;
;             const char* a3 = last ? nA + kstepA : G8_AK(t + 3); const char* b3 = b2 + kstep;
;             G8_LDB(B0, 0, 0); G8_LDB(B1, 0, 1); G8_SCHED; G8_LDA(At, 0, 0); G8_STAGE(G8_SA(1, 1), a1 + hstepA, voffA);
;             G8_WAIT_V(8); G8_WAIT_L(0); G8_BAR; G8_MMA(0, 0, At, B0); G8_MMA(0, 1, At, B1); G8_BAR; G8_SCHED;
;             G8_LDA(At, 0, 1); G8_STAGE(G8_SB(0, 0), b2, voffB); G8_STAGE(G8_SB(0, 1), b2 + hstepB, voffB); G8_STAGE(G8_SA(0, 0), a2, voffA);
.LBB0_714:
	ds_read_b128 v[146:149], v206
	ds_read_b128 v[150:153], v206 offset:1024
	ds_read_b128 v[154:157], v206 offset:2048
	ds_read_b128 v[158:161], v206 offset:3072
	ds_read_b128 v[162:165], v207
	ds_read_b128 v[166:169], v207 offset:1024
	ds_read_b128 v[170:173], v207 offset:2048
	ds_read_b128 v[174:177], v207 offset:3072
	s_add_u32 s44, s8, s42
	s_addc_u32 s45, s9, s43
	s_add_u32 s46, s44, 0x100
	s_addc_u32 s47, s45, 0
	s_add_u32 s52, s26, s42
	s_addc_u32 s54, s31, s43
	s_add_u32 s44, s44, 0x180
	s_addc_u32 s45, s45, 0
	s_cmpk_eq_i32 s42, 0x700
	s_cselect_b32 s81, s1, s45
	s_cselect_b32 s80, s0, s44
	s_cselect_b32 s83, s37, s54
	s_cselect_b32 s82, s36, s52
	s_cselect_b32 s85, s35, s47
	s_cselect_b32 s84, s34, s46
	v_lshl_add_u64 v[0:1], v[132:133], 0, s[42:43]
	s_add_i32 m0, s92, 0xc000
	ds_read_b128 v[178:181], v208
	ds_read_b128 v[182:185], v208 offset:1024
	ds_read_b128 v[186:189], v208 offset:2048
	ds_read_b128 v[190:193], v208 offset:3072
	ds_read_b128 v[194:197], v208 offset:4096
	ds_read_b128 v[198:201], v208 offset:5120
	ds_read_b128 v[214:217], v208 offset:6144
	ds_read_b128 v[218:221], v208 offset:7168
	global_load_lds_dwordx4 v[0:1], off
	v_lshl_add_u64 v[0:1], v[130:131], 0, s[42:43]
	s_add_i32 m0, s92, 0xe000
	s_nop 0
	global_load_lds_dwordx4 v[0:1], off
	s_waitcnt vmcnt(8)
	s_waitcnt lgkmcnt(0)
	s_barrier
	s_nop 0
	s_waitcnt lgkmcnt(0)
	v_mfma_f32_16x16x32_bf16 v[126:129], v[146:149], v[178:181], v[126:129]
	v_mfma_f32_16x16x32_bf16 v[122:125], v[154:157], v[178:181], v[122:125]
	v_mfma_f32_16x16x32_bf16 v[118:121], v[146:149], v[186:189], v[118:121]
	v_mfma_f32_16x16x32_bf16 v[114:117], v[154:157], v[186:189], v[114:117]
	v_mfma_f32_16x16x32_bf16 v[110:113], v[146:149], v[194:197], v[110:113]
	v_mfma_f32_16x16x32_bf16 v[106:109], v[154:157], v[194:197], v[106:109]
	v_mfma_f32_16x16x32_bf16 v[102:105], v[146:149], v[214:217], v[102:105]
	v_mfma_f32_16x16x32_bf16 v[98:101], v[154:157], v[214:217], v[98:101]
	v_mfma_f32_16x16x32_bf16 v[126:129], v[150:153], v[182:185], v[126:129]
	v_mfma_f32_16x16x32_bf16 v[122:125], v[158:161], v[182:185], v[122:125]
	v_mfma_f32_16x16x32_bf16 v[118:121], v[150:153], v[190:193], v[118:121]
	v_mfma_f32_16x16x32_bf16 v[114:117], v[158:161], v[190:193], v[114:117]
	v_mfma_f32_16x16x32_bf16 v[110:113], v[150:153], v[198:201], v[110:113]
	v_mfma_f32_16x16x32_bf16 v[106:109], v[158:161], v[198:201], v[106:109]
	v_mfma_f32_16x16x32_bf16 v[102:105], v[150:153], v[218:221], v[102:105]
	v_mfma_f32_16x16x32_bf16 v[98:101], v[158:161], v[218:221], v[98:101]
	s_nop 0
	s_nop 0
	v_mfma_f32_16x16x32_bf16 v[62:65], v[162:165], v[178:181], v[62:65]
	v_mfma_f32_16x16x32_bf16 v[58:61], v[170:173], v[178:181], v[58:61]
	v_mfma_f32_16x16x32_bf16 v[54:57], v[162:165], v[186:189], v[54:57]
	v_mfma_f32_16x16x32_bf16 v[50:53], v[170:173], v[186:189], v[50:53]
	v_mfma_f32_16x16x32_bf16 v[46:49], v[162:165], v[194:197], v[46:49]
	v_mfma_f32_16x16x32_bf16 v[42:45], v[170:173], v[194:197], v[42:45]
	v_mfma_f32_16x16x32_bf16 v[38:41], v[162:165], v[214:217], v[38:41]
	v_mfma_f32_16x16x32_bf16 v[34:37], v[170:173], v[214:217], v[34:37]
	v_mfma_f32_16x16x32_bf16 v[62:65], v[166:169], v[182:185], v[62:65]
	v_mfma_f32_16x16x32_bf16 v[58:61], v[174:177], v[182:185], v[58:61]
	v_mfma_f32_16x16x32_bf16 v[54:57], v[166:169], v[190:193], v[54:57]
	v_mfma_f32_16x16x32_bf16 v[50:53], v[174:177], v[190:193], v[50:53]
	v_mfma_f32_16x16x32_bf16 v[46:49], v[166:169], v[198:201], v[46:49]
	v_mfma_f32_16x16x32_bf16 v[42:45], v[174:177], v[198:201], v[42:45]
	v_mfma_f32_16x16x32_bf16 v[38:41], v[166:169], v[218:221], v[38:41]
	v_mfma_f32_16x16x32_bf16 v[34:37], v[174:177], v[218:221], v[34:37]
	s_nop 0
	s_barrier
	s_add_i32 s44, s62, s91
	v_lshl_add_u64 v[0:1], s[82:83], 0, v[136:137]
	s_mov_b32 m0, s44
	ds_read_b128 v[178:181], v208 offset:16384
	ds_read_b128 v[182:185], v208 offset:17408
	ds_read_b128 v[186:189], v208 offset:18432
	ds_read_b128 v[190:193], v208 offset:19456
	ds_read_b128 v[194:197], v208 offset:20480
	ds_read_b128 v[198:201], v208 offset:21504
	ds_read_b128 v[214:217], v208 offset:22528
	ds_read_b128 v[218:221], v208 offset:23552
	global_load_lds_dwordx4 v[0:1], off
	s_add_i32 m0, s44, 0x2000
	s_add_u32 s44, s82, 0x200000
	v_lshl_add_u64 v[222:223], s[82:83], 0, v[140:141]
	s_addc_u32 s45, s83, 0
	s_add_i32 s46, s63, s91
	global_load_lds_dwordx4 v[222:223], off
	v_lshl_add_u64 v[224:225], s[44:45], 0, v[136:137]
	s_mov_b32 m0, s46
	s_nop 0
	global_load_lds_dwordx4 v[224:225], off
	v_lshl_add_u64 v[224:225], s[44:45], 0, v[140:141]
	s_add_i32 m0, s46, 0x2000
	s_nop 0
	global_load_lds_dwordx4 v[224:225], off
	v_lshl_add_u64 v[224:225], s[84:85], 0, v[134:135]
	s_mov_b32 m0, s92
	s_nop 0
	global_load_lds_dwordx4 v[224:225], off
	v_lshl_add_u64 v[224:225], s[84:85], 0, v[138:139]
	s_mov_b32 m0, s93
	s_nop 0
	global_load_lds_dwordx4 v[224:225], off
	s_waitcnt vmcnt(8)
	s_waitcnt lgkmcnt(0)
	s_barrier
; #define G8_STAGE(bufoff, gbase, voff) do { _Pragma("unroll") for (int _i = 0; _i < 2; ++_i) \
;         __builtin_amdgcn_global_load_lds((const unsigned*)((const char*)(gbase) + (voff)[_i]), (LAS unsigned*)(lds + (bufoff) + ldsw + _i * 8192), 16, 0, 0); } while (0)
; #define G8_LDA(dst, b, h) do { _Pragma("unroll") for (int m = 0; m < 4; ++m) _Pragma("unroll") for (int k = 0; k < 2; ++k) dst[m][k] = *(const LAS bf16x8*)(lds + G8_SA(b, h) + aoff + m * 2048 + k * 1024); } while (0)
; #define G8_LDB(dst, b, h) do { _Pragma("unroll") for (int n = 0; n < 2; ++n) _Pragma("unroll") for (int k = 0; k < 2; ++k) dst[n][k] = *(const LAS bf16x8*)(lds + G8_SB(b, h) + boff + n * 2048 + k * 1024); } while (0)
; #define G8_MMA(ai, bj, At, Bt) do { __builtin_amdgcn_s_setprio(1); _Pragma("unroll") for (int m = 0; m < 4; ++m) _Pragma("unroll") for (int n = 0; n < 2; ++n) _Pragma("unroll") for (int k = 0; k < 2; ++k) \
;         acc[ai][bj][m][n] = __builtin_amdgcn_mfma_f32_16x16x32_bf16(Bt[n][k], At[m][k], acc[ai][bj][m][n], 0, 0, 0); __builtin_amdgcn_s_setprio(0); } while (0)
; #define G8_WAIT_V(n) asm volatile("s_waitcnt vmcnt(" #n ")" ::: "memory")
; #define G8_WAIT_L(n) asm volatile("s_waitcnt lgkmcnt(" #n ")" ::: "memory")
; #define G8_BAR __builtin_amdgcn_s_barrier()
; #define G8_SCHED __builtin_amdgcn_sched_barrier(0)
; template <class Epi, class Sched>
; DEV void gemm_phase(LAS char* lds, const Sched& S, const Epi& E) {
;     ...
;             G8_WAIT_V(8); G8_WAIT_L(0); G8_BAR; G8_MMA(1, 0, At, B0); G8_MMA(1, 1, At, B1); G8_BAR; G8_SCHED;
;             G8_LDB(B0, 1, 0); G8_LDB(B1, 1, 1); G8_SCHED; G8_LDA(At, 1, 0); G8_STAGE(G8_SA(0, 1), a2 + hstepA, voffA);
;             G8_WAIT_V(8); G8_WAIT_L(0); G8_BAR; G8_MMA(0, 0, At, B0); G8_MMA(0, 1, At, B1); G8_BAR; G8_SCHED;
	s_nop 0
	s_waitcnt lgkmcnt(0)
	v_mfma_f32_16x16x32_bf16 v[94:97], v[146:149], v[178:181], v[94:97]
	v_mfma_f32_16x16x32_bf16 v[90:93], v[154:157], v[178:181], v[90:93]
	v_mfma_f32_16x16x32_bf16 v[86:89], v[146:149], v[186:189], v[86:89]
	v_mfma_f32_16x16x32_bf16 v[82:85], v[154:157], v[186:189], v[82:85]
	v_mfma_f32_16x16x32_bf16 v[78:81], v[146:149], v[194:197], v[78:81]
	v_mfma_f32_16x16x32_bf16 v[74:77], v[154:157], v[194:197], v[74:77]
	v_mfma_f32_16x16x32_bf16 v[70:73], v[146:149], v[214:217], v[70:73]
	v_mfma_f32_16x16x32_bf16 v[66:69], v[154:157], v[214:217], v[66:69]
	v_mfma_f32_16x16x32_bf16 v[94:97], v[150:153], v[182:185], v[94:97]
	v_mfma_f32_16x16x32_bf16 v[90:93], v[158:161], v[182:185], v[90:93]
	v_mfma_f32_16x16x32_bf16 v[86:89], v[150:153], v[190:193], v[86:89]
	v_mfma_f32_16x16x32_bf16 v[82:85], v[158:161], v[190:193], v[82:85]
	v_mfma_f32_16x16x32_bf16 v[78:81], v[150:153], v[198:201], v[78:81]
	v_mfma_f32_16x16x32_bf16 v[74:77], v[158:161], v[198:201], v[74:77]
	v_mfma_f32_16x16x32_bf16 v[70:73], v[150:153], v[218:221], v[70:73]
	v_mfma_f32_16x16x32_bf16 v[66:69], v[158:161], v[218:221], v[66:69]
	s_nop 0
	s_nop 0
	v_mfma_f32_16x16x32_bf16 v[30:33], v[162:165], v[178:181], v[30:33]
	v_mfma_f32_16x16x32_bf16 v[26:29], v[170:173], v[178:181], v[26:29]
	v_mfma_f32_16x16x32_bf16 v[22:25], v[162:165], v[186:189], v[22:25]
	v_mfma_f32_16x16x32_bf16 v[18:21], v[170:173], v[186:189], v[18:21]
	v_mfma_f32_16x16x32_bf16 v[14:17], v[162:165], v[194:197], v[14:17]
	v_mfma_f32_16x16x32_bf16 v[10:13], v[170:173], v[194:197], v[10:13]
	v_mfma_f32_16x16x32_bf16 v[6:9], v[162:165], v[214:217], v[6:9]
	v_mfma_f32_16x16x32_bf16 v[2:5], v[170:173], v[214:217], v[2:5]
	v_mfma_f32_16x16x32_bf16 v[30:33], v[166:169], v[182:185], v[30:33]
	v_mfma_f32_16x16x32_bf16 v[26:29], v[174:177], v[182:185], v[26:29]
	v_mfma_f32_16x16x32_bf16 v[22:25], v[166:169], v[190:193], v[22:25]
	v_mfma_f32_16x16x32_bf16 v[18:21], v[174:177], v[190:193], v[18:21]
	v_mfma_f32_16x16x32_bf16 v[14:17], v[166:169], v[198:201], v[14:17]
	v_mfma_f32_16x16x32_bf16 v[10:13], v[174:177], v[198:201], v[10:13]
	v_mfma_f32_16x16x32_bf16 v[6:9], v[166:169], v[218:221], v[6:9]
	v_mfma_f32_16x16x32_bf16 v[2:5], v[174:177], v[218:221], v[2:5]
	s_nop 0
	s_barrier
	v_add_u32_e32 v158, s50, v204
	v_add_u32_e32 v174, s51, v204
	ds_read_b128 v[146:149], v158
	ds_read_b128 v[150:153], v158 offset:1024
	ds_read_b128 v[154:157], v158 offset:2048
	ds_read_b128 v[158:161], v158 offset:3072
	ds_read_b128 v[162:165], v174
	ds_read_b128 v[166:169], v174 offset:1024
	ds_read_b128 v[170:173], v174 offset:2048
	ds_read_b128 v[174:177], v174 offset:3072
	s_add_u32 s44, s84, 0x40000
	s_addc_u32 s45, s85, 0
	s_mov_b32 m0, s94
	v_lshl_add_u64 v[224:225], s[44:45], 0, v[134:135]
	ds_read_b128 v[178:181], v208 offset:32768
	ds_read_b128 v[182:185], v208 offset:33792
	ds_read_b128 v[186:189], v208 offset:34816
	ds_read_b128 v[190:193], v208 offset:35840
	ds_read_b128 v[194:197], v208 offset:36864
	ds_read_b128 v[198:201], v208 offset:37888
	ds_read_b128 v[214:217], v208 offset:38912
	ds_read_b128 v[218:221], v208 offset:39936
	global_load_lds_dwordx4 v[224:225], off
	v_lshl_add_u64 v[224:225], s[44:45], 0, v[138:139]
	s_mov_b32 m0, s95
	s_nop 0
	global_load_lds_dwordx4 v[224:225], off
	s_waitcnt vmcnt(8)
	s_waitcnt lgkmcnt(0)
	s_barrier
	s_nop 0
	s_waitcnt lgkmcnt(0)
	v_mfma_f32_16x16x32_bf16 v[126:129], v[146:149], v[178:181], v[126:129]
	v_mfma_f32_16x16x32_bf16 v[122:125], v[154:157], v[178:181], v[122:125]
	v_mfma_f32_16x16x32_bf16 v[118:121], v[146:149], v[186:189], v[118:121]
	v_mfma_f32_16x16x32_bf16 v[114:117], v[154:157], v[186:189], v[114:117]
	v_mfma_f32_16x16x32_bf16 v[110:113], v[146:149], v[194:197], v[110:113]
	v_mfma_f32_16x16x32_bf16 v[106:109], v[154:157], v[194:197], v[106:109]
	v_mfma_f32_16x16x32_bf16 v[102:105], v[146:149], v[214:217], v[102:105]
	v_mfma_f32_16x16x32_bf16 v[98:101], v[154:157], v[214:217], v[98:101]
	v_mfma_f32_16x16x32_bf16 v[126:129], v[150:153], v[182:185], v[126:129]
	v_mfma_f32_16x16x32_bf16 v[122:125], v[158:161], v[182:185], v[122:125]
	v_mfma_f32_16x16x32_bf16 v[118:121], v[150:153], v[190:193], v[118:121]
	v_mfma_f32_16x16x32_bf16 v[114:117], v[158:161], v[190:193], v[114:117]
	v_mfma_f32_16x16x32_bf16 v[110:113], v[150:153], v[198:201], v[110:113]
	v_mfma_f32_16x16x32_bf16 v[106:109], v[158:161], v[198:201], v[106:109]
	v_mfma_f32_16x16x32_bf16 v[102:105], v[150:153], v[218:221], v[102:105]
	v_mfma_f32_16x16x32_bf16 v[98:101], v[158:161], v[218:221], v[98:101]
	s_nop 0
	s_nop 0
	v_mfma_f32_16x16x32_bf16 v[62:65], v[162:165], v[178:181], v[62:65]
	v_mfma_f32_16x16x32_bf16 v[58:61], v[170:173], v[178:181], v[58:61]
	v_mfma_f32_16x16x32_bf16 v[54:57], v[162:165], v[186:189], v[54:57]
	v_mfma_f32_16x16x32_bf16 v[50:53], v[170:173], v[186:189], v[50:53]
	v_mfma_f32_16x16x32_bf16 v[46:49], v[162:165], v[194:197], v[46:49]
	v_mfma_f32_16x16x32_bf16 v[42:45], v[170:173], v[194:197], v[42:45]
	v_mfma_f32_16x16x32_bf16 v[38:41], v[162:165], v[214:217], v[38:41]
	v_mfma_f32_16x16x32_bf16 v[34:37], v[170:173], v[214:217], v[34:37]
	v_mfma_f32_16x16x32_bf16 v[62:65], v[166:169], v[182:185], v[62:65]
	v_mfma_f32_16x16x32_bf16 v[58:61], v[174:177], v[182:185], v[58:61]
	v_mfma_f32_16x16x32_bf16 v[54:57], v[166:169], v[190:193], v[54:57]
	v_mfma_f32_16x16x32_bf16 v[50:53], v[174:177], v[190:193], v[50:53]
	v_mfma_f32_16x16x32_bf16 v[46:49], v[166:169], v[198:201], v[46:49]
	v_mfma_f32_16x16x32_bf16 v[42:45], v[174:177], v[198:201], v[42:45]
	v_mfma_f32_16x16x32_bf16 v[38:41], v[166:169], v[218:221], v[38:41]
	v_mfma_f32_16x16x32_bf16 v[34:37], v[174:177], v[218:221], v[34:37]
	s_nop 0
	s_barrier
; #define G8_STAGE(bufoff, gbase, voff) do { _Pragma("unroll") for (int _i = 0; _i < 2; ++_i) \
;         __builtin_amdgcn_global_load_lds((const unsigned*)((const char*)(gbase) + (voff)[_i]), (LAS unsigned*)(lds + (bufoff) + ldsw + _i * 8192), 16, 0, 0); } while (0)
; #define G8_LDA(dst, b, h) do { _Pragma("unroll") for (int m = 0; m < 4; ++m) _Pragma("unroll") for (int k = 0; k < 2; ++k) dst[m][k] = *(const LAS bf16x8*)(lds + G8_SA(b, h) + aoff + m * 2048 + k * 1024); } while (0)
; #define G8_MMA(ai, bj, At, Bt) do { __builtin_amdgcn_s_setprio(1); _Pragma("unroll") for (int m = 0; m < 4; ++m) _Pragma("unroll") for (int n = 0; n < 2; ++n) _Pragma("unroll") for (int k = 0; k < 2; ++k) \
;         acc[ai][bj][m][n] = __builtin_amdgcn_mfma_f32_16x16x32_bf16(Bt[n][k], At[m][k], acc[ai][bj][m][n], 0, 0, 0); __builtin_amdgcn_s_setprio(0); } while (0)
; #define G8_WAIT_V(n) asm volatile("s_waitcnt vmcnt(" #n ")" ::: "memory")
; #define G8_WAIT_L(n) asm volatile("s_waitcnt lgkmcnt(" #n ")" ::: "memory")
; #define G8_BAR __builtin_amdgcn_s_barrier()
; #define G8_SCHED __builtin_amdgcn_sched_barrier(0)
; template <class Epi, class Sched>
; DEV void gemm_phase(LAS char* lds, const Sched& S, const Epi& E) {
;     ...
;             G8_LDA(At, 1, 1); G8_STAGE(G8_SB(1, 0), b3, voffB); G8_STAGE(G8_SB(1, 1), b3 + hstepB, voffB); G8_STAGE(G8_SA(1, 0), a3, voffA);
;             G8_WAIT_V(8); G8_WAIT_L(0); G8_BAR; G8_MMA(1, 0, At, B0); G8_MMA(1, 1, At, B1); G8_BAR; G8_SCHED;
;         }
;         if (wr == 0) G8_BAR;
	s_add_i32 s44, s50, s91
	v_lshl_add_u64 v[0:1], v[0:1], 0, s[24:25]
	s_mov_b32 m0, s44
	ds_read_b128 v[178:181], v208 offset:49152
	ds_read_b128 v[182:185], v208 offset:50176
	ds_read_b128 v[186:189], v208 offset:51200
	ds_read_b128 v[190:193], v208 offset:52224
	ds_read_b128 v[194:197], v208 offset:53248
	ds_read_b128 v[198:201], v208 offset:54272
	ds_read_b128 v[214:217], v208 offset:55296
	ds_read_b128 v[218:221], v208 offset:56320
	global_load_lds_dwordx4 v[0:1], off
	s_add_i32 m0, s44, 0x2000
	s_add_u32 s44, s82, 0x200080
	v_lshl_add_u64 v[0:1], v[222:223], 0, s[24:25]
	s_addc_u32 s45, s83, 0
	s_add_i32 s46, s51, s91
	global_load_lds_dwordx4 v[0:1], off
	v_lshl_add_u64 v[0:1], s[44:45], 0, v[136:137]
	s_mov_b32 m0, s46
	s_nop 0
	global_load_lds_dwordx4 v[0:1], off
	v_lshl_add_u64 v[0:1], s[44:45], 0, v[140:141]
	s_add_i32 m0, s46, 0x2000
	s_nop 0
	global_load_lds_dwordx4 v[0:1], off
	v_lshl_add_u64 v[0:1], s[80:81], 0, v[134:135]
	s_mov_b32 m0, s74
	s_nop 0
	global_load_lds_dwordx4 v[0:1], off
	v_lshl_add_u64 v[0:1], s[80:81], 0, v[138:139]
	s_mov_b32 m0, s75
	s_nop 0
	global_load_lds_dwordx4 v[0:1], off
	s_waitcnt vmcnt(8)
	s_waitcnt lgkmcnt(0)
	s_barrier
	s_nop 0
	s_waitcnt lgkmcnt(0)
	v_mfma_f32_16x16x32_bf16 v[94:97], v[146:149], v[178:181], v[94:97]
	v_mfma_f32_16x16x32_bf16 v[90:93], v[154:157], v[178:181], v[90:93]
	v_mfma_f32_16x16x32_bf16 v[86:89], v[146:149], v[186:189], v[86:89]
	v_mfma_f32_16x16x32_bf16 v[82:85], v[154:157], v[186:189], v[82:85]
	v_mfma_f32_16x16x32_bf16 v[78:81], v[146:149], v[194:197], v[78:81]
	v_mfma_f32_16x16x32_bf16 v[74:77], v[154:157], v[194:197], v[74:77]
	v_mfma_f32_16x16x32_bf16 v[70:73], v[146:149], v[214:217], v[70:73]
	v_mfma_f32_16x16x32_bf16 v[66:69], v[154:157], v[214:217], v[66:69]
	v_mfma_f32_16x16x32_bf16 v[94:97], v[150:153], v[182:185], v[94:97]
	v_mfma_f32_16x16x32_bf16 v[90:93], v[158:161], v[182:185], v[90:93]
	v_mfma_f32_16x16x32_bf16 v[86:89], v[150:153], v[190:193], v[86:89]
	v_mfma_f32_16x16x32_bf16 v[82:85], v[158:161], v[190:193], v[82:85]
	v_mfma_f32_16x16x32_bf16 v[78:81], v[150:153], v[198:201], v[78:81]
	v_mfma_f32_16x16x32_bf16 v[74:77], v[158:161], v[198:201], v[74:77]
	v_mfma_f32_16x16x32_bf16 v[70:73], v[150:153], v[218:221], v[70:73]
	v_mfma_f32_16x16x32_bf16 v[66:69], v[158:161], v[218:221], v[66:69]
	s_nop 0
	s_nop 0
	v_mfma_f32_16x16x32_bf16 v[30:33], v[162:165], v[178:181], v[30:33]
	v_mfma_f32_16x16x32_bf16 v[26:29], v[170:173], v[178:181], v[26:29]
	v_mfma_f32_16x16x32_bf16 v[22:25], v[162:165], v[186:189], v[22:25]
	v_mfma_f32_16x16x32_bf16 v[18:21], v[170:173], v[186:189], v[18:21]
	v_mfma_f32_16x16x32_bf16 v[14:17], v[162:165], v[194:197], v[14:17]
	v_mfma_f32_16x16x32_bf16 v[10:13], v[170:173], v[194:197], v[10:13]
	v_mfma_f32_16x16x32_bf16 v[6:9], v[162:165], v[214:217], v[6:9]
	v_mfma_f32_16x16x32_bf16 v[2:5], v[170:173], v[214:217], v[2:5]
	v_mfma_f32_16x16x32_bf16 v[30:33], v[166:169], v[182:185], v[30:33]
	v_mfma_f32_16x16x32_bf16 v[26:29], v[174:177], v[182:185], v[26:29]
	v_mfma_f32_16x16x32_bf16 v[22:25], v[166:169], v[190:193], v[22:25]
	v_mfma_f32_16x16x32_bf16 v[18:21], v[174:177], v[190:193], v[18:21]
	v_mfma_f32_16x16x32_bf16 v[14:17], v[166:169], v[198:201], v[14:17]
	v_mfma_f32_16x16x32_bf16 v[10:13], v[174:177], v[198:201], v[10:13]
	v_mfma_f32_16x16x32_bf16 v[6:9], v[166:169], v[218:221], v[6:9]
	v_mfma_f32_16x16x32_bf16 v[2:5], v[174:177], v[218:221], v[2:5]
	s_nop 0
	s_barrier
	s_add_i32 s41, s41, 2
	s_add_u32 s42, s42, 0x100
	s_addc_u32 s43, s43, 0
	s_cmp_gt_u32 s41, 13
	s_cbranch_scc0 .LBB0_714
	s_and_b64 vcc, exec, s[28:29]
	s_cbranch_vccz .LBB0_717
	s_barrier

; #define G8_STAGE(bufoff, gbase, voff) do { _Pragma("unroll") for (int _i = 0; _i < 2; ++_i) \
;         __builtin_amdgcn_global_load_lds((const unsigned*)((const char*)(gbase) + (voff)[_i]), (LAS unsigned*)(lds + (bufoff) + ldsw + _i * 8192), 16, 0, 0); } while (0)
; #define G8_LDA(dst, b, h) do { _Pragma("unroll") for (int m = 0; m < 4; ++m) _Pragma("unroll") for (int k = 0; k < 2; ++k) dst[m][k] = *(const LAS bf16x8*)(lds + G8_SA(b, h) + aoff + m * 2048 + k * 1024); } while (0)
; #define G8_LDB(dst, b, h) do { _Pragma("unroll") for (int n = 0; n < 2; ++n) _Pragma("unroll") for (int k = 0; k < 2; ++k) dst[n][k] = *(const LAS bf16x8*)(lds + G8_SB(b, h) + boff + n * 2048 + k * 1024); } while (0)
; #define G8_MMA(ai, bj, At, Bt) do { __builtin_amdgcn_s_setprio(1); _Pragma("unroll") for (int m = 0; m < 4; ++m) _Pragma("unroll") for (int n = 0; n < 2; ++n) _Pragma("unroll") for (int k = 0; k < 2; ++k) \
;         acc[ai][bj][m][n] = __builtin_amdgcn_mfma_f32_16x16x32_bf16(Bt[n][k], At[m][k], acc[ai][bj][m][n], 0, 0, 0); __builtin_amdgcn_s_setprio(0); } while (0)
; #define G8_WAIT_V(n) asm volatile("s_waitcnt vmcnt(" #n ")" ::: "memory")
; #define G8_WAIT_L(n) asm volatile("s_waitcnt lgkmcnt(" #n ")" ::: "memory")
; #define G8_BAR __builtin_amdgcn_s_barrier()
; #define G8_SCHED __builtin_amdgcn_sched_barrier(0)
; template <class Epi, class Sched>
; DEV void gemm_phase(LAS char* lds, const Sched& S, const Epi& E) {
;     ...
;         for (int t = 0; t < nt; t += 2) {
;             const bool last = (t == nt - 2);
;             const char* a1 = G8_AK(t + 1);
;             const char* a2 = last ? nA : G8_AK(t + 2); const char* b2 = last ? nB : cB + (size_t)(t + 2) * kstep;
;             const char* a3 = last ? nA + kstepA : G8_AK(t + 3); const char* b3 = b2 + kstep;
;             G8_LDB(B0, 0, 0); G8_LDB(B1, 0, 1); G8_SCHED; G8_LDA(At, 0, 0); G8_STAGE(G8_SA(1, 1), a1 + hstepA, voffA);
;             G8_WAIT_V(8); G8_WAIT_L(0); G8_BAR; G8_MMA(0, 0, At, B0); G8_MMA(0, 1, At, B1); G8_BAR; G8_SCHED;
;             G8_LDA(At, 0, 1); G8_STAGE(G8_SB(0, 0), b2, voffB); G8_STAGE(G8_SB(0, 1), b2 + hstepB, voffB); G8_STAGE(G8_SA(0, 0), a2, voffA);
.LBB0_851:
	v_add_u32_e32 v0, s62, v212
	ds_read_b128 v[106:109], v0
	ds_read_b128 v[110:113], v0 offset:1024
	ds_read_b128 v[118:121], v0 offset:2048
	ds_read_b128 v[126:129], v0 offset:3072
	v_add_u32_e32 v0, s63, v212
	ds_read_b128 v[146:149], v0
	ds_read_b128 v[150:153], v0 offset:1024
	ds_read_b128 v[154:157], v0 offset:2048
	ds_read_b128 v[158:161], v0 offset:3072
	s_and_b64 s[0:1], exec, s[90:91]
	s_cselect_b32 s91, s35, s41
	s_cselect_b32 s90, s34, s27
	s_add_u32 s0, s58, 0x40000
	s_addc_u32 s1, s59, 0
	v_lshl_add_u64 v[0:1], s[0:1], 0, v[164:165]
	s_add_i32 m0, s55, 0xc000
	ds_read_b128 v[170:173], v216
	ds_read_b128 v[174:177], v216 offset:1024
	ds_read_b128 v[178:181], v216 offset:2048
	ds_read_b128 v[182:185], v216 offset:3072
	ds_read_b128 v[186:189], v216 offset:4096
	ds_read_b128 v[190:193], v216 offset:5120
	ds_read_b128 v[194:197], v216 offset:6144
	ds_read_b128 v[198:201], v216 offset:7168
	global_load_lds_dwordx4 v[0:1], off
	v_lshl_add_u64 v[0:1], s[0:1], 0, v[166:167]
	s_add_i32 m0, s55, 0xe000
	s_nop 0
	global_load_lds_dwordx4 v[0:1], off
	s_waitcnt vmcnt(8)
	s_waitcnt lgkmcnt(0)
	s_barrier
	s_nop 0
	s_waitcnt lgkmcnt(0)
	v_mfma_f32_16x16x32_bf16 v[142:145], v[106:109], v[170:173], v[142:145]
	v_mfma_f32_16x16x32_bf16 v[138:141], v[118:121], v[170:173], v[138:141]
	v_mfma_f32_16x16x32_bf16 v[122:125], v[106:109], v[178:181], v[122:125]
	v_mfma_f32_16x16x32_bf16 v[114:117], v[118:121], v[178:181], v[114:117]
	v_mfma_f32_16x16x32_bf16 v[94:97], v[106:109], v[186:189], v[94:97]
	v_mfma_f32_16x16x32_bf16 v[90:93], v[118:121], v[186:189], v[90:93]
	v_mfma_f32_16x16x32_bf16 v[78:81], v[106:109], v[194:197], v[78:81]
	v_mfma_f32_16x16x32_bf16 v[74:77], v[118:121], v[194:197], v[74:77]
	v_mfma_f32_16x16x32_bf16 v[142:145], v[110:113], v[174:177], v[142:145]
	v_mfma_f32_16x16x32_bf16 v[138:141], v[126:129], v[174:177], v[138:141]
	v_mfma_f32_16x16x32_bf16 v[122:125], v[110:113], v[182:185], v[122:125]
	v_mfma_f32_16x16x32_bf16 v[114:117], v[126:129], v[182:185], v[114:117]
	v_mfma_f32_16x16x32_bf16 v[94:97], v[110:113], v[190:193], v[94:97]
	v_mfma_f32_16x16x32_bf16 v[90:93], v[126:129], v[190:193], v[90:93]
	v_mfma_f32_16x16x32_bf16 v[78:81], v[110:113], v[198:201], v[78:81]
	v_mfma_f32_16x16x32_bf16 v[74:77], v[126:129], v[198:201], v[74:77]
	s_nop 0
	s_nop 0
	v_mfma_f32_16x16x32_bf16 v[134:137], v[146:149], v[170:173], v[134:137]
	v_mfma_f32_16x16x32_bf16 v[130:133], v[154:157], v[170:173], v[130:133]
	v_mfma_f32_16x16x32_bf16 v[102:105], v[146:149], v[178:181], v[102:105]
	v_mfma_f32_16x16x32_bf16 v[98:101], v[154:157], v[178:181], v[98:101]
	v_mfma_f32_16x16x32_bf16 v[86:89], v[146:149], v[186:189], v[86:89]
	v_mfma_f32_16x16x32_bf16 v[82:85], v[154:157], v[186:189], v[82:85]
	v_mfma_f32_16x16x32_bf16 v[70:73], v[146:149], v[194:197], v[70:73]
	v_mfma_f32_16x16x32_bf16 v[66:69], v[154:157], v[194:197], v[66:69]
	v_mfma_f32_16x16x32_bf16 v[134:137], v[150:153], v[174:177], v[134:137]
	v_mfma_f32_16x16x32_bf16 v[130:133], v[158:161], v[174:177], v[130:133]
	v_mfma_f32_16x16x32_bf16 v[102:105], v[150:153], v[182:185], v[102:105]
	v_mfma_f32_16x16x32_bf16 v[98:101], v[158:161], v[182:185], v[98:101]
	v_mfma_f32_16x16x32_bf16 v[86:89], v[150:153], v[190:193], v[86:89]
	v_mfma_f32_16x16x32_bf16 v[82:85], v[158:161], v[190:193], v[82:85]
	v_mfma_f32_16x16x32_bf16 v[70:73], v[150:153], v[198:201], v[70:73]
	v_mfma_f32_16x16x32_bf16 v[66:69], v[158:161], v[198:201], v[66:69]
	s_nop 0
	s_barrier
	s_add_i32 s0, s62, s54
	v_lshl_add_u64 v[0:1], s[90:91], 0, v[162:163]
	s_mov_b32 m0, s0
	ds_read_b128 v[170:173], v216 offset:16384
	ds_read_b128 v[174:177], v216 offset:17408
	ds_read_b128 v[178:181], v216 offset:18432
	ds_read_b128 v[182:185], v216 offset:19456
	ds_read_b128 v[186:189], v216 offset:20480
	ds_read_b128 v[190:193], v216 offset:21504
	ds_read_b128 v[194:197], v216 offset:22528
	ds_read_b128 v[198:201], v216 offset:23552
	global_load_lds_dwordx4 v[0:1], off
	s_add_i32 m0, s0, 0x2000
	s_add_u32 s0, s90, 0x80000
	v_lshl_add_u64 v[202:203], s[90:91], 0, v[168:169]
	s_addc_u32 s1, s91, 0
	s_add_i32 s12, s63, s54
	global_load_lds_dwordx4 v[202:203], off
	v_lshl_add_u64 v[204:205], s[0:1], 0, v[162:163]
	s_mov_b32 m0, s12
	s_nop 0
	global_load_lds_dwordx4 v[204:205], off
	v_lshl_add_u64 v[204:205], s[0:1], 0, v[168:169]
	s_add_i32 m0, s12, 0x2000
	s_nop 0
	global_load_lds_dwordx4 v[204:205], off
	v_lshl_add_u64 v[204:205], s[88:89], 0, v[164:165]
	s_mov_b32 m0, s55
	s_nop 0
	global_load_lds_dwordx4 v[204:205], off
	v_lshl_add_u64 v[204:205], s[88:89], 0, v[166:167]
	s_mov_b32 m0, s56
	s_nop 0
	global_load_lds_dwordx4 v[204:205], off
	s_waitcnt vmcnt(8)
	s_waitcnt lgkmcnt(0)
	s_barrier
; #define G8_STAGE(bufoff, gbase, voff) do { _Pragma("unroll") for (int _i = 0; _i < 2; ++_i) \
;         __builtin_amdgcn_global_load_lds((const unsigned*)((const char*)(gbase) + (voff)[_i]), (LAS unsigned*)(lds + (bufoff) + ldsw + _i * 8192), 16, 0, 0); } while (0)
; #define G8_LDA(dst, b, h) do { _Pragma("unroll") for (int m = 0; m < 4; ++m) _Pragma("unroll") for (int k = 0; k < 2; ++k) dst[m][k] = *(const LAS bf16x8*)(lds + G8_SA(b, h) + aoff + m * 2048 + k * 1024); } while (0)
; #define G8_LDB(dst, b, h) do { _Pragma("unroll") for (int n = 0; n < 2; ++n) _Pragma("unroll") for (int k = 0; k < 2; ++k) dst[n][k] = *(const LAS bf16x8*)(lds + G8_SB(b, h) + boff + n * 2048 + k * 1024); } while (0)
; #define G8_MMA(ai, bj, At, Bt) do { __builtin_amdgcn_s_setprio(1); _Pragma("unroll") for (int m = 0; m < 4; ++m) _Pragma("unroll") for (int n = 0; n < 2; ++n) _Pragma("unroll") for (int k = 0; k < 2; ++k) \
;         acc[ai][bj][m][n] = __builtin_amdgcn_mfma_f32_16x16x32_bf16(Bt[n][k], At[m][k], acc[ai][bj][m][n], 0, 0, 0); __builtin_amdgcn_s_setprio(0); } while (0)
; #define G8_WAIT_V(n) asm volatile("s_waitcnt vmcnt(" #n ")" ::: "memory")
; #define G8_WAIT_L(n) asm volatile("s_waitcnt lgkmcnt(" #n ")" ::: "memory")
; #define G8_BAR __builtin_amdgcn_s_barrier()
; #define G8_SCHED __builtin_amdgcn_sched_barrier(0)
; template <class Epi, class Sched>
; DEV void gemm_phase(LAS char* lds, const Sched& S, const Epi& E) {
;     ...
;             G8_WAIT_V(8); G8_WAIT_L(0); G8_BAR; G8_MMA(1, 0, At, B0); G8_MMA(1, 1, At, B1); G8_BAR; G8_SCHED;
;             G8_LDB(B0, 1, 0); G8_LDB(B1, 1, 1); G8_SCHED; G8_LDA(At, 1, 0); G8_STAGE(G8_SA(0, 1), a2 + hstepA, voffA);
;             G8_WAIT_V(8); G8_WAIT_L(0); G8_BAR; G8_MMA(0, 0, At, B0); G8_MMA(0, 1, At, B1); G8_BAR; G8_SCHED;
	s_nop 0
	s_waitcnt lgkmcnt(0)
	v_mfma_f32_16x16x32_bf16 v[62:65], v[106:109], v[170:173], v[62:65]
	v_mfma_f32_16x16x32_bf16 v[58:61], v[118:121], v[170:173], v[58:61]
	v_mfma_f32_16x16x32_bf16 v[46:49], v[106:109], v[178:181], v[46:49]
	v_mfma_f32_16x16x32_bf16 v[42:45], v[118:121], v[178:181], v[42:45]
	v_mfma_f32_16x16x32_bf16 v[30:33], v[106:109], v[186:189], v[30:33]
	v_mfma_f32_16x16x32_bf16 v[26:29], v[118:121], v[186:189], v[26:29]
	v_mfma_f32_16x16x32_bf16 v[14:17], v[106:109], v[194:197], v[14:17]
	v_mfma_f32_16x16x32_bf16 v[10:13], v[118:121], v[194:197], v[10:13]
	v_mfma_f32_16x16x32_bf16 v[62:65], v[110:113], v[174:177], v[62:65]
	v_mfma_f32_16x16x32_bf16 v[58:61], v[126:129], v[174:177], v[58:61]
	v_mfma_f32_16x16x32_bf16 v[46:49], v[110:113], v[182:185], v[46:49]
	v_mfma_f32_16x16x32_bf16 v[42:45], v[126:129], v[182:185], v[42:45]
	v_mfma_f32_16x16x32_bf16 v[30:33], v[110:113], v[190:193], v[30:33]
	v_mfma_f32_16x16x32_bf16 v[26:29], v[126:129], v[190:193], v[26:29]
	v_mfma_f32_16x16x32_bf16 v[14:17], v[110:113], v[198:201], v[14:17]
	v_mfma_f32_16x16x32_bf16 v[10:13], v[126:129], v[198:201], v[10:13]
	s_nop 0
	s_nop 0
	v_mfma_f32_16x16x32_bf16 v[54:57], v[146:149], v[170:173], v[54:57]
	v_mfma_f32_16x16x32_bf16 v[50:53], v[154:157], v[170:173], v[50:53]
	v_mfma_f32_16x16x32_bf16 v[38:41], v[146:149], v[178:181], v[38:41]
	v_mfma_f32_16x16x32_bf16 v[34:37], v[154:157], v[178:181], v[34:37]
	v_mfma_f32_16x16x32_bf16 v[22:25], v[146:149], v[186:189], v[22:25]
	v_mfma_f32_16x16x32_bf16 v[18:21], v[154:157], v[186:189], v[18:21]
	v_mfma_f32_16x16x32_bf16 v[6:9], v[146:149], v[194:197], v[6:9]
	v_mfma_f32_16x16x32_bf16 v[2:5], v[154:157], v[194:197], v[2:5]
	v_mfma_f32_16x16x32_bf16 v[54:57], v[150:153], v[174:177], v[54:57]
	v_mfma_f32_16x16x32_bf16 v[50:53], v[158:161], v[174:177], v[50:53]
	v_mfma_f32_16x16x32_bf16 v[38:41], v[150:153], v[182:185], v[38:41]
	v_mfma_f32_16x16x32_bf16 v[34:37], v[158:161], v[182:185], v[34:37]
	v_mfma_f32_16x16x32_bf16 v[22:25], v[150:153], v[190:193], v[22:25]
	v_mfma_f32_16x16x32_bf16 v[18:21], v[158:161], v[190:193], v[18:21]
	v_mfma_f32_16x16x32_bf16 v[6:9], v[150:153], v[198:201], v[6:9]
	v_mfma_f32_16x16x32_bf16 v[2:5], v[158:161], v[198:201], v[2:5]
	s_nop 0
	s_barrier
	v_add_u32_e32 v126, s50, v212
	v_add_u32_e32 v158, s51, v212
	ds_read_b128 v[106:109], v126
	ds_read_b128 v[110:113], v126 offset:1024
	ds_read_b128 v[118:121], v126 offset:2048
	ds_read_b128 v[126:129], v126 offset:3072
	ds_read_b128 v[146:149], v158
	ds_read_b128 v[150:153], v158 offset:1024
	ds_read_b128 v[154:157], v158 offset:2048
	ds_read_b128 v[158:161], v158 offset:3072
	s_add_u32 s0, s88, 0x40000
	s_addc_u32 s1, s89, 0
	s_mov_b32 m0, s57
	v_lshl_add_u64 v[204:205], s[0:1], 0, v[164:165]
	ds_read_b128 v[170:173], v216 offset:32768
	ds_read_b128 v[174:177], v216 offset:33792
	ds_read_b128 v[178:181], v216 offset:34816
	ds_read_b128 v[182:185], v216 offset:35840
	ds_read_b128 v[186:189], v216 offset:36864
	ds_read_b128 v[190:193], v216 offset:37888
	ds_read_b128 v[194:197], v216 offset:38912
	ds_read_b128 v[198:201], v216 offset:39936
	global_load_lds_dwordx4 v[204:205], off
	v_lshl_add_u64 v[204:205], s[0:1], 0, v[166:167]
	s_mov_b32 m0, s60
	s_nop 0
	global_load_lds_dwordx4 v[204:205], off
	s_waitcnt vmcnt(8)
	s_waitcnt lgkmcnt(0)
	s_barrier
	s_nop 0
	s_waitcnt lgkmcnt(0)
	v_mfma_f32_16x16x32_bf16 v[142:145], v[106:109], v[170:173], v[142:145]
	v_mfma_f32_16x16x32_bf16 v[138:141], v[118:121], v[170:173], v[138:141]
	v_mfma_f32_16x16x32_bf16 v[122:125], v[106:109], v[178:181], v[122:125]
	v_mfma_f32_16x16x32_bf16 v[114:117], v[118:121], v[178:181], v[114:117]
	v_mfma_f32_16x16x32_bf16 v[94:97], v[106:109], v[186:189], v[94:97]
	v_mfma_f32_16x16x32_bf16 v[90:93], v[118:121], v[186:189], v[90:93]
	v_mfma_f32_16x16x32_bf16 v[78:81], v[106:109], v[194:197], v[78:81]
	v_mfma_f32_16x16x32_bf16 v[74:77], v[118:121], v[194:197], v[74:77]
	v_mfma_f32_16x16x32_bf16 v[142:145], v[110:113], v[174:177], v[142:145]
	v_mfma_f32_16x16x32_bf16 v[138:141], v[126:129], v[174:177], v[138:141]
	v_mfma_f32_16x16x32_bf16 v[122:125], v[110:113], v[182:185], v[122:125]
	v_mfma_f32_16x16x32_bf16 v[114:117], v[126:129], v[182:185], v[114:117]
	v_mfma_f32_16x16x32_bf16 v[94:97], v[110:113], v[190:193], v[94:97]
	v_mfma_f32_16x16x32_bf16 v[90:93], v[126:129], v[190:193], v[90:93]
	v_mfma_f32_16x16x32_bf16 v[78:81], v[110:113], v[198:201], v[78:81]
	v_mfma_f32_16x16x32_bf16 v[74:77], v[126:129], v[198:201], v[74:77]
	s_nop 0
	s_nop 0
	v_mfma_f32_16x16x32_bf16 v[134:137], v[146:149], v[170:173], v[134:137]
	v_mfma_f32_16x16x32_bf16 v[130:133], v[154:157], v[170:173], v[130:133]
	v_mfma_f32_16x16x32_bf16 v[102:105], v[146:149], v[178:181], v[102:105]
	v_mfma_f32_16x16x32_bf16 v[98:101], v[154:157], v[178:181], v[98:101]
	v_mfma_f32_16x16x32_bf16 v[86:89], v[146:149], v[186:189], v[86:89]
	v_mfma_f32_16x16x32_bf16 v[82:85], v[154:157], v[186:189], v[82:85]
	v_mfma_f32_16x16x32_bf16 v[70:73], v[146:149], v[194:197], v[70:73]
	v_mfma_f32_16x16x32_bf16 v[66:69], v[154:157], v[194:197], v[66:69]
	v_mfma_f32_16x16x32_bf16 v[134:137], v[150:153], v[174:177], v[134:137]
	v_mfma_f32_16x16x32_bf16 v[130:133], v[158:161], v[174:177], v[130:133]
	v_mfma_f32_16x16x32_bf16 v[102:105], v[150:153], v[182:185], v[102:105]
	v_mfma_f32_16x16x32_bf16 v[98:101], v[158:161], v[182:185], v[98:101]
	v_mfma_f32_16x16x32_bf16 v[86:89], v[150:153], v[190:193], v[86:89]
	v_mfma_f32_16x16x32_bf16 v[82:85], v[158:161], v[190:193], v[82:85]
	v_mfma_f32_16x16x32_bf16 v[70:73], v[150:153], v[198:201], v[70:73]
	v_mfma_f32_16x16x32_bf16 v[66:69], v[158:161], v[198:201], v[66:69]
	s_nop 0
	s_barrier
; #define G8_STAGE(bufoff, gbase, voff) do { _Pragma("unroll") for (int _i = 0; _i < 2; ++_i) \
;         __builtin_amdgcn_global_load_lds((const unsigned*)((const char*)(gbase) + (voff)[_i]), (LAS unsigned*)(lds + (bufoff) + ldsw + _i * 8192), 16, 0, 0); } while (0)
; #define G8_LDA(dst, b, h) do { _Pragma("unroll") for (int m = 0; m < 4; ++m) _Pragma("unroll") for (int k = 0; k < 2; ++k) dst[m][k] = *(const LAS bf16x8*)(lds + G8_SA(b, h) + aoff + m * 2048 + k * 1024); } while (0)
; #define G8_MMA(ai, bj, At, Bt) do { __builtin_amdgcn_s_setprio(1); _Pragma("unroll") for (int m = 0; m < 4; ++m) _Pragma("unroll") for (int n = 0; n < 2; ++n) _Pragma("unroll") for (int k = 0; k < 2; ++k) \
;         acc[ai][bj][m][n] = __builtin_amdgcn_mfma_f32_16x16x32_bf16(Bt[n][k], At[m][k], acc[ai][bj][m][n], 0, 0, 0); __builtin_amdgcn_s_setprio(0); } while (0)
; #define G8_WAIT_V(n) asm volatile("s_waitcnt vmcnt(" #n ")" ::: "memory")
; #define G8_WAIT_L(n) asm volatile("s_waitcnt lgkmcnt(" #n ")" ::: "memory")
; #define G8_BAR __builtin_amdgcn_s_barrier()
; #define G8_SCHED __builtin_amdgcn_sched_barrier(0)
; template <class Epi, class Sched>
; DEV void gemm_phase(LAS char* lds, const Sched& S, const Epi& E) {
;     ...
;             G8_LDA(At, 1, 1); G8_STAGE(G8_SB(1, 0), b3, voffB); G8_STAGE(G8_SB(1, 1), b3 + hstepB, voffB); G8_STAGE(G8_SA(1, 0), a3, voffA);
;             G8_WAIT_V(8); G8_WAIT_L(0); G8_BAR; G8_MMA(1, 0, At, B0); G8_MMA(1, 1, At, B1); G8_BAR; G8_SCHED;
;         }
	s_add_i32 s0, s50, s54
	v_lshl_add_u64 v[0:1], v[0:1], 0, s[22:23]
	s_mov_b32 m0, s0
	ds_read_b128 v[170:173], v216 offset:49152
	ds_read_b128 v[174:177], v216 offset:50176
	ds_read_b128 v[178:181], v216 offset:51200
	ds_read_b128 v[182:185], v216 offset:52224
	ds_read_b128 v[186:189], v216 offset:53248
	ds_read_b128 v[190:193], v216 offset:54272
	ds_read_b128 v[194:197], v216 offset:55296
	ds_read_b128 v[198:201], v216 offset:56320
	global_load_lds_dwordx4 v[0:1], off
	s_add_i32 m0, s0, 0x2000
	s_add_u32 s0, s90, 0x80080
	v_lshl_add_u64 v[0:1], v[202:203], 0, s[22:23]
	s_addc_u32 s1, s91, 0
	s_add_i32 s12, s51, s54
	global_load_lds_dwordx4 v[0:1], off
	v_lshl_add_u64 v[0:1], s[0:1], 0, v[162:163]
	s_mov_b32 m0, s12
	s_nop 0
	global_load_lds_dwordx4 v[0:1], off
	v_lshl_add_u64 v[0:1], s[0:1], 0, v[168:169]
	s_add_i32 m0, s12, 0x2000
	s_nop 0
	global_load_lds_dwordx4 v[0:1], off
	v_lshl_add_u64 v[0:1], s[86:87], 0, v[164:165]
	s_mov_b32 m0, s75
	s_nop 0
	global_load_lds_dwordx4 v[0:1], off
	v_lshl_add_u64 v[0:1], s[86:87], 0, v[166:167]
	s_mov_b32 m0, s76
	s_nop 0
	global_load_lds_dwordx4 v[0:1], off
	s_waitcnt vmcnt(8)
	s_waitcnt lgkmcnt(0)
	s_barrier
	s_nop 0
	s_waitcnt lgkmcnt(0)
	v_mfma_f32_16x16x32_bf16 v[62:65], v[106:109], v[170:173], v[62:65]
	v_mfma_f32_16x16x32_bf16 v[58:61], v[118:121], v[170:173], v[58:61]
	v_mfma_f32_16x16x32_bf16 v[46:49], v[106:109], v[178:181], v[46:49]
	v_mfma_f32_16x16x32_bf16 v[42:45], v[118:121], v[178:181], v[42:45]
	v_mfma_f32_16x16x32_bf16 v[30:33], v[106:109], v[186:189], v[30:33]
	v_mfma_f32_16x16x32_bf16 v[26:29], v[118:121], v[186:189], v[26:29]
	v_mfma_f32_16x16x32_bf16 v[14:17], v[106:109], v[194:197], v[14:17]
	v_mfma_f32_16x16x32_bf16 v[10:13], v[118:121], v[194:197], v[10:13]
	v_mfma_f32_16x16x32_bf16 v[62:65], v[110:113], v[174:177], v[62:65]
	v_mfma_f32_16x16x32_bf16 v[58:61], v[126:129], v[174:177], v[58:61]
	v_mfma_f32_16x16x32_bf16 v[46:49], v[110:113], v[182:185], v[46:49]
	v_mfma_f32_16x16x32_bf16 v[42:45], v[126:129], v[182:185], v[42:45]
	v_mfma_f32_16x16x32_bf16 v[30:33], v[110:113], v[190:193], v[30:33]
	v_mfma_f32_16x16x32_bf16 v[26:29], v[126:129], v[190:193], v[26:29]
	v_mfma_f32_16x16x32_bf16 v[14:17], v[110:113], v[198:201], v[14:17]
	v_mfma_f32_16x16x32_bf16 v[10:13], v[126:129], v[198:201], v[10:13]
	s_nop 0
	s_nop 0
	v_mfma_f32_16x16x32_bf16 v[54:57], v[146:149], v[170:173], v[54:57]
	v_mfma_f32_16x16x32_bf16 v[50:53], v[154:157], v[170:173], v[50:53]
	v_mfma_f32_16x16x32_bf16 v[38:41], v[146:149], v[178:181], v[38:41]
	v_mfma_f32_16x16x32_bf16 v[34:37], v[154:157], v[178:181], v[34:37]
	v_mfma_f32_16x16x32_bf16 v[22:25], v[146:149], v[186:189], v[22:25]
	v_mfma_f32_16x16x32_bf16 v[18:21], v[154:157], v[186:189], v[18:21]
	v_mfma_f32_16x16x32_bf16 v[6:9], v[146:149], v[194:197], v[6:9]
	v_mfma_f32_16x16x32_bf16 v[2:5], v[154:157], v[194:197], v[2:5]
	v_mfma_f32_16x16x32_bf16 v[54:57], v[150:153], v[174:177], v[54:57]
	v_mfma_f32_16x16x32_bf16 v[50:53], v[158:161], v[174:177], v[50:53]
	v_mfma_f32_16x16x32_bf16 v[38:41], v[150:153], v[182:185], v[38:41]
	v_mfma_f32_16x16x32_bf16 v[34:37], v[158:161], v[182:185], v[34:37]
	v_mfma_f32_16x16x32_bf16 v[22:25], v[150:153], v[190:193], v[22:25]
	v_mfma_f32_16x16x32_bf16 v[18:21], v[158:161], v[190:193], v[18:21]
	v_mfma_f32_16x16x32_bf16 v[6:9], v[150:153], v[198:201], v[6:9]
	v_mfma_f32_16x16x32_bf16 v[2:5], v[158:161], v[198:201], v[2:5]
	s_nop 0
	s_barrier
	s_add_i32 s0, s52, 2
	s_add_u32 s84, s84, 0x100
	s_addc_u32 s85, s85, 0
	s_add_u32 s27, s27, 0x100
	s_addc_u32 s41, s41, 0
	s_cmp_gt_u32 s52, 29
	s_mov_b32 s52, s0
	s_cbranch_scc1 .LBB0_860

; #define G8_STAGE(bufoff, gbase, voff) do { _Pragma("unroll") for (int _i = 0; _i < 2; ++_i) \
;         __builtin_amdgcn_global_load_lds((const unsigned*)((const char*)(gbase) + (voff)[_i]), (LAS unsigned*)(lds + (bufoff) + ldsw + _i * 8192), 16, 0, 0); } while (0)
; #define G8_LDA(dst, b, h) do { _Pragma("unroll") for (int m = 0; m < 4; ++m) _Pragma("unroll") for (int k = 0; k < 2; ++k) dst[m][k] = *(const LAS bf16x8*)(lds + G8_SA(b, h) + aoff + m * 2048 + k * 1024); } while (0)
; #define G8_LDB(dst, b, h) do { _Pragma("unroll") for (int n = 0; n < 2; ++n) _Pragma("unroll") for (int k = 0; k < 2; ++k) dst[n][k] = *(const LAS bf16x8*)(lds + G8_SB(b, h) + boff + n * 2048 + k * 1024); } while (0)
; #define G8_MMA(ai, bj, At, Bt) do { __builtin_amdgcn_s_setprio(1); _Pragma("unroll") for (int m = 0; m < 4; ++m) _Pragma("unroll") for (int n = 0; n < 2; ++n) _Pragma("unroll") for (int k = 0; k < 2; ++k) \
;         acc[ai][bj][m][n] = __builtin_amdgcn_mfma_f32_16x16x32_bf16(Bt[n][k], At[m][k], acc[ai][bj][m][n], 0, 0, 0); __builtin_amdgcn_s_setprio(0); } while (0)
; #define G8_WAIT_V(n) asm volatile("s_waitcnt vmcnt(" #n ")" ::: "memory")
; #define G8_WAIT_L(n) asm volatile("s_waitcnt lgkmcnt(" #n ")" ::: "memory")
; #define G8_BAR __builtin_amdgcn_s_barrier()
; #define G8_SCHED __builtin_amdgcn_sched_barrier(0)
; template <class Epi, class Sched>
; DEV void gemm_phase(LAS char* lds, const Sched& S, const Epi& E) {
;     ...
;         for (int t = 0; t < nt; t += 2) {
;             const bool last = (t == nt - 2);
;             const char* a1 = G8_AK(t + 1);
;             const char* a2 = last ? nA : G8_AK(t + 2); const char* b2 = last ? nB : cB + (size_t)(t + 2) * kstep;
;             const char* a3 = last ? nA + kstepA : G8_AK(t + 3); const char* b3 = b2 + kstep;
;             G8_LDB(B0, 0, 0); G8_LDB(B1, 0, 1); G8_SCHED; G8_LDA(At, 0, 0); G8_STAGE(G8_SA(1, 1), a1 + hstepA, voffA);
;             G8_WAIT_V(8); G8_WAIT_L(0); G8_BAR; G8_MMA(0, 0, At, B0); G8_MMA(0, 1, At, B1); G8_BAR; G8_SCHED;
;             G8_LDA(At, 0, 1); G8_STAGE(G8_SB(0, 0), b2, voffB); G8_STAGE(G8_SB(0, 1), b2 + hstepB, voffB); G8_STAGE(G8_SA(0, 0), a2, voffA);
.LBB0_1066:
	ds_read_b128 v[150:153], v165
	ds_read_b128 v[154:157], v165 offset:1024
	ds_read_b128 v[158:161], v165 offset:2048
	ds_read_b128 v[168:171], v165 offset:3072
	ds_read_b128 v[172:175], v166
	ds_read_b128 v[176:179], v166 offset:1024
	ds_read_b128 v[180:183], v166 offset:2048
	ds_read_b128 v[184:187], v166 offset:3072
	s_add_u32 s26, s22, s24
	s_addc_u32 s27, s23, s25
	s_add_u32 s30, s26, 0x100
	s_addc_u32 s31, s27, 0
	s_add_u32 s28, s47, s24
	s_addc_u32 s29, s52, s25
	s_add_u32 s26, s26, 0x180
	s_addc_u32 s27, s27, 0
	s_cmpk_eq_i32 s24, 0x700
	s_cselect_b32 s27, s46, s27
	s_cselect_b32 s26, s15, s26
	s_cselect_b32 s29, s19, s29
	s_cselect_b32 s28, s18, s28
	s_cselect_b32 s31, s17, s31
	s_cselect_b32 s30, s16, s30
	v_lshl_add_u64 v[0:1], v[148:149], 0, s[24:25]
	s_add_i32 m0, s38, 0xc000
	ds_read_b128 v[188:191], v167
	ds_read_b128 v[192:195], v167 offset:1024
	ds_read_b128 v[196:199], v167 offset:2048
	ds_read_b128 v[200:203], v167 offset:3072
	ds_read_b128 v[204:207], v167 offset:4096
	ds_read_b128 v[208:211], v167 offset:5120
	ds_read_b128 v[212:215], v167 offset:6144
	ds_read_b128 v[216:219], v167 offset:7168
	global_load_lds_dwordx4 v[0:1], off
	v_lshl_add_u64 v[0:1], v[146:147], 0, s[24:25]
	s_add_i32 m0, s38, 0xe000
	s_nop 0
	global_load_lds_dwordx4 v[0:1], off
	s_waitcnt vmcnt(8)
	s_waitcnt lgkmcnt(0)
	s_barrier
	s_nop 0
	s_waitcnt lgkmcnt(0)
	v_mfma_f32_16x16x32_bf16 v[126:129], v[150:153], v[188:191], v[126:129]
	v_mfma_f32_16x16x32_bf16 v[122:125], v[158:161], v[188:191], v[122:125]
	v_mfma_f32_16x16x32_bf16 v[118:121], v[150:153], v[196:199], v[118:121]
	v_mfma_f32_16x16x32_bf16 v[114:117], v[158:161], v[196:199], v[114:117]
	v_mfma_f32_16x16x32_bf16 v[110:113], v[150:153], v[204:207], v[110:113]
	v_mfma_f32_16x16x32_bf16 v[102:105], v[158:161], v[204:207], v[102:105]
	v_mfma_f32_16x16x32_bf16 v[94:97], v[150:153], v[212:215], v[94:97]
	v_mfma_f32_16x16x32_bf16 v[86:89], v[158:161], v[212:215], v[86:89]
	v_mfma_f32_16x16x32_bf16 v[126:129], v[154:157], v[192:195], v[126:129]
	v_mfma_f32_16x16x32_bf16 v[122:125], v[168:171], v[192:195], v[122:125]
	v_mfma_f32_16x16x32_bf16 v[118:121], v[154:157], v[200:203], v[118:121]
	v_mfma_f32_16x16x32_bf16 v[114:117], v[168:171], v[200:203], v[114:117]
	v_mfma_f32_16x16x32_bf16 v[110:113], v[154:157], v[208:211], v[110:113]
	v_mfma_f32_16x16x32_bf16 v[102:105], v[168:171], v[208:211], v[102:105]
	v_mfma_f32_16x16x32_bf16 v[94:97], v[154:157], v[216:219], v[94:97]
	v_mfma_f32_16x16x32_bf16 v[86:89], v[168:171], v[216:219], v[86:89]
	s_nop 0
	s_nop 0
	v_mfma_f32_16x16x32_bf16 v[106:109], v[172:175], v[188:191], v[106:109]
	v_mfma_f32_16x16x32_bf16 v[98:101], v[180:183], v[188:191], v[98:101]
	v_mfma_f32_16x16x32_bf16 v[90:93], v[172:175], v[196:199], v[90:93]
	v_mfma_f32_16x16x32_bf16 v[82:85], v[180:183], v[196:199], v[82:85]
	v_mfma_f32_16x16x32_bf16 v[78:81], v[172:175], v[204:207], v[78:81]
	v_mfma_f32_16x16x32_bf16 v[74:77], v[180:183], v[204:207], v[74:77]
	v_mfma_f32_16x16x32_bf16 v[70:73], v[172:175], v[212:215], v[70:73]
	v_mfma_f32_16x16x32_bf16 v[66:69], v[180:183], v[212:215], v[66:69]
	v_mfma_f32_16x16x32_bf16 v[106:109], v[176:179], v[192:195], v[106:109]
	v_mfma_f32_16x16x32_bf16 v[98:101], v[184:187], v[192:195], v[98:101]
	v_mfma_f32_16x16x32_bf16 v[90:93], v[176:179], v[200:203], v[90:93]
	v_mfma_f32_16x16x32_bf16 v[82:85], v[184:187], v[200:203], v[82:85]
	v_mfma_f32_16x16x32_bf16 v[78:81], v[176:179], v[208:211], v[78:81]
	v_mfma_f32_16x16x32_bf16 v[74:77], v[184:187], v[208:211], v[74:77]
	v_mfma_f32_16x16x32_bf16 v[70:73], v[176:179], v[216:219], v[70:73]
	v_mfma_f32_16x16x32_bf16 v[66:69], v[184:187], v[216:219], v[66:69]
	s_nop 0
	s_barrier
	s_add_i32 s55, s62, s37
	v_lshl_add_u64 v[0:1], s[28:29], 0, v[132:133]
	s_mov_b32 m0, s55
	ds_read_b128 v[188:191], v167 offset:16384
	ds_read_b128 v[192:195], v167 offset:17408
	ds_read_b128 v[196:199], v167 offset:18432
	ds_read_b128 v[200:203], v167 offset:19456
	ds_read_b128 v[204:207], v167 offset:20480
	ds_read_b128 v[208:211], v167 offset:21504
	ds_read_b128 v[212:215], v167 offset:22528
	ds_read_b128 v[216:219], v167 offset:23552
	global_load_lds_dwordx4 v[0:1], off
	s_add_i32 m0, s55, 0x2000
	s_add_u32 s56, s28, 0x40000
	v_lshl_add_u64 v[220:221], s[28:29], 0, v[136:137]
	s_addc_u32 s57, s29, 0
	s_add_i32 s55, s63, s37
	global_load_lds_dwordx4 v[220:221], off
	v_lshl_add_u64 v[222:223], s[56:57], 0, v[132:133]
	s_mov_b32 m0, s55
	s_nop 0
	global_load_lds_dwordx4 v[222:223], off
	v_lshl_add_u64 v[222:223], s[56:57], 0, v[136:137]
	s_add_i32 m0, s55, 0x2000
	s_nop 0
	global_load_lds_dwordx4 v[222:223], off
	v_lshl_add_u64 v[222:223], s[30:31], 0, v[130:131]
	s_mov_b32 m0, s38
	s_nop 0
	global_load_lds_dwordx4 v[222:223], off
	v_lshl_add_u64 v[222:223], s[30:31], 0, v[134:135]
	s_mov_b32 m0, s39
	s_nop 0
	global_load_lds_dwordx4 v[222:223], off
	s_waitcnt vmcnt(8)
	s_waitcnt lgkmcnt(0)
	s_barrier
; #define G8_STAGE(bufoff, gbase, voff) do { _Pragma("unroll") for (int _i = 0; _i < 2; ++_i) \
;         __builtin_amdgcn_global_load_lds((const unsigned*)((const char*)(gbase) + (voff)[_i]), (LAS unsigned*)(lds + (bufoff) + ldsw + _i * 8192), 16, 0, 0); } while (0)
; #define G8_LDA(dst, b, h) do { _Pragma("unroll") for (int m = 0; m < 4; ++m) _Pragma("unroll") for (int k = 0; k < 2; ++k) dst[m][k] = *(const LAS bf16x8*)(lds + G8_SA(b, h) + aoff + m * 2048 + k * 1024); } while (0)
; #define G8_LDB(dst, b, h) do { _Pragma("unroll") for (int n = 0; n < 2; ++n) _Pragma("unroll") for (int k = 0; k < 2; ++k) dst[n][k] = *(const LAS bf16x8*)(lds + G8_SB(b, h) + boff + n * 2048 + k * 1024); } while (0)
; #define G8_MMA(ai, bj, At, Bt) do { __builtin_amdgcn_s_setprio(1); _Pragma("unroll") for (int m = 0; m < 4; ++m) _Pragma("unroll") for (int n = 0; n < 2; ++n) _Pragma("unroll") for (int k = 0; k < 2; ++k) \
;         acc[ai][bj][m][n] = __builtin_amdgcn_mfma_f32_16x16x32_bf16(Bt[n][k], At[m][k], acc[ai][bj][m][n], 0, 0, 0); __builtin_amdgcn_s_setprio(0); } while (0)
; #define G8_WAIT_V(n) asm volatile("s_waitcnt vmcnt(" #n ")" ::: "memory")
; #define G8_WAIT_L(n) asm volatile("s_waitcnt lgkmcnt(" #n ")" ::: "memory")
; #define G8_BAR __builtin_amdgcn_s_barrier()
; #define G8_SCHED __builtin_amdgcn_sched_barrier(0)
; template <class Epi, class Sched>
; DEV void gemm_phase(LAS char* lds, const Sched& S, const Epi& E) {
;     ...
;             G8_WAIT_V(8); G8_WAIT_L(0); G8_BAR; G8_MMA(1, 0, At, B0); G8_MMA(1, 1, At, B1); G8_BAR; G8_SCHED;
;             G8_LDB(B0, 1, 0); G8_LDB(B1, 1, 1); G8_SCHED; G8_LDA(At, 1, 0); G8_STAGE(G8_SA(0, 1), a2 + hstepA, voffA);
;             G8_WAIT_V(8); G8_WAIT_L(0); G8_BAR; G8_MMA(0, 0, At, B0); G8_MMA(0, 1, At, B1); G8_BAR; G8_SCHED;
	s_nop 0
	s_waitcnt lgkmcnt(0)
	v_mfma_f32_16x16x32_bf16 v[62:65], v[150:153], v[188:191], v[62:65]
	v_mfma_f32_16x16x32_bf16 v[58:61], v[158:161], v[188:191], v[58:61]
	v_mfma_f32_16x16x32_bf16 v[54:57], v[150:153], v[196:199], v[54:57]
	v_mfma_f32_16x16x32_bf16 v[50:53], v[158:161], v[196:199], v[50:53]
	v_mfma_f32_16x16x32_bf16 v[46:49], v[150:153], v[204:207], v[46:49]
	v_mfma_f32_16x16x32_bf16 v[38:41], v[158:161], v[204:207], v[38:41]
	v_mfma_f32_16x16x32_bf16 v[30:33], v[150:153], v[212:215], v[30:33]
	v_mfma_f32_16x16x32_bf16 v[22:25], v[158:161], v[212:215], v[22:25]
	v_mfma_f32_16x16x32_bf16 v[62:65], v[154:157], v[192:195], v[62:65]
	v_mfma_f32_16x16x32_bf16 v[58:61], v[168:171], v[192:195], v[58:61]
	v_mfma_f32_16x16x32_bf16 v[54:57], v[154:157], v[200:203], v[54:57]
	v_mfma_f32_16x16x32_bf16 v[50:53], v[168:171], v[200:203], v[50:53]
	v_mfma_f32_16x16x32_bf16 v[46:49], v[154:157], v[208:211], v[46:49]
	v_mfma_f32_16x16x32_bf16 v[38:41], v[168:171], v[208:211], v[38:41]
	v_mfma_f32_16x16x32_bf16 v[30:33], v[154:157], v[216:219], v[30:33]
	v_mfma_f32_16x16x32_bf16 v[22:25], v[168:171], v[216:219], v[22:25]
	s_nop 0
	s_nop 0
	v_mfma_f32_16x16x32_bf16 v[42:45], v[172:175], v[188:191], v[42:45]
	v_mfma_f32_16x16x32_bf16 v[34:37], v[180:183], v[188:191], v[34:37]
	v_mfma_f32_16x16x32_bf16 v[26:29], v[172:175], v[196:199], v[26:29]
	v_mfma_f32_16x16x32_bf16 v[18:21], v[180:183], v[196:199], v[18:21]
	v_mfma_f32_16x16x32_bf16 v[14:17], v[172:175], v[204:207], v[14:17]
	v_mfma_f32_16x16x32_bf16 v[10:13], v[180:183], v[204:207], v[10:13]
	v_mfma_f32_16x16x32_bf16 v[6:9], v[172:175], v[212:215], v[6:9]
	v_mfma_f32_16x16x32_bf16 v[2:5], v[180:183], v[212:215], v[2:5]
	v_mfma_f32_16x16x32_bf16 v[42:45], v[176:179], v[192:195], v[42:45]
	v_mfma_f32_16x16x32_bf16 v[34:37], v[184:187], v[192:195], v[34:37]
	v_mfma_f32_16x16x32_bf16 v[26:29], v[176:179], v[200:203], v[26:29]
	v_mfma_f32_16x16x32_bf16 v[18:21], v[184:187], v[200:203], v[18:21]
	v_mfma_f32_16x16x32_bf16 v[14:17], v[176:179], v[208:211], v[14:17]
	v_mfma_f32_16x16x32_bf16 v[10:13], v[184:187], v[208:211], v[10:13]
	v_mfma_f32_16x16x32_bf16 v[6:9], v[176:179], v[216:219], v[6:9]
	v_mfma_f32_16x16x32_bf16 v[2:5], v[184:187], v[216:219], v[2:5]
	s_nop 0
	s_barrier
	v_add_u32_e32 v138, s50, v163
	ds_read_b128 v[150:153], v138
	ds_read_b128 v[154:157], v138 offset:1024
	ds_read_b128 v[158:161], v138 offset:2048
	ds_read_b128 v[168:171], v138 offset:3072
	v_add_u32_e32 v138, s51, v163
	ds_read_b128 v[172:175], v138
	ds_read_b128 v[176:179], v138 offset:1024
	ds_read_b128 v[180:183], v138 offset:2048
	ds_read_b128 v[184:187], v138 offset:3072
	s_add_u32 s30, s30, 0x40000
	s_addc_u32 s31, s31, 0
	s_mov_b32 m0, s40
	v_lshl_add_u64 v[222:223], s[30:31], 0, v[130:131]
	ds_read_b128 v[188:191], v167 offset:32768
	ds_read_b128 v[192:195], v167 offset:33792
	ds_read_b128 v[196:199], v167 offset:34816
	ds_read_b128 v[200:203], v167 offset:35840
	ds_read_b128 v[204:207], v167 offset:36864
	ds_read_b128 v[208:211], v167 offset:37888
	ds_read_b128 v[212:215], v167 offset:38912
	ds_read_b128 v[216:219], v167 offset:39936
	global_load_lds_dwordx4 v[222:223], off
	v_lshl_add_u64 v[222:223], s[30:31], 0, v[134:135]
	s_mov_b32 m0, s41
	s_nop 0
	global_load_lds_dwordx4 v[222:223], off
	s_waitcnt vmcnt(8)
	s_waitcnt lgkmcnt(0)
	s_barrier
	s_nop 0
	s_waitcnt lgkmcnt(0)
	v_mfma_f32_16x16x32_bf16 v[126:129], v[150:153], v[188:191], v[126:129]
	v_mfma_f32_16x16x32_bf16 v[122:125], v[158:161], v[188:191], v[122:125]
	v_mfma_f32_16x16x32_bf16 v[118:121], v[150:153], v[196:199], v[118:121]
	v_mfma_f32_16x16x32_bf16 v[114:117], v[158:161], v[196:199], v[114:117]
	v_mfma_f32_16x16x32_bf16 v[110:113], v[150:153], v[204:207], v[110:113]
	v_mfma_f32_16x16x32_bf16 v[102:105], v[158:161], v[204:207], v[102:105]
	v_mfma_f32_16x16x32_bf16 v[94:97], v[150:153], v[212:215], v[94:97]
	v_mfma_f32_16x16x32_bf16 v[86:89], v[158:161], v[212:215], v[86:89]
	v_mfma_f32_16x16x32_bf16 v[126:129], v[154:157], v[192:195], v[126:129]
	v_mfma_f32_16x16x32_bf16 v[122:125], v[168:171], v[192:195], v[122:125]
	v_mfma_f32_16x16x32_bf16 v[118:121], v[154:157], v[200:203], v[118:121]
	v_mfma_f32_16x16x32_bf16 v[114:117], v[168:171], v[200:203], v[114:117]
	v_mfma_f32_16x16x32_bf16 v[110:113], v[154:157], v[208:211], v[110:113]
	v_mfma_f32_16x16x32_bf16 v[102:105], v[168:171], v[208:211], v[102:105]
	v_mfma_f32_16x16x32_bf16 v[94:97], v[154:157], v[216:219], v[94:97]
	v_mfma_f32_16x16x32_bf16 v[86:89], v[168:171], v[216:219], v[86:89]
	s_nop 0
	s_nop 0
	v_mfma_f32_16x16x32_bf16 v[106:109], v[172:175], v[188:191], v[106:109]
	v_mfma_f32_16x16x32_bf16 v[98:101], v[180:183], v[188:191], v[98:101]
	v_mfma_f32_16x16x32_bf16 v[90:93], v[172:175], v[196:199], v[90:93]
	v_mfma_f32_16x16x32_bf16 v[82:85], v[180:183], v[196:199], v[82:85]
	v_mfma_f32_16x16x32_bf16 v[78:81], v[172:175], v[204:207], v[78:81]
	v_mfma_f32_16x16x32_bf16 v[74:77], v[180:183], v[204:207], v[74:77]
	v_mfma_f32_16x16x32_bf16 v[70:73], v[172:175], v[212:215], v[70:73]
	v_mfma_f32_16x16x32_bf16 v[66:69], v[180:183], v[212:215], v[66:69]
	v_mfma_f32_16x16x32_bf16 v[106:109], v[176:179], v[192:195], v[106:109]
	v_mfma_f32_16x16x32_bf16 v[98:101], v[184:187], v[192:195], v[98:101]
	v_mfma_f32_16x16x32_bf16 v[90:93], v[176:179], v[200:203], v[90:93]
	v_mfma_f32_16x16x32_bf16 v[82:85], v[184:187], v[200:203], v[82:85]
	v_mfma_f32_16x16x32_bf16 v[78:81], v[176:179], v[208:211], v[78:81]
	v_mfma_f32_16x16x32_bf16 v[74:77], v[184:187], v[208:211], v[74:77]
	v_mfma_f32_16x16x32_bf16 v[70:73], v[176:179], v[216:219], v[70:73]
	v_mfma_f32_16x16x32_bf16 v[66:69], v[184:187], v[216:219], v[66:69]
	s_nop 0
	s_barrier
; #define G8_STAGE(bufoff, gbase, voff) do { _Pragma("unroll") for (int _i = 0; _i < 2; ++_i) \
;         __builtin_amdgcn_global_load_lds((const unsigned*)((const char*)(gbase) + (voff)[_i]), (LAS unsigned*)(lds + (bufoff) + ldsw + _i * 8192), 16, 0, 0); } while (0)
; #define G8_LDA(dst, b, h) do { _Pragma("unroll") for (int m = 0; m < 4; ++m) _Pragma("unroll") for (int k = 0; k < 2; ++k) dst[m][k] = *(const LAS bf16x8*)(lds + G8_SA(b, h) + aoff + m * 2048 + k * 1024); } while (0)
; #define G8_MMA(ai, bj, At, Bt) do { __builtin_amdgcn_s_setprio(1); _Pragma("unroll") for (int m = 0; m < 4; ++m) _Pragma("unroll") for (int n = 0; n < 2; ++n) _Pragma("unroll") for (int k = 0; k < 2; ++k) \
;         acc[ai][bj][m][n] = __builtin_amdgcn_mfma_f32_16x16x32_bf16(Bt[n][k], At[m][k], acc[ai][bj][m][n], 0, 0, 0); __builtin_amdgcn_s_setprio(0); } while (0)
; #define G8_WAIT_V(n) asm volatile("s_waitcnt vmcnt(" #n ")" ::: "memory")
; #define G8_WAIT_L(n) asm volatile("s_waitcnt lgkmcnt(" #n ")" ::: "memory")
; #define G8_BAR __builtin_amdgcn_s_barrier()
; #define G8_SCHED __builtin_amdgcn_sched_barrier(0)
; template <class Epi, class Sched>
; DEV void gemm_phase(LAS char* lds, const Sched& S, const Epi& E) {
;     ...
;             G8_LDA(At, 1, 1); G8_STAGE(G8_SB(1, 0), b3, voffB); G8_STAGE(G8_SB(1, 1), b3 + hstepB, voffB); G8_STAGE(G8_SA(1, 0), a3, voffA);
;             G8_WAIT_V(8); G8_WAIT_L(0); G8_BAR; G8_MMA(1, 0, At, B0); G8_MMA(1, 1, At, B1); G8_BAR; G8_SCHED;
;         }
;         if (wr == 0) G8_BAR;
	s_add_i32 s30, s50, s37
	v_lshl_add_u64 v[0:1], v[0:1], 0, s[10:11]
	s_mov_b32 m0, s30
	ds_read_b128 v[188:191], v167 offset:49152
	ds_read_b128 v[192:195], v167 offset:50176
	ds_read_b128 v[196:199], v167 offset:51200
	ds_read_b128 v[200:203], v167 offset:52224
	ds_read_b128 v[204:207], v167 offset:53248
	ds_read_b128 v[208:211], v167 offset:54272
	ds_read_b128 v[212:215], v167 offset:55296
	ds_read_b128 v[216:219], v167 offset:56320
	global_load_lds_dwordx4 v[0:1], off
	s_add_i32 m0, s30, 0x2000
	s_add_u32 s28, s28, 0x40080
	v_lshl_add_u64 v[0:1], v[220:221], 0, s[10:11]
	s_addc_u32 s29, s29, 0
	s_add_i32 s30, s51, s37
	global_load_lds_dwordx4 v[0:1], off
	v_lshl_add_u64 v[0:1], s[28:29], 0, v[132:133]
	s_mov_b32 m0, s30
	s_nop 0
	global_load_lds_dwordx4 v[0:1], off
	v_lshl_add_u64 v[0:1], s[28:29], 0, v[136:137]
	s_add_i32 m0, s30, 0x2000
	s_nop 0
	global_load_lds_dwordx4 v[0:1], off
	v_lshl_add_u64 v[0:1], s[26:27], 0, v[130:131]
	s_mov_b32 m0, s42
	s_nop 0
	global_load_lds_dwordx4 v[0:1], off
	v_lshl_add_u64 v[0:1], s[26:27], 0, v[134:135]
	s_mov_b32 m0, s43
	s_nop 0
	global_load_lds_dwordx4 v[0:1], off
	s_waitcnt vmcnt(8)
	s_waitcnt lgkmcnt(0)
	s_barrier
	s_nop 0
	s_waitcnt lgkmcnt(0)
	v_mfma_f32_16x16x32_bf16 v[62:65], v[150:153], v[188:191], v[62:65]
	v_mfma_f32_16x16x32_bf16 v[58:61], v[158:161], v[188:191], v[58:61]
	v_mfma_f32_16x16x32_bf16 v[54:57], v[150:153], v[196:199], v[54:57]
	v_mfma_f32_16x16x32_bf16 v[50:53], v[158:161], v[196:199], v[50:53]
	v_mfma_f32_16x16x32_bf16 v[46:49], v[150:153], v[204:207], v[46:49]
	v_mfma_f32_16x16x32_bf16 v[38:41], v[158:161], v[204:207], v[38:41]
	v_mfma_f32_16x16x32_bf16 v[30:33], v[150:153], v[212:215], v[30:33]
	v_mfma_f32_16x16x32_bf16 v[22:25], v[158:161], v[212:215], v[22:25]
	v_mfma_f32_16x16x32_bf16 v[62:65], v[154:157], v[192:195], v[62:65]
	v_mfma_f32_16x16x32_bf16 v[58:61], v[168:171], v[192:195], v[58:61]
	v_mfma_f32_16x16x32_bf16 v[54:57], v[154:157], v[200:203], v[54:57]
	v_mfma_f32_16x16x32_bf16 v[50:53], v[168:171], v[200:203], v[50:53]
	v_mfma_f32_16x16x32_bf16 v[46:49], v[154:157], v[208:211], v[46:49]
	v_mfma_f32_16x16x32_bf16 v[38:41], v[168:171], v[208:211], v[38:41]
	v_mfma_f32_16x16x32_bf16 v[30:33], v[154:157], v[216:219], v[30:33]
	v_mfma_f32_16x16x32_bf16 v[22:25], v[168:171], v[216:219], v[22:25]
	s_nop 0
	s_nop 0
	v_mfma_f32_16x16x32_bf16 v[42:45], v[172:175], v[188:191], v[42:45]
	v_mfma_f32_16x16x32_bf16 v[34:37], v[180:183], v[188:191], v[34:37]
	v_mfma_f32_16x16x32_bf16 v[26:29], v[172:175], v[196:199], v[26:29]
	v_mfma_f32_16x16x32_bf16 v[18:21], v[180:183], v[196:199], v[18:21]
	v_mfma_f32_16x16x32_bf16 v[14:17], v[172:175], v[204:207], v[14:17]
	v_mfma_f32_16x16x32_bf16 v[10:13], v[180:183], v[204:207], v[10:13]
	v_mfma_f32_16x16x32_bf16 v[6:9], v[172:175], v[212:215], v[6:9]
	v_mfma_f32_16x16x32_bf16 v[2:5], v[180:183], v[212:215], v[2:5]
	v_mfma_f32_16x16x32_bf16 v[42:45], v[176:179], v[192:195], v[42:45]
	v_mfma_f32_16x16x32_bf16 v[34:37], v[184:187], v[192:195], v[34:37]
	v_mfma_f32_16x16x32_bf16 v[26:29], v[176:179], v[200:203], v[26:29]
	v_mfma_f32_16x16x32_bf16 v[18:21], v[184:187], v[200:203], v[18:21]
	v_mfma_f32_16x16x32_bf16 v[14:17], v[176:179], v[208:211], v[14:17]
	v_mfma_f32_16x16x32_bf16 v[10:13], v[184:187], v[208:211], v[10:13]
	v_mfma_f32_16x16x32_bf16 v[6:9], v[176:179], v[216:219], v[6:9]
	v_mfma_f32_16x16x32_bf16 v[2:5], v[184:187], v[216:219], v[2:5]
	s_nop 0
	s_barrier
	s_add_i32 s54, s54, 2
	s_add_u32 s24, s24, 0x100
	s_addc_u32 s25, s25, 0
	s_cmp_gt_u32 s54, 13
	s_cbranch_scc0 .LBB0_1066
	s_and_b64 vcc, exec, s[12:13]
	s_cbranch_vccz .LBB0_1069
	s_barrier

; #define G8_STAGE(bufoff, gbase, voff) do { _Pragma("unroll") for (int _i = 0; _i < 2; ++_i) \
;         __builtin_amdgcn_global_load_lds((const unsigned*)((const char*)(gbase) + (voff)[_i]), (LAS unsigned*)(lds + (bufoff) + ldsw + _i * 8192), 16, 0, 0); } while (0)
; #define G8_LDA(dst, b, h) do { _Pragma("unroll") for (int m = 0; m < 4; ++m) _Pragma("unroll") for (int k = 0; k < 2; ++k) dst[m][k] = *(const LAS bf16x8*)(lds + G8_SA(b, h) + aoff + m * 2048 + k * 1024); } while (0)
; #define G8_LDB(dst, b, h) do { _Pragma("unroll") for (int n = 0; n < 2; ++n) _Pragma("unroll") for (int k = 0; k < 2; ++k) dst[n][k] = *(const LAS bf16x8*)(lds + G8_SB(b, h) + boff + n * 2048 + k * 1024); } while (0)
; #define G8_MMA(ai, bj, At, Bt) do { __builtin_amdgcn_s_setprio(1); _Pragma("unroll") for (int m = 0; m < 4; ++m) _Pragma("unroll") for (int n = 0; n < 2; ++n) _Pragma("unroll") for (int k = 0; k < 2; ++k) \
;         acc[ai][bj][m][n] = __builtin_amdgcn_mfma_f32_16x16x32_bf16(Bt[n][k], At[m][k], acc[ai][bj][m][n], 0, 0, 0); __builtin_amdgcn_s_setprio(0); } while (0)
; #define G8_WAIT_V(n) asm volatile("s_waitcnt vmcnt(" #n ")" ::: "memory")
; #define G8_WAIT_L(n) asm volatile("s_waitcnt lgkmcnt(" #n ")" ::: "memory")
; #define G8_BAR __builtin_amdgcn_s_barrier()
; #define G8_SCHED __builtin_amdgcn_sched_barrier(0)
; template <class Epi, class Sched>
; DEV void gemm_phase(LAS char* lds, const Sched& S, const Epi& E) {
;     ...
;         for (int t = 0; t < nt; t += 2) {
;             const bool last = (t == nt - 2);
;             const char* a1 = G8_AK(t + 1);
;             const char* a2 = last ? nA : G8_AK(t + 2); const char* b2 = last ? nB : cB + (size_t)(t + 2) * kstep;
;             const char* a3 = last ? nA + kstepA : G8_AK(t + 3); const char* b3 = b2 + kstep;
;             G8_LDB(B0, 0, 0); G8_LDB(B1, 0, 1); G8_SCHED; G8_LDA(At, 0, 0); G8_STAGE(G8_SA(1, 1), a1 + hstepA, voffA);
;             G8_WAIT_V(8); G8_WAIT_L(0); G8_BAR; G8_MMA(0, 0, At, B0); G8_MMA(0, 1, At, B1); G8_BAR; G8_SCHED;
;             G8_LDA(At, 0, 1); G8_STAGE(G8_SB(0, 0), b2, voffB); G8_STAGE(G8_SB(0, 1), b2 + hstepB, voffB); G8_STAGE(G8_SA(0, 0), a2, voffA);
.LBB0_1316:
	ds_read_b128 v[62:65], v246
	ds_read_b128 v[70:73], v246 offset:1024
	ds_read_b128 v[78:81], v246 offset:2048
	ds_read_b128 v[82:85], v246 offset:3072
	ds_read_b128 v[90:93], v247
	ds_read_b128 v[98:101], v247 offset:1024
	ds_read_b128 v[110:113], v247 offset:2048
	ds_read_b128 v[122:125], v247 offset:3072
	s_add_u32 s38, s34, s36
	s_addc_u32 s39, s35, s37
	s_add_u32 s42, s38, 0x400000
	s_addc_u32 s43, s39, 0
	s_add_u32 s38, s38, 0x600000
	s_addc_u32 s39, s39, 0
	s_cmp_eq_u32 s36, 0x1c00000
	s_cselect_b32 s39, s1, s39
	s_cselect_b32 s38, s0, s38
	s_cselect_b32 s41, s27, s31
	s_cselect_b32 s40, s26, s23
	s_cselect_b32 s43, s25, s43
	s_cselect_b32 s42, s24, s42
	v_lshl_add_u64 v[0:1], v[60:61], 0, s[36:37]
	s_add_i32 m0, s59, 0xc000
	ds_read_b128 v[134:137], v248
	ds_read_b128 v[146:149], v248 offset:1024
	ds_read_b128 v[158:161], v248 offset:2048
	ds_read_b128 v[166:169], v248 offset:3072
	ds_read_b128 v[174:177], v248 offset:4096
	ds_read_b128 v[182:185], v248 offset:5120
	ds_read_b128 v[190:193], v248 offset:6144
	ds_read_b128 v[194:197], v248 offset:7168
	global_load_lds_dwordx4 v[0:1], off
	v_lshl_add_u64 v[0:1], v[58:59], 0, s[36:37]
	s_add_i32 m0, s59, 0xe000
	s_nop 0
	global_load_lds_dwordx4 v[0:1], off
	s_waitcnt vmcnt(8)
	s_waitcnt lgkmcnt(0)
	s_barrier
	s_nop 0
	s_waitcnt lgkmcnt(0)
	v_mfma_f32_16x16x32_bf16 v[186:189], v[62:65], v[134:137], v[186:189]
	v_mfma_f32_16x16x32_bf16 v[178:181], v[78:81], v[134:137], v[178:181]
	v_mfma_f32_16x16x32_bf16 v[154:157], v[62:65], v[158:161], v[154:157]
	v_mfma_f32_16x16x32_bf16 v[150:153], v[78:81], v[158:161], v[150:153]
	v_mfma_f32_16x16x32_bf16 v[130:133], v[62:65], v[174:177], v[130:133]
	v_mfma_f32_16x16x32_bf16 v[126:129], v[78:81], v[174:177], v[126:129]
	v_mfma_f32_16x16x32_bf16 v[106:109], v[62:65], v[190:193], v[106:109]
	v_mfma_f32_16x16x32_bf16 v[102:105], v[78:81], v[190:193], v[102:105]
	v_mfma_f32_16x16x32_bf16 v[186:189], v[70:73], v[146:149], v[186:189]
	v_mfma_f32_16x16x32_bf16 v[178:181], v[82:85], v[146:149], v[178:181]
	v_mfma_f32_16x16x32_bf16 v[154:157], v[70:73], v[166:169], v[154:157]
	v_mfma_f32_16x16x32_bf16 v[150:153], v[82:85], v[166:169], v[150:153]
	v_mfma_f32_16x16x32_bf16 v[130:133], v[70:73], v[182:185], v[130:133]
	v_mfma_f32_16x16x32_bf16 v[126:129], v[82:85], v[182:185], v[126:129]
	v_mfma_f32_16x16x32_bf16 v[106:109], v[70:73], v[194:197], v[106:109]
	v_mfma_f32_16x16x32_bf16 v[102:105], v[82:85], v[194:197], v[102:105]
	s_nop 0
	s_nop 0
	v_mfma_f32_16x16x32_bf16 v[170:173], v[90:93], v[134:137], v[170:173]
	v_mfma_f32_16x16x32_bf16 v[142:145], v[90:93], v[158:161], v[142:145]
	v_mfma_f32_16x16x32_bf16 v[138:141], v[110:113], v[158:161], v[138:141]
	v_mfma_f32_16x16x32_bf16 v[118:121], v[90:93], v[174:177], v[118:121]
	v_mfma_f32_16x16x32_bf16 v[114:117], v[110:113], v[174:177], v[114:117]
	v_mfma_f32_16x16x32_bf16 v[94:97], v[90:93], v[190:193], v[94:97]
	v_mfma_f32_16x16x32_bf16 v[86:89], v[110:113], v[190:193], v[86:89]
	v_mfma_f32_16x16x32_bf16 v[170:173], v[98:101], v[146:149], v[170:173]
	v_mfma_f32_16x16x32_bf16 v[134:137], v[110:113], v[134:137], v[162:165]
	v_mfma_f32_16x16x32_bf16 v[142:145], v[98:101], v[166:169], v[142:145]
	v_mfma_f32_16x16x32_bf16 v[138:141], v[122:125], v[166:169], v[138:141]
	v_mfma_f32_16x16x32_bf16 v[118:121], v[98:101], v[182:185], v[118:121]
	v_mfma_f32_16x16x32_bf16 v[114:117], v[122:125], v[182:185], v[114:117]
	v_mfma_f32_16x16x32_bf16 v[94:97], v[98:101], v[194:197], v[94:97]
	v_mfma_f32_16x16x32_bf16 v[86:89], v[122:125], v[194:197], v[86:89]
	v_mfma_f32_16x16x32_bf16 v[134:137], v[122:125], v[146:149], v[134:137]
	s_nop 0
	s_barrier
	s_add_i32 s58, s62, s57
	v_lshl_add_u64 v[0:1], s[40:41], 0, v[212:213]
	s_mov_b32 m0, s58
	ds_read_b128 v[146:149], v248 offset:16384
	ds_read_b128 v[158:161], v248 offset:17408
	ds_read_b128 v[162:165], v248 offset:18432
	ds_read_b128 v[166:169], v248 offset:19456
	ds_read_b128 v[174:177], v248 offset:20480
	ds_read_b128 v[182:185], v248 offset:21504
	ds_read_b128 v[190:193], v248 offset:22528
	ds_read_b128 v[194:197], v248 offset:23552
	global_load_lds_dwordx4 v[0:1], off
	s_add_i32 m0, s58, 0x2000
	s_add_u32 s76, s40, 0x40000
	v_lshl_add_u64 v[202:203], s[40:41], 0, v[216:217]
	s_addc_u32 s77, s41, 0
	s_add_i32 s58, s63, s57
	global_load_lds_dwordx4 v[202:203], off
	v_lshl_add_u64 v[198:199], s[76:77], 0, v[212:213]
	s_mov_b32 m0, s58
	s_nop 0
	global_load_lds_dwordx4 v[198:199], off
	v_lshl_add_u64 v[198:199], s[76:77], 0, v[216:217]
	s_add_i32 m0, s58, 0x2000
	s_nop 0
	global_load_lds_dwordx4 v[198:199], off
	v_lshl_add_u64 v[198:199], s[42:43], 0, v[210:211]
	s_mov_b32 m0, s59
	s_nop 0
	global_load_lds_dwordx4 v[198:199], off
	v_lshl_add_u64 v[198:199], s[42:43], 0, v[214:215]
	s_mov_b32 m0, s60
	s_nop 0
	global_load_lds_dwordx4 v[198:199], off
	s_waitcnt vmcnt(8)
	s_waitcnt lgkmcnt(0)
	s_barrier
; #define G8_STAGE(bufoff, gbase, voff) do { _Pragma("unroll") for (int _i = 0; _i < 2; ++_i) \
;         __builtin_amdgcn_global_load_lds((const unsigned*)((const char*)(gbase) + (voff)[_i]), (LAS unsigned*)(lds + (bufoff) + ldsw + _i * 8192), 16, 0, 0); } while (0)
; #define G8_LDA(dst, b, h) do { _Pragma("unroll") for (int m = 0; m < 4; ++m) _Pragma("unroll") for (int k = 0; k < 2; ++k) dst[m][k] = *(const LAS bf16x8*)(lds + G8_SA(b, h) + aoff + m * 2048 + k * 1024); } while (0)
; #define G8_LDB(dst, b, h) do { _Pragma("unroll") for (int n = 0; n < 2; ++n) _Pragma("unroll") for (int k = 0; k < 2; ++k) dst[n][k] = *(const LAS bf16x8*)(lds + G8_SB(b, h) + boff + n * 2048 + k * 1024); } while (0)
; #define G8_MMA(ai, bj, At, Bt) do { __builtin_amdgcn_s_setprio(1); _Pragma("unroll") for (int m = 0; m < 4; ++m) _Pragma("unroll") for (int n = 0; n < 2; ++n) _Pragma("unroll") for (int k = 0; k < 2; ++k) \
;         acc[ai][bj][m][n] = __builtin_amdgcn_mfma_f32_16x16x32_bf16(Bt[n][k], At[m][k], acc[ai][bj][m][n], 0, 0, 0); __builtin_amdgcn_s_setprio(0); } while (0)
; #define G8_WAIT_V(n) asm volatile("s_waitcnt vmcnt(" #n ")" ::: "memory")
; #define G8_WAIT_L(n) asm volatile("s_waitcnt lgkmcnt(" #n ")" ::: "memory")
; #define G8_BAR __builtin_amdgcn_s_barrier()
; #define G8_SCHED __builtin_amdgcn_sched_barrier(0)
; template <class Epi, class Sched>
; DEV void gemm_phase(LAS char* lds, const Sched& S, const Epi& E) {
;     ...
;             G8_WAIT_V(8); G8_WAIT_L(0); G8_BAR; G8_MMA(1, 0, At, B0); G8_MMA(1, 1, At, B1); G8_BAR; G8_SCHED;
;             G8_LDB(B0, 1, 0); G8_LDB(B1, 1, 1); G8_SCHED; G8_LDA(At, 1, 0); G8_STAGE(G8_SA(0, 1), a2 + hstepA, voffA);
;             G8_WAIT_V(8); G8_WAIT_L(0); G8_BAR; G8_MMA(0, 0, At, B0); G8_MMA(0, 1, At, B1); G8_BAR; G8_SCHED;
	s_nop 0
	s_waitcnt lgkmcnt(0)
	v_mfma_f32_16x16x32_bf16 v[74:77], v[62:65], v[146:149], v[74:77]
	v_mfma_f32_16x16x32_bf16 v[66:69], v[78:81], v[146:149], v[66:69]
	v_mfma_f32_16x16x32_bf16 v[46:49], v[62:65], v[162:165], v[46:49]
	v_mfma_f32_16x16x32_bf16 v[42:45], v[78:81], v[162:165], v[42:45]
	v_mfma_f32_16x16x32_bf16 v[30:33], v[62:65], v[174:177], v[30:33]
	v_mfma_f32_16x16x32_bf16 v[26:29], v[78:81], v[174:177], v[26:29]
	v_mfma_f32_16x16x32_bf16 v[14:17], v[62:65], v[190:193], v[14:17]
	v_mfma_f32_16x16x32_bf16 v[10:13], v[78:81], v[190:193], v[10:13]
	v_mfma_f32_16x16x32_bf16 v[74:77], v[70:73], v[158:161], v[74:77]
	v_mfma_f32_16x16x32_bf16 v[66:69], v[82:85], v[158:161], v[66:69]
	v_mfma_f32_16x16x32_bf16 v[46:49], v[70:73], v[166:169], v[46:49]
	v_mfma_f32_16x16x32_bf16 v[42:45], v[82:85], v[166:169], v[42:45]
	v_mfma_f32_16x16x32_bf16 v[30:33], v[70:73], v[182:185], v[30:33]
	v_mfma_f32_16x16x32_bf16 v[26:29], v[82:85], v[182:185], v[26:29]
	v_mfma_f32_16x16x32_bf16 v[14:17], v[70:73], v[194:197], v[14:17]
	v_mfma_f32_16x16x32_bf16 v[10:13], v[82:85], v[194:197], v[10:13]
	s_nop 0
	s_nop 0
	v_mfma_f32_16x16x32_bf16 v[54:57], v[90:93], v[146:149], v[54:57]
	v_mfma_f32_16x16x32_bf16 v[50:53], v[110:113], v[146:149], v[50:53]
	v_mfma_f32_16x16x32_bf16 v[38:41], v[90:93], v[162:165], v[38:41]
	v_mfma_f32_16x16x32_bf16 v[34:37], v[110:113], v[162:165], v[34:37]
	v_mfma_f32_16x16x32_bf16 v[22:25], v[90:93], v[174:177], v[22:25]
	v_mfma_f32_16x16x32_bf16 v[18:21], v[110:113], v[174:177], v[18:21]
	v_mfma_f32_16x16x32_bf16 v[6:9], v[90:93], v[190:193], v[6:9]
	v_mfma_f32_16x16x32_bf16 v[2:5], v[110:113], v[190:193], v[2:5]
	v_mfma_f32_16x16x32_bf16 v[54:57], v[98:101], v[158:161], v[54:57]
	v_mfma_f32_16x16x32_bf16 v[50:53], v[122:125], v[158:161], v[50:53]
	v_mfma_f32_16x16x32_bf16 v[38:41], v[98:101], v[166:169], v[38:41]
	v_mfma_f32_16x16x32_bf16 v[34:37], v[122:125], v[166:169], v[34:37]
	v_mfma_f32_16x16x32_bf16 v[22:25], v[98:101], v[182:185], v[22:25]
	v_mfma_f32_16x16x32_bf16 v[18:21], v[122:125], v[182:185], v[18:21]
	v_mfma_f32_16x16x32_bf16 v[6:9], v[98:101], v[194:197], v[6:9]
	v_mfma_f32_16x16x32_bf16 v[2:5], v[122:125], v[194:197], v[2:5]
	s_nop 0
	s_barrier
	v_add_u32_e32 v82, s50, v243
	v_add_u32_e32 v122, s51, v243
	ds_read_b128 v[62:65], v82
	ds_read_b128 v[70:73], v82 offset:1024
	ds_read_b128 v[78:81], v82 offset:2048
	ds_read_b128 v[82:85], v82 offset:3072
	ds_read_b128 v[90:93], v122
	ds_read_b128 v[98:101], v122 offset:1024
	ds_read_b128 v[110:113], v122 offset:2048
	ds_read_b128 v[122:125], v122 offset:3072
	s_add_u32 s42, s42, 0x1000
	s_addc_u32 s43, s43, 0
	s_mov_b32 m0, s61
	v_lshl_add_u64 v[162:163], s[42:43], 0, v[210:211]
	ds_read_b128 v[146:149], v248 offset:32768
	ds_read_b128 v[158:161], v248 offset:33792
	ds_read_b128 v[166:169], v248 offset:34816
	ds_read_b128 v[174:177], v248 offset:35840
	ds_read_b128 v[182:185], v248 offset:36864
	ds_read_b128 v[190:193], v248 offset:37888
	ds_read_b128 v[194:197], v248 offset:38912
	ds_read_b128 v[198:201], v248 offset:39936
	global_load_lds_dwordx4 v[162:163], off
	v_lshl_add_u64 v[162:163], s[42:43], 0, v[214:215]
	s_mov_b32 m0, s65
	s_nop 0
	global_load_lds_dwordx4 v[162:163], off
	s_waitcnt vmcnt(8)
	s_waitcnt lgkmcnt(0)
	s_barrier
	s_nop 0
	s_waitcnt lgkmcnt(0)
	v_mfma_f32_16x16x32_bf16 v[162:165], v[62:65], v[146:149], v[186:189]
	v_mfma_f32_16x16x32_bf16 v[186:189], v[70:73], v[158:161], v[162:165]
	v_mfma_f32_16x16x32_bf16 v[162:165], v[78:81], v[146:149], v[178:181]
	v_mfma_f32_16x16x32_bf16 v[154:157], v[62:65], v[166:169], v[154:157]
	v_mfma_f32_16x16x32_bf16 v[150:153], v[78:81], v[166:169], v[150:153]
	v_mfma_f32_16x16x32_bf16 v[130:133], v[62:65], v[182:185], v[130:133]
	v_mfma_f32_16x16x32_bf16 v[126:129], v[78:81], v[182:185], v[126:129]
	v_mfma_f32_16x16x32_bf16 v[106:109], v[62:65], v[194:197], v[106:109]
	v_mfma_f32_16x16x32_bf16 v[102:105], v[78:81], v[194:197], v[102:105]
	v_mfma_f32_16x16x32_bf16 v[178:181], v[82:85], v[158:161], v[162:165]
	v_mfma_f32_16x16x32_bf16 v[154:157], v[70:73], v[174:177], v[154:157]
	v_mfma_f32_16x16x32_bf16 v[150:153], v[82:85], v[174:177], v[150:153]
	v_mfma_f32_16x16x32_bf16 v[130:133], v[70:73], v[190:193], v[130:133]
	v_mfma_f32_16x16x32_bf16 v[126:129], v[82:85], v[190:193], v[126:129]
	v_mfma_f32_16x16x32_bf16 v[106:109], v[70:73], v[198:201], v[106:109]
	v_mfma_f32_16x16x32_bf16 v[102:105], v[82:85], v[198:201], v[102:105]
	s_nop 0
	s_nop 0
	v_mfma_f32_16x16x32_bf16 v[162:165], v[90:93], v[146:149], v[170:173]
	v_mfma_f32_16x16x32_bf16 v[134:137], v[110:113], v[146:149], v[134:137]
	v_mfma_f32_16x16x32_bf16 v[170:173], v[98:101], v[158:161], v[162:165]
	v_mfma_f32_16x16x32_bf16 v[162:165], v[122:125], v[158:161], v[134:137]
	v_mfma_f32_16x16x32_bf16 v[134:137], v[90:93], v[166:169], v[142:145]
	v_mfma_f32_16x16x32_bf16 v[142:145], v[98:101], v[174:177], v[134:137]
	v_mfma_f32_16x16x32_bf16 v[134:137], v[110:113], v[166:169], v[138:141]
	v_mfma_f32_16x16x32_bf16 v[118:121], v[90:93], v[182:185], v[118:121]
	v_mfma_f32_16x16x32_bf16 v[114:117], v[110:113], v[182:185], v[114:117]
	v_mfma_f32_16x16x32_bf16 v[94:97], v[90:93], v[194:197], v[94:97]
	v_mfma_f32_16x16x32_bf16 v[86:89], v[110:113], v[194:197], v[86:89]
	v_mfma_f32_16x16x32_bf16 v[138:141], v[122:125], v[174:177], v[134:137]
	v_mfma_f32_16x16x32_bf16 v[118:121], v[98:101], v[190:193], v[118:121]
	v_mfma_f32_16x16x32_bf16 v[114:117], v[122:125], v[190:193], v[114:117]
	v_mfma_f32_16x16x32_bf16 v[94:97], v[98:101], v[198:201], v[94:97]
	v_mfma_f32_16x16x32_bf16 v[86:89], v[122:125], v[198:201], v[86:89]
	s_nop 0
	s_barrier
; #define G8_STAGE(bufoff, gbase, voff) do { _Pragma("unroll") for (int _i = 0; _i < 2; ++_i) \
;         __builtin_amdgcn_global_load_lds((const unsigned*)((const char*)(gbase) + (voff)[_i]), (LAS unsigned*)(lds + (bufoff) + ldsw + _i * 8192), 16, 0, 0); } while (0)
; #define G8_LDA(dst, b, h) do { _Pragma("unroll") for (int m = 0; m < 4; ++m) _Pragma("unroll") for (int k = 0; k < 2; ++k) dst[m][k] = *(const LAS bf16x8*)(lds + G8_SA(b, h) + aoff + m * 2048 + k * 1024); } while (0)
; #define G8_MMA(ai, bj, At, Bt) do { __builtin_amdgcn_s_setprio(1); _Pragma("unroll") for (int m = 0; m < 4; ++m) _Pragma("unroll") for (int n = 0; n < 2; ++n) _Pragma("unroll") for (int k = 0; k < 2; ++k) \
;         acc[ai][bj][m][n] = __builtin_amdgcn_mfma_f32_16x16x32_bf16(Bt[n][k], At[m][k], acc[ai][bj][m][n], 0, 0, 0); __builtin_amdgcn_s_setprio(0); } while (0)
; #define G8_WAIT_V(n) asm volatile("s_waitcnt vmcnt(" #n ")" ::: "memory")
; #define G8_WAIT_L(n) asm volatile("s_waitcnt lgkmcnt(" #n ")" ::: "memory")
; #define G8_BAR __builtin_amdgcn_s_barrier()
; #define G8_SCHED __builtin_amdgcn_sched_barrier(0)
; template <class Epi, class Sched>
; DEV void gemm_phase(LAS char* lds, const Sched& S, const Epi& E) {
;     ...
;             G8_LDA(At, 1, 1); G8_STAGE(G8_SB(1, 0), b3, voffB); G8_STAGE(G8_SB(1, 1), b3 + hstepB, voffB); G8_STAGE(G8_SA(1, 0), a3, voffA);
;             G8_WAIT_V(8); G8_WAIT_L(0); G8_BAR; G8_MMA(1, 0, At, B0); G8_MMA(1, 1, At, B1); G8_BAR; G8_SCHED;
;         }
;         if (wr == 0) G8_BAR;
	s_add_i32 s42, s50, s57
	v_lshl_add_u64 v[0:1], v[0:1], 0, s[18:19]
	s_mov_b32 m0, s42
	ds_read_b128 v[134:137], v248 offset:49152
	ds_read_b128 v[146:149], v248 offset:50176
	ds_read_b128 v[158:161], v248 offset:51200
	ds_read_b128 v[166:169], v248 offset:52224
	ds_read_b128 v[174:177], v248 offset:53248
	ds_read_b128 v[182:185], v248 offset:54272
	ds_read_b128 v[190:193], v248 offset:55296
	ds_read_b128 v[194:197], v248 offset:56320
	global_load_lds_dwordx4 v[0:1], off
	s_add_i32 m0, s42, 0x2000
	s_add_u32 s40, s40, 0x40080
	v_lshl_add_u64 v[0:1], v[202:203], 0, s[18:19]
	s_addc_u32 s41, s41, 0
	s_add_i32 s42, s51, s57
	global_load_lds_dwordx4 v[0:1], off
	v_lshl_add_u64 v[0:1], s[40:41], 0, v[212:213]
	s_mov_b32 m0, s42
	s_nop 0
	global_load_lds_dwordx4 v[0:1], off
	v_lshl_add_u64 v[0:1], s[40:41], 0, v[216:217]
	s_add_i32 m0, s42, 0x2000
	s_nop 0
	global_load_lds_dwordx4 v[0:1], off
	v_lshl_add_u64 v[0:1], s[38:39], 0, v[210:211]
	s_mov_b32 m0, s68
	s_nop 0
	global_load_lds_dwordx4 v[0:1], off
	v_lshl_add_u64 v[0:1], s[38:39], 0, v[214:215]
	s_mov_b32 m0, s69
	s_nop 0
	global_load_lds_dwordx4 v[0:1], off
	s_waitcnt vmcnt(8)
	s_waitcnt lgkmcnt(0)
	s_barrier
	s_nop 0
	s_waitcnt lgkmcnt(0)
	v_mfma_f32_16x16x32_bf16 v[74:77], v[62:65], v[134:137], v[74:77]
	v_mfma_f32_16x16x32_bf16 v[66:69], v[78:81], v[134:137], v[66:69]
	v_mfma_f32_16x16x32_bf16 v[46:49], v[62:65], v[158:161], v[46:49]
	v_mfma_f32_16x16x32_bf16 v[42:45], v[78:81], v[158:161], v[42:45]
	v_mfma_f32_16x16x32_bf16 v[30:33], v[62:65], v[174:177], v[30:33]
	v_mfma_f32_16x16x32_bf16 v[26:29], v[78:81], v[174:177], v[26:29]
	v_mfma_f32_16x16x32_bf16 v[14:17], v[62:65], v[190:193], v[14:17]
	v_mfma_f32_16x16x32_bf16 v[10:13], v[78:81], v[190:193], v[10:13]
	v_mfma_f32_16x16x32_bf16 v[74:77], v[70:73], v[146:149], v[74:77]
	v_mfma_f32_16x16x32_bf16 v[66:69], v[82:85], v[146:149], v[66:69]
	v_mfma_f32_16x16x32_bf16 v[46:49], v[70:73], v[166:169], v[46:49]
	v_mfma_f32_16x16x32_bf16 v[42:45], v[82:85], v[166:169], v[42:45]
	v_mfma_f32_16x16x32_bf16 v[30:33], v[70:73], v[182:185], v[30:33]
	v_mfma_f32_16x16x32_bf16 v[26:29], v[82:85], v[182:185], v[26:29]
	v_mfma_f32_16x16x32_bf16 v[14:17], v[70:73], v[194:197], v[14:17]
	v_mfma_f32_16x16x32_bf16 v[10:13], v[82:85], v[194:197], v[10:13]
	s_nop 0
	s_nop 0
	v_mfma_f32_16x16x32_bf16 v[54:57], v[90:93], v[134:137], v[54:57]
	v_mfma_f32_16x16x32_bf16 v[50:53], v[110:113], v[134:137], v[50:53]
	v_mfma_f32_16x16x32_bf16 v[38:41], v[90:93], v[158:161], v[38:41]
	v_mfma_f32_16x16x32_bf16 v[34:37], v[110:113], v[158:161], v[34:37]
	v_mfma_f32_16x16x32_bf16 v[22:25], v[90:93], v[174:177], v[22:25]
	v_mfma_f32_16x16x32_bf16 v[18:21], v[110:113], v[174:177], v[18:21]
	v_mfma_f32_16x16x32_bf16 v[6:9], v[90:93], v[190:193], v[6:9]
	v_mfma_f32_16x16x32_bf16 v[2:5], v[110:113], v[190:193], v[2:5]
	v_mfma_f32_16x16x32_bf16 v[54:57], v[98:101], v[146:149], v[54:57]
	v_mfma_f32_16x16x32_bf16 v[50:53], v[122:125], v[146:149], v[50:53]
	v_mfma_f32_16x16x32_bf16 v[38:41], v[98:101], v[166:169], v[38:41]
	v_mfma_f32_16x16x32_bf16 v[34:37], v[122:125], v[166:169], v[34:37]
	v_mfma_f32_16x16x32_bf16 v[22:25], v[98:101], v[182:185], v[22:25]
	v_mfma_f32_16x16x32_bf16 v[18:21], v[122:125], v[182:185], v[18:21]
	v_mfma_f32_16x16x32_bf16 v[6:9], v[98:101], v[194:197], v[6:9]
	v_mfma_f32_16x16x32_bf16 v[2:5], v[122:125], v[194:197], v[2:5]
	s_nop 0
	s_barrier
	s_add_i32 s52, s52, 2
	s_add_u32 s23, s23, 0x100
	s_addc_u32 s31, s31, 0
	s_add_u32 s36, s36, 0x400000
	s_addc_u32 s37, s37, 0
	s_cmp_gt_u32 s52, 13
	s_cbranch_scc0 .LBB0_1316
	s_and_b64 vcc, exec, s[20:21]
	s_cbranch_vccz .LBB0_1319
	s_barrier

; #define G8_STAGE(bufoff, gbase, voff) do { _Pragma("unroll") for (int _i = 0; _i < 2; ++_i) \
;         __builtin_amdgcn_global_load_lds((const unsigned*)((const char*)(gbase) + (voff)[_i]), (LAS unsigned*)(lds + (bufoff) + ldsw + _i * 8192), 16, 0, 0); } while (0)
; #define G8_LDA(dst, b, h) do { _Pragma("unroll") for (int m = 0; m < 4; ++m) _Pragma("unroll") for (int k = 0; k < 2; ++k) dst[m][k] = *(const LAS bf16x8*)(lds + G8_SA(b, h) + aoff + m * 2048 + k * 1024); } while (0)
; #define G8_LDB(dst, b, h) do { _Pragma("unroll") for (int n = 0; n < 2; ++n) _Pragma("unroll") for (int k = 0; k < 2; ++k) dst[n][k] = *(const LAS bf16x8*)(lds + G8_SB(b, h) + boff + n * 2048 + k * 1024); } while (0)
; #define G8_MMA(ai, bj, At, Bt) do { __builtin_amdgcn_s_setprio(1); _Pragma("unroll") for (int m = 0; m < 4; ++m) _Pragma("unroll") for (int n = 0; n < 2; ++n) _Pragma("unroll") for (int k = 0; k < 2; ++k) \
;         acc[ai][bj][m][n] = __builtin_amdgcn_mfma_f32_16x16x32_bf16(Bt[n][k], At[m][k], acc[ai][bj][m][n], 0, 0, 0); __builtin_amdgcn_s_setprio(0); } while (0)
; #define G8_WAIT_V(n) asm volatile("s_waitcnt vmcnt(" #n ")" ::: "memory")
; #define G8_WAIT_L(n) asm volatile("s_waitcnt lgkmcnt(" #n ")" ::: "memory")
; #define G8_BAR __builtin_amdgcn_s_barrier()
; #define G8_SCHED __builtin_amdgcn_sched_barrier(0)
; template <class Epi, class Sched>
; DEV void gemm_phase(LAS char* lds, const Sched& S, const Epi& E) {
;     ...
;         for (int t = 0; t < nt; t += 2) {
;             const bool last = (t == nt - 2);
;             const char* a1 = G8_AK(t + 1);
;             const char* a2 = last ? nA : G8_AK(t + 2); const char* b2 = last ? nB : cB + (size_t)(t + 2) * kstep;
;             const char* a3 = last ? nA + kstepA : G8_AK(t + 3); const char* b3 = b2 + kstep;
;             G8_LDB(B0, 0, 0); G8_LDB(B1, 0, 1); G8_SCHED; G8_LDA(At, 0, 0); G8_STAGE(G8_SA(1, 1), a1 + hstepA, voffA);
;             G8_WAIT_V(8); G8_WAIT_L(0); G8_BAR; G8_MMA(0, 0, At, B0); G8_MMA(0, 1, At, B1); G8_BAR; G8_SCHED;
;             G8_LDA(At, 0, 1); G8_STAGE(G8_SB(0, 0), b2, voffB); G8_STAGE(G8_SB(0, 1), b2 + hstepB, voffB); G8_STAGE(G8_SA(0, 0), a2, voffA);
.LBB0_1347:
	ds_read_b128 v[126:129], v116
	ds_read_b128 v[142:145], v116 offset:1024
	ds_read_b128 v[150:153], v116 offset:2048
	ds_read_b128 v[162:165], v116 offset:3072
	ds_read_b128 v[166:169], v117
	ds_read_b128 v[170:173], v117 offset:1024
	ds_read_b128 v[174:177], v117 offset:2048
	ds_read_b128 v[178:181], v117 offset:3072
	s_add_u32 s16, s10, s14
	s_addc_u32 s17, s11, s15
	s_add_u32 s20, s16, 0x100
	s_addc_u32 s21, s17, 0
	s_add_u32 s18, s37, s14
	s_addc_u32 s19, s38, s15
	s_add_u32 s16, s16, 0x180
	s_addc_u32 s17, s17, 0
	s_cmpk_eq_i32 s14, 0x700
	s_cselect_b32 s17, s34, s17
	s_cselect_b32 s16, s31, s16
	s_cselect_b32 s19, s7, s19
	s_cselect_b32 s18, s6, s18
	s_cselect_b32 s21, s11, s21
	s_cselect_b32 s20, s10, s20
	s_mov_b32 m0, s40
	v_lshl_add_u64 v[0:1], v[112:113], 0, s[14:15]
	ds_read_b128 v[182:185], v118
	ds_read_b128 v[186:189], v118 offset:1024
	ds_read_b128 v[190:193], v118 offset:2048
	ds_read_b128 v[194:197], v118 offset:3072
	ds_read_b128 v[198:201], v118 offset:4096
	ds_read_b128 v[202:205], v118 offset:5120
	ds_read_b128 v[206:209], v118 offset:6144
	ds_read_b128 v[210:213], v118 offset:7168
	global_load_lds_dwordx4 v[0:1], off
	v_lshl_add_u64 v[0:1], v[110:111], 0, s[14:15]
	s_mov_b32 m0, s41
	s_nop 0
	global_load_lds_dwordx4 v[0:1], off
	s_waitcnt vmcnt(8)
	s_waitcnt lgkmcnt(0)
	s_barrier
	s_nop 0
	s_waitcnt lgkmcnt(0)
	v_mfma_f32_16x16x32_bf16 v[158:161], v[126:129], v[182:185], v[158:161]
	v_mfma_f32_16x16x32_bf16 v[154:157], v[150:153], v[182:185], v[154:157]
	v_mfma_f32_16x16x32_bf16 v[134:137], v[126:129], v[190:193], v[134:137]
	v_mfma_f32_16x16x32_bf16 v[130:133], v[150:153], v[190:193], v[130:133]
	v_mfma_f32_16x16x32_bf16 v[94:97], v[126:129], v[198:201], v[94:97]
	v_mfma_f32_16x16x32_bf16 v[90:93], v[150:153], v[198:201], v[90:93]
	v_mfma_f32_16x16x32_bf16 v[78:81], v[126:129], v[206:209], v[78:81]
	v_mfma_f32_16x16x32_bf16 v[74:77], v[150:153], v[206:209], v[74:77]
	v_mfma_f32_16x16x32_bf16 v[158:161], v[142:145], v[186:189], v[158:161]
	v_mfma_f32_16x16x32_bf16 v[154:157], v[162:165], v[186:189], v[154:157]
	v_mfma_f32_16x16x32_bf16 v[134:137], v[142:145], v[194:197], v[134:137]
	v_mfma_f32_16x16x32_bf16 v[130:133], v[162:165], v[194:197], v[130:133]
	v_mfma_f32_16x16x32_bf16 v[94:97], v[142:145], v[202:205], v[94:97]
	v_mfma_f32_16x16x32_bf16 v[90:93], v[162:165], v[202:205], v[90:93]
	v_mfma_f32_16x16x32_bf16 v[78:81], v[142:145], v[210:213], v[78:81]
	v_mfma_f32_16x16x32_bf16 v[74:77], v[162:165], v[210:213], v[74:77]
	s_nop 0
	s_nop 0
	v_mfma_f32_16x16x32_bf16 v[146:149], v[166:169], v[182:185], v[146:149]
	v_mfma_f32_16x16x32_bf16 v[138:141], v[174:177], v[182:185], v[138:141]
	v_mfma_f32_16x16x32_bf16 v[122:125], v[166:169], v[190:193], v[122:125]
	v_mfma_f32_16x16x32_bf16 v[102:105], v[174:177], v[190:193], v[102:105]
	v_mfma_f32_16x16x32_bf16 v[86:89], v[166:169], v[198:201], v[86:89]
	v_mfma_f32_16x16x32_bf16 v[82:85], v[174:177], v[198:201], v[82:85]
	v_mfma_f32_16x16x32_bf16 v[70:73], v[166:169], v[206:209], v[70:73]
	v_mfma_f32_16x16x32_bf16 v[66:69], v[174:177], v[206:209], v[66:69]
	v_mfma_f32_16x16x32_bf16 v[146:149], v[170:173], v[186:189], v[146:149]
	v_mfma_f32_16x16x32_bf16 v[138:141], v[178:181], v[186:189], v[138:141]
	v_mfma_f32_16x16x32_bf16 v[122:125], v[170:173], v[194:197], v[122:125]
	v_mfma_f32_16x16x32_bf16 v[102:105], v[178:181], v[194:197], v[102:105]
	v_mfma_f32_16x16x32_bf16 v[86:89], v[170:173], v[202:205], v[86:89]
	v_mfma_f32_16x16x32_bf16 v[82:85], v[178:181], v[202:205], v[82:85]
	v_mfma_f32_16x16x32_bf16 v[70:73], v[170:173], v[210:213], v[70:73]
	v_mfma_f32_16x16x32_bf16 v[66:69], v[178:181], v[210:213], v[66:69]
	s_nop 0
	s_barrier
	s_mov_b32 m0, s42
	v_lshl_add_u64 v[0:1], s[18:19], 0, v[100:101]
	s_add_u32 s56, s18, 0x40000
	ds_read_b128 v[182:185], v118 offset:16384
	ds_read_b128 v[186:189], v118 offset:17408
	ds_read_b128 v[190:193], v118 offset:18432
	ds_read_b128 v[194:197], v118 offset:19456
	ds_read_b128 v[198:201], v118 offset:20480
	ds_read_b128 v[202:205], v118 offset:21504
	ds_read_b128 v[206:209], v118 offset:22528
	ds_read_b128 v[210:213], v118 offset:23552
	global_load_lds_dwordx4 v[0:1], off
	v_lshl_add_u64 v[214:215], s[18:19], 0, v[108:109]
	s_mov_b32 m0, s43
	s_addc_u32 s57, s19, 0
	global_load_lds_dwordx4 v[214:215], off
	v_lshl_add_u64 v[216:217], s[56:57], 0, v[100:101]
	s_mov_b32 m0, s45
	s_nop 0
	global_load_lds_dwordx4 v[216:217], off
	v_lshl_add_u64 v[216:217], s[56:57], 0, v[108:109]
	s_mov_b32 m0, s46
	s_nop 0
	global_load_lds_dwordx4 v[216:217], off
	v_lshl_add_u64 v[216:217], s[20:21], 0, v[98:99]
	s_mov_b32 m0, s1
	s_nop 0
	global_load_lds_dwordx4 v[216:217], off
	v_lshl_add_u64 v[216:217], s[20:21], 0, v[106:107]
	s_mov_b32 m0, s28
	s_nop 0
	global_load_lds_dwordx4 v[216:217], off
	s_waitcnt vmcnt(8)
	s_waitcnt lgkmcnt(0)
	s_barrier
; #define G8_STAGE(bufoff, gbase, voff) do { _Pragma("unroll") for (int _i = 0; _i < 2; ++_i) \
;         __builtin_amdgcn_global_load_lds((const unsigned*)((const char*)(gbase) + (voff)[_i]), (LAS unsigned*)(lds + (bufoff) + ldsw + _i * 8192), 16, 0, 0); } while (0)
; #define G8_LDA(dst, b, h) do { _Pragma("unroll") for (int m = 0; m < 4; ++m) _Pragma("unroll") for (int k = 0; k < 2; ++k) dst[m][k] = *(const LAS bf16x8*)(lds + G8_SA(b, h) + aoff + m * 2048 + k * 1024); } while (0)
; #define G8_LDB(dst, b, h) do { _Pragma("unroll") for (int n = 0; n < 2; ++n) _Pragma("unroll") for (int k = 0; k < 2; ++k) dst[n][k] = *(const LAS bf16x8*)(lds + G8_SB(b, h) + boff + n * 2048 + k * 1024); } while (0)
; #define G8_MMA(ai, bj, At, Bt) do { __builtin_amdgcn_s_setprio(1); _Pragma("unroll") for (int m = 0; m < 4; ++m) _Pragma("unroll") for (int n = 0; n < 2; ++n) _Pragma("unroll") for (int k = 0; k < 2; ++k) \
;         acc[ai][bj][m][n] = __builtin_amdgcn_mfma_f32_16x16x32_bf16(Bt[n][k], At[m][k], acc[ai][bj][m][n], 0, 0, 0); __builtin_amdgcn_s_setprio(0); } while (0)
; #define G8_WAIT_V(n) asm volatile("s_waitcnt vmcnt(" #n ")" ::: "memory")
; #define G8_WAIT_L(n) asm volatile("s_waitcnt lgkmcnt(" #n ")" ::: "memory")
; #define G8_BAR __builtin_amdgcn_s_barrier()
; #define G8_SCHED __builtin_amdgcn_sched_barrier(0)
; template <class Epi, class Sched>
; DEV void gemm_phase(LAS char* lds, const Sched& S, const Epi& E) {
;     ...
;             G8_WAIT_V(8); G8_WAIT_L(0); G8_BAR; G8_MMA(1, 0, At, B0); G8_MMA(1, 1, At, B1); G8_BAR; G8_SCHED;
;             G8_LDB(B0, 1, 0); G8_LDB(B1, 1, 1); G8_SCHED; G8_LDA(At, 1, 0); G8_STAGE(G8_SA(0, 1), a2 + hstepA, voffA);
;             G8_WAIT_V(8); G8_WAIT_L(0); G8_BAR; G8_MMA(0, 0, At, B0); G8_MMA(0, 1, At, B1); G8_BAR; G8_SCHED;
	s_nop 0
	s_waitcnt lgkmcnt(0)
	v_mfma_f32_16x16x32_bf16 v[62:65], v[126:129], v[182:185], v[62:65]
	v_mfma_f32_16x16x32_bf16 v[58:61], v[150:153], v[182:185], v[58:61]
	v_mfma_f32_16x16x32_bf16 v[46:49], v[126:129], v[190:193], v[46:49]
	v_mfma_f32_16x16x32_bf16 v[42:45], v[150:153], v[190:193], v[42:45]
	v_mfma_f32_16x16x32_bf16 v[30:33], v[126:129], v[198:201], v[30:33]
	v_mfma_f32_16x16x32_bf16 v[26:29], v[150:153], v[198:201], v[26:29]
	v_mfma_f32_16x16x32_bf16 v[14:17], v[126:129], v[206:209], v[14:17]
	v_mfma_f32_16x16x32_bf16 v[10:13], v[150:153], v[206:209], v[10:13]
	v_mfma_f32_16x16x32_bf16 v[62:65], v[142:145], v[186:189], v[62:65]
	v_mfma_f32_16x16x32_bf16 v[58:61], v[162:165], v[186:189], v[58:61]
	v_mfma_f32_16x16x32_bf16 v[46:49], v[142:145], v[194:197], v[46:49]
	v_mfma_f32_16x16x32_bf16 v[42:45], v[162:165], v[194:197], v[42:45]
	v_mfma_f32_16x16x32_bf16 v[30:33], v[142:145], v[202:205], v[30:33]
	v_mfma_f32_16x16x32_bf16 v[26:29], v[162:165], v[202:205], v[26:29]
	v_mfma_f32_16x16x32_bf16 v[14:17], v[142:145], v[210:213], v[14:17]
	v_mfma_f32_16x16x32_bf16 v[10:13], v[162:165], v[210:213], v[10:13]
	s_nop 0
	s_nop 0
	v_mfma_f32_16x16x32_bf16 v[54:57], v[166:169], v[182:185], v[54:57]
	v_mfma_f32_16x16x32_bf16 v[50:53], v[174:177], v[182:185], v[50:53]
	v_mfma_f32_16x16x32_bf16 v[38:41], v[166:169], v[190:193], v[38:41]
	v_mfma_f32_16x16x32_bf16 v[34:37], v[174:177], v[190:193], v[34:37]
	v_mfma_f32_16x16x32_bf16 v[22:25], v[166:169], v[198:201], v[22:25]
	v_mfma_f32_16x16x32_bf16 v[18:21], v[174:177], v[198:201], v[18:21]
	v_mfma_f32_16x16x32_bf16 v[6:9], v[166:169], v[206:209], v[6:9]
	v_mfma_f32_16x16x32_bf16 v[2:5], v[174:177], v[206:209], v[2:5]
	v_mfma_f32_16x16x32_bf16 v[54:57], v[170:173], v[186:189], v[54:57]
	v_mfma_f32_16x16x32_bf16 v[50:53], v[178:181], v[186:189], v[50:53]
	v_mfma_f32_16x16x32_bf16 v[38:41], v[170:173], v[194:197], v[38:41]
	v_mfma_f32_16x16x32_bf16 v[34:37], v[178:181], v[194:197], v[34:37]
	v_mfma_f32_16x16x32_bf16 v[22:25], v[170:173], v[202:205], v[22:25]
	v_mfma_f32_16x16x32_bf16 v[18:21], v[178:181], v[202:205], v[18:21]
	v_mfma_f32_16x16x32_bf16 v[6:9], v[170:173], v[210:213], v[6:9]
	v_mfma_f32_16x16x32_bf16 v[2:5], v[178:181], v[210:213], v[2:5]
	s_nop 0
	s_barrier
	ds_read_b128 v[126:129], v119
	ds_read_b128 v[142:145], v119 offset:1024
	ds_read_b128 v[150:153], v119 offset:2048
	ds_read_b128 v[162:165], v119 offset:3072
	ds_read_b128 v[166:169], v120
	ds_read_b128 v[170:173], v120 offset:1024
	ds_read_b128 v[174:177], v120 offset:2048
	ds_read_b128 v[178:181], v120 offset:3072
	s_add_u32 s20, s20, 0x40000
	s_addc_u32 s21, s21, 0
	s_mov_b32 m0, s29
	v_lshl_add_u64 v[216:217], s[20:21], 0, v[98:99]
	ds_read_b128 v[182:185], v118 offset:32768
	ds_read_b128 v[186:189], v118 offset:33792
	ds_read_b128 v[190:193], v118 offset:34816
	ds_read_b128 v[194:197], v118 offset:35840
	ds_read_b128 v[198:201], v118 offset:36864
	ds_read_b128 v[202:205], v118 offset:37888
	ds_read_b128 v[206:209], v118 offset:38912
	ds_read_b128 v[210:213], v118 offset:39936
	global_load_lds_dwordx4 v[216:217], off
	v_lshl_add_u64 v[216:217], s[20:21], 0, v[106:107]
	s_mov_b32 m0, s30
	s_nop 0
	global_load_lds_dwordx4 v[216:217], off
	s_waitcnt vmcnt(8)
	s_waitcnt lgkmcnt(0)
	s_barrier
	s_nop 0
	s_waitcnt lgkmcnt(0)
	v_mfma_f32_16x16x32_bf16 v[158:161], v[126:129], v[182:185], v[158:161]
	v_mfma_f32_16x16x32_bf16 v[154:157], v[150:153], v[182:185], v[154:157]
	v_mfma_f32_16x16x32_bf16 v[134:137], v[126:129], v[190:193], v[134:137]
	v_mfma_f32_16x16x32_bf16 v[130:133], v[150:153], v[190:193], v[130:133]
	v_mfma_f32_16x16x32_bf16 v[94:97], v[126:129], v[198:201], v[94:97]
	v_mfma_f32_16x16x32_bf16 v[90:93], v[150:153], v[198:201], v[90:93]
	v_mfma_f32_16x16x32_bf16 v[78:81], v[126:129], v[206:209], v[78:81]
	v_mfma_f32_16x16x32_bf16 v[74:77], v[150:153], v[206:209], v[74:77]
	v_mfma_f32_16x16x32_bf16 v[158:161], v[142:145], v[186:189], v[158:161]
	v_mfma_f32_16x16x32_bf16 v[154:157], v[162:165], v[186:189], v[154:157]
	v_mfma_f32_16x16x32_bf16 v[134:137], v[142:145], v[194:197], v[134:137]
	v_mfma_f32_16x16x32_bf16 v[130:133], v[162:165], v[194:197], v[130:133]
	v_mfma_f32_16x16x32_bf16 v[94:97], v[142:145], v[202:205], v[94:97]
	v_mfma_f32_16x16x32_bf16 v[90:93], v[162:165], v[202:205], v[90:93]
	v_mfma_f32_16x16x32_bf16 v[78:81], v[142:145], v[210:213], v[78:81]
	v_mfma_f32_16x16x32_bf16 v[74:77], v[162:165], v[210:213], v[74:77]
	s_nop 0
	s_nop 0
	v_mfma_f32_16x16x32_bf16 v[146:149], v[166:169], v[182:185], v[146:149]
	v_mfma_f32_16x16x32_bf16 v[138:141], v[174:177], v[182:185], v[138:141]
	v_mfma_f32_16x16x32_bf16 v[122:125], v[166:169], v[190:193], v[122:125]
	v_mfma_f32_16x16x32_bf16 v[102:105], v[174:177], v[190:193], v[102:105]
	v_mfma_f32_16x16x32_bf16 v[86:89], v[166:169], v[198:201], v[86:89]
	v_mfma_f32_16x16x32_bf16 v[82:85], v[174:177], v[198:201], v[82:85]
	v_mfma_f32_16x16x32_bf16 v[70:73], v[166:169], v[206:209], v[70:73]
	v_mfma_f32_16x16x32_bf16 v[66:69], v[174:177], v[206:209], v[66:69]
	v_mfma_f32_16x16x32_bf16 v[146:149], v[170:173], v[186:189], v[146:149]
	v_mfma_f32_16x16x32_bf16 v[138:141], v[178:181], v[186:189], v[138:141]
	v_mfma_f32_16x16x32_bf16 v[122:125], v[170:173], v[194:197], v[122:125]
	v_mfma_f32_16x16x32_bf16 v[102:105], v[178:181], v[194:197], v[102:105]
	v_mfma_f32_16x16x32_bf16 v[86:89], v[170:173], v[202:205], v[86:89]
	v_mfma_f32_16x16x32_bf16 v[82:85], v[178:181], v[202:205], v[82:85]
	v_mfma_f32_16x16x32_bf16 v[70:73], v[170:173], v[210:213], v[70:73]
	v_mfma_f32_16x16x32_bf16 v[66:69], v[178:181], v[210:213], v[66:69]
	s_nop 0
	s_barrier
; #define G8_STAGE(bufoff, gbase, voff) do { _Pragma("unroll") for (int _i = 0; _i < 2; ++_i) \
;         __builtin_amdgcn_global_load_lds((const unsigned*)((const char*)(gbase) + (voff)[_i]), (LAS unsigned*)(lds + (bufoff) + ldsw + _i * 8192), 16, 0, 0); } while (0)
; #define G8_LDA(dst, b, h) do { _Pragma("unroll") for (int m = 0; m < 4; ++m) _Pragma("unroll") for (int k = 0; k < 2; ++k) dst[m][k] = *(const LAS bf16x8*)(lds + G8_SA(b, h) + aoff + m * 2048 + k * 1024); } while (0)
; #define G8_MMA(ai, bj, At, Bt) do { __builtin_amdgcn_s_setprio(1); _Pragma("unroll") for (int m = 0; m < 4; ++m) _Pragma("unroll") for (int n = 0; n < 2; ++n) _Pragma("unroll") for (int k = 0; k < 2; ++k) \
;         acc[ai][bj][m][n] = __builtin_amdgcn_mfma_f32_16x16x32_bf16(Bt[n][k], At[m][k], acc[ai][bj][m][n], 0, 0, 0); __builtin_amdgcn_s_setprio(0); } while (0)
; #define G8_WAIT_V(n) asm volatile("s_waitcnt vmcnt(" #n ")" ::: "memory")
; #define G8_WAIT_L(n) asm volatile("s_waitcnt lgkmcnt(" #n ")" ::: "memory")
; #define G8_BAR __builtin_amdgcn_s_barrier()
; #define G8_SCHED __builtin_amdgcn_sched_barrier(0)
; template <class Epi, class Sched>
; DEV void gemm_phase(LAS char* lds, const Sched& S, const Epi& E) {
;     ...
;             G8_LDA(At, 1, 1); G8_STAGE(G8_SB(1, 0), b3, voffB); G8_STAGE(G8_SB(1, 1), b3 + hstepB, voffB); G8_STAGE(G8_SA(1, 0), a3, voffA);
;             G8_WAIT_V(8); G8_WAIT_L(0); G8_BAR; G8_MMA(1, 0, At, B0); G8_MMA(1, 1, At, B1); G8_BAR; G8_SCHED;
;         }
;         if (wr == 0) G8_BAR;
	s_mov_b32 m0, s47
	v_lshl_add_u64 v[0:1], v[0:1], 0, s[12:13]
	s_add_u32 s18, s18, 0x40080
	ds_read_b128 v[182:185], v118 offset:49152
	ds_read_b128 v[186:189], v118 offset:50176
	ds_read_b128 v[190:193], v118 offset:51200
	ds_read_b128 v[194:197], v118 offset:52224
	ds_read_b128 v[198:201], v118 offset:53248
	ds_read_b128 v[202:205], v118 offset:54272
	ds_read_b128 v[206:209], v118 offset:55296
	ds_read_b128 v[210:213], v118 offset:56320
	global_load_lds_dwordx4 v[0:1], off
	v_lshl_add_u64 v[0:1], v[214:215], 0, s[12:13]
	s_mov_b32 m0, s52
	s_addc_u32 s19, s19, 0
	global_load_lds_dwordx4 v[0:1], off
	v_lshl_add_u64 v[0:1], s[18:19], 0, v[100:101]
	s_mov_b32 m0, s53
	s_nop 0
	global_load_lds_dwordx4 v[0:1], off
	v_lshl_add_u64 v[0:1], s[18:19], 0, v[108:109]
	s_mov_b32 m0, s54
	s_nop 0
	global_load_lds_dwordx4 v[0:1], off
	v_lshl_add_u64 v[0:1], s[16:17], 0, v[98:99]
	s_mov_b32 m0, s35
	s_nop 0
	global_load_lds_dwordx4 v[0:1], off
	v_lshl_add_u64 v[0:1], s[16:17], 0, v[106:107]
	s_mov_b32 m0, s36
	s_nop 0
	global_load_lds_dwordx4 v[0:1], off
	s_waitcnt vmcnt(8)
	s_waitcnt lgkmcnt(0)
	s_barrier
	s_nop 0
	s_waitcnt lgkmcnt(0)
	v_mfma_f32_16x16x32_bf16 v[62:65], v[126:129], v[182:185], v[62:65]
	v_mfma_f32_16x16x32_bf16 v[58:61], v[150:153], v[182:185], v[58:61]
	v_mfma_f32_16x16x32_bf16 v[46:49], v[126:129], v[190:193], v[46:49]
	v_mfma_f32_16x16x32_bf16 v[42:45], v[150:153], v[190:193], v[42:45]
	v_mfma_f32_16x16x32_bf16 v[30:33], v[126:129], v[198:201], v[30:33]
	v_mfma_f32_16x16x32_bf16 v[26:29], v[150:153], v[198:201], v[26:29]
	v_mfma_f32_16x16x32_bf16 v[14:17], v[126:129], v[206:209], v[14:17]
	v_mfma_f32_16x16x32_bf16 v[10:13], v[150:153], v[206:209], v[10:13]
	v_mfma_f32_16x16x32_bf16 v[62:65], v[142:145], v[186:189], v[62:65]
	v_mfma_f32_16x16x32_bf16 v[58:61], v[162:165], v[186:189], v[58:61]
	v_mfma_f32_16x16x32_bf16 v[46:49], v[142:145], v[194:197], v[46:49]
	v_mfma_f32_16x16x32_bf16 v[42:45], v[162:165], v[194:197], v[42:45]
	v_mfma_f32_16x16x32_bf16 v[30:33], v[142:145], v[202:205], v[30:33]
	v_mfma_f32_16x16x32_bf16 v[26:29], v[162:165], v[202:205], v[26:29]
	v_mfma_f32_16x16x32_bf16 v[14:17], v[142:145], v[210:213], v[14:17]
	v_mfma_f32_16x16x32_bf16 v[10:13], v[162:165], v[210:213], v[10:13]
	s_nop 0
	s_nop 0
	v_mfma_f32_16x16x32_bf16 v[54:57], v[166:169], v[182:185], v[54:57]
	v_mfma_f32_16x16x32_bf16 v[50:53], v[174:177], v[182:185], v[50:53]
	v_mfma_f32_16x16x32_bf16 v[38:41], v[166:169], v[190:193], v[38:41]
	v_mfma_f32_16x16x32_bf16 v[34:37], v[174:177], v[190:193], v[34:37]
	v_mfma_f32_16x16x32_bf16 v[22:25], v[166:169], v[198:201], v[22:25]
	v_mfma_f32_16x16x32_bf16 v[18:21], v[174:177], v[198:201], v[18:21]
	v_mfma_f32_16x16x32_bf16 v[6:9], v[166:169], v[206:209], v[6:9]
	v_mfma_f32_16x16x32_bf16 v[2:5], v[174:177], v[206:209], v[2:5]
	v_mfma_f32_16x16x32_bf16 v[54:57], v[170:173], v[186:189], v[54:57]
	v_mfma_f32_16x16x32_bf16 v[50:53], v[178:181], v[186:189], v[50:53]
	v_mfma_f32_16x16x32_bf16 v[38:41], v[170:173], v[194:197], v[38:41]
	v_mfma_f32_16x16x32_bf16 v[34:37], v[178:181], v[194:197], v[34:37]
	v_mfma_f32_16x16x32_bf16 v[22:25], v[170:173], v[202:205], v[22:25]
	v_mfma_f32_16x16x32_bf16 v[18:21], v[178:181], v[202:205], v[18:21]
	v_mfma_f32_16x16x32_bf16 v[6:9], v[170:173], v[210:213], v[6:9]
	v_mfma_f32_16x16x32_bf16 v[2:5], v[178:181], v[210:213], v[2:5]
	s_nop 0
	s_barrier
	s_add_i32 s39, s39, 2
	s_add_u32 s14, s14, 0x100
	s_addc_u32 s15, s15, 0
	s_cmp_gt_u32 s39, 13
	s_cbranch_scc0 .LBB0_1347
	s_cmpk_lt_u32 s0, 0x100
	s_cbranch_scc0 .LBB0_1350
	s_barrier

; #define G8_STAGE(bufoff, gbase, voff) do { _Pragma("unroll") for (int _i = 0; _i < 2; ++_i) \
;         __builtin_amdgcn_global_load_lds((const unsigned*)((const char*)(gbase) + (voff)[_i]), (LAS unsigned*)(lds + (bufoff) + ldsw + _i * 8192), 16, 0, 0); } while (0)
; #define G8_LDA(dst, b, h) do { _Pragma("unroll") for (int m = 0; m < 4; ++m) _Pragma("unroll") for (int k = 0; k < 2; ++k) dst[m][k] = *(const LAS bf16x8*)(lds + G8_SA(b, h) + aoff + m * 2048 + k * 1024); } while (0)
; #define G8_LDB(dst, b, h) do { _Pragma("unroll") for (int n = 0; n < 2; ++n) _Pragma("unroll") for (int k = 0; k < 2; ++k) dst[n][k] = *(const LAS bf16x8*)(lds + G8_SB(b, h) + boff + n * 2048 + k * 1024); } while (0)
; #define G8_MMA(ai, bj, At, Bt) do { __builtin_amdgcn_s_setprio(1); _Pragma("unroll") for (int m = 0; m < 4; ++m) _Pragma("unroll") for (int n = 0; n < 2; ++n) _Pragma("unroll") for (int k = 0; k < 2; ++k) \
;         acc[ai][bj][m][n] = __builtin_amdgcn_mfma_f32_16x16x32_bf16(Bt[n][k], At[m][k], acc[ai][bj][m][n], 0, 0, 0); __builtin_amdgcn_s_setprio(0); } while (0)
; #define G8_WAIT_V(n) asm volatile("s_waitcnt vmcnt(" #n ")" ::: "memory")
; #define G8_WAIT_L(n) asm volatile("s_waitcnt lgkmcnt(" #n ")" ::: "memory")
; #define G8_BAR __builtin_amdgcn_s_barrier()
; #define G8_SCHED __builtin_amdgcn_sched_barrier(0)
; template <class Epi, class Sched>
; DEV void gemm_phase(LAS char* lds, const Sched& S, const Epi& E) {
;     ...
;         for (int t = 0; t < nt; t += 2) {
;             const bool last = (t == nt - 2);
;             const char* a1 = G8_AK(t + 1);
;             const char* a2 = last ? nA : G8_AK(t + 2); const char* b2 = last ? nB : cB + (size_t)(t + 2) * kstep;
;             const char* a3 = last ? nA + kstepA : G8_AK(t + 3); const char* b3 = b2 + kstep;
;             G8_LDB(B0, 0, 0); G8_LDB(B1, 0, 1); G8_SCHED; G8_LDA(At, 0, 0); G8_STAGE(G8_SA(1, 1), a1 + hstepA, voffA);
;             G8_WAIT_V(8); G8_WAIT_L(0); G8_BAR; G8_MMA(0, 0, At, B0); G8_MMA(0, 1, At, B1); G8_BAR; G8_SCHED;
;             G8_LDA(At, 0, 1); G8_STAGE(G8_SB(0, 0), b2, voffB); G8_STAGE(G8_SB(0, 1), b2 + hstepB, voffB); G8_STAGE(G8_SA(0, 0), a2, voffA);
.LBB0_1373:
	s_add_u32 s13, s24, s34
	s_addc_u32 s15, s25, s35
	s_add_u32 s17, s13, 0x100
	s_addc_u32 s36, s15, 0
	s_add_u32 s34, s26, s34
	s_addc_u32 s35, s27, s35
	s_add_u32 s34, s34, 0x100
	s_addc_u32 s35, s35, 0
	s_add_u32 s37, s13, 0x180
	s_addc_u32 s38, s15, 0
	s_and_b64 s[30:31], s[30:31], exec
	s_cselect_b32 s30, s0, s37
	s_cselect_b32 s31, s1, s38
	s_cselect_b32 s41, s23, s35
	s_cselect_b32 s40, s22, s34
	s_cselect_b32 s39, s19, s36
	s_cselect_b32 s38, s18, s17
	s_add_u32 s68, s13, 0x40080
	ds_read_b128 v[144:147], v151
	ds_read_b128 v[156:159], v151 offset:1024
	ds_read_b128 v[160:163], v151 offset:2048
	ds_read_b128 v[164:167], v151 offset:3072
	ds_read_b128 v[168:171], v152
	ds_read_b128 v[172:175], v152 offset:1024
	ds_read_b128 v[176:179], v152 offset:2048
	ds_read_b128 v[180:183], v152 offset:3072
	s_addc_u32 s69, s15, 0
	s_add_i32 s77, s62, s54
	s_add_i32 m0, s55, 0xc000
	s_add_i32 s78, s55, 0xe000
	s_add_i32 s72, s77, 0x2000
	s_add_u32 s42, s40, 0x10000
	s_addc_u32 s43, s41, 0
	s_add_i32 s76, s63, s54
	s_add_i32 s73, s76, 0x2000
	s_add_u32 s36, s38, 0x40000
	s_addc_u32 s37, s39, 0
	s_add_i32 s58, s50, s54
	s_add_i32 s15, s58, 0x2000
	s_add_u32 s34, s40, 0x10080
	s_addc_u32 s35, s41, 0
	s_add_i32 s17, s51, s54
	s_add_i32 s13, s17, 0x2000
	v_lshl_add_u64 v[0:1], s[68:69], 0, v[130:131]
	ds_read_b128 v[184:187], v153
	ds_read_b128 v[188:191], v153 offset:1024
	ds_read_b128 v[192:195], v153 offset:2048
	ds_read_b128 v[196:199], v153 offset:3072
	ds_read_b128 v[200:203], v153 offset:4096
	ds_read_b128 v[204:207], v153 offset:5120
	ds_read_b128 v[208:211], v153 offset:6144
	ds_read_b128 v[212:215], v153 offset:7168
	global_load_lds_dwordx4 v[0:1], off
	v_lshl_add_u64 v[0:1], s[68:69], 0, v[134:135]
	s_mov_b32 m0, s78
	s_nop 0
	global_load_lds_dwordx4 v[0:1], off
	s_waitcnt vmcnt(8)
	s_waitcnt lgkmcnt(0)
	s_barrier
	s_nop 0
	s_waitcnt lgkmcnt(0)
	v_mfma_f32_16x16x32_bf16 v[126:129], v[144:147], v[184:187], v[126:129]
	v_mfma_f32_16x16x32_bf16 v[122:125], v[160:163], v[184:187], v[122:125]
	v_mfma_f32_16x16x32_bf16 v[118:121], v[144:147], v[192:195], v[118:121]
	v_mfma_f32_16x16x32_bf16 v[114:117], v[160:163], v[192:195], v[114:117]
	v_mfma_f32_16x16x32_bf16 v[102:105], v[144:147], v[200:203], v[102:105]
	v_mfma_f32_16x16x32_bf16 v[98:101], v[160:163], v[200:203], v[98:101]
	v_mfma_f32_16x16x32_bf16 v[86:89], v[144:147], v[208:211], v[86:89]
	v_mfma_f32_16x16x32_bf16 v[82:85], v[160:163], v[208:211], v[82:85]
	v_mfma_f32_16x16x32_bf16 v[126:129], v[156:159], v[188:191], v[126:129]
	v_mfma_f32_16x16x32_bf16 v[122:125], v[164:167], v[188:191], v[122:125]
	v_mfma_f32_16x16x32_bf16 v[118:121], v[156:159], v[196:199], v[118:121]
	v_mfma_f32_16x16x32_bf16 v[114:117], v[164:167], v[196:199], v[114:117]
	v_mfma_f32_16x16x32_bf16 v[102:105], v[156:159], v[204:207], v[102:105]
	v_mfma_f32_16x16x32_bf16 v[98:101], v[164:167], v[204:207], v[98:101]
	v_mfma_f32_16x16x32_bf16 v[86:89], v[156:159], v[212:215], v[86:89]
	v_mfma_f32_16x16x32_bf16 v[82:85], v[164:167], v[212:215], v[82:85]
	s_nop 0
	s_nop 0
	v_mfma_f32_16x16x32_bf16 v[110:113], v[168:171], v[184:187], v[110:113]
	v_mfma_f32_16x16x32_bf16 v[106:109], v[176:179], v[184:187], v[106:109]
	v_mfma_f32_16x16x32_bf16 v[94:97], v[168:171], v[192:195], v[94:97]
	v_mfma_f32_16x16x32_bf16 v[90:93], v[176:179], v[192:195], v[90:93]
	v_mfma_f32_16x16x32_bf16 v[78:81], v[168:171], v[200:203], v[78:81]
	v_mfma_f32_16x16x32_bf16 v[74:77], v[176:179], v[200:203], v[74:77]
	v_mfma_f32_16x16x32_bf16 v[70:73], v[168:171], v[208:211], v[70:73]
	v_mfma_f32_16x16x32_bf16 v[66:69], v[176:179], v[208:211], v[66:69]
	v_mfma_f32_16x16x32_bf16 v[110:113], v[172:175], v[188:191], v[110:113]
	v_mfma_f32_16x16x32_bf16 v[106:109], v[180:183], v[188:191], v[106:109]
	v_mfma_f32_16x16x32_bf16 v[94:97], v[172:175], v[196:199], v[94:97]
	v_mfma_f32_16x16x32_bf16 v[90:93], v[180:183], v[196:199], v[90:93]
	v_mfma_f32_16x16x32_bf16 v[78:81], v[172:175], v[204:207], v[78:81]
	v_mfma_f32_16x16x32_bf16 v[74:77], v[180:183], v[204:207], v[74:77]
	v_mfma_f32_16x16x32_bf16 v[70:73], v[172:175], v[212:215], v[70:73]
	v_mfma_f32_16x16x32_bf16 v[66:69], v[180:183], v[212:215], v[66:69]
	s_nop 0
	s_barrier
	s_mov_b32 m0, s77
	v_lshl_add_u64 v[0:1], s[40:41], 0, v[132:133]
	ds_read_b128 v[184:187], v153 offset:16384
	ds_read_b128 v[188:191], v153 offset:17408
	ds_read_b128 v[192:195], v153 offset:18432
	ds_read_b128 v[196:199], v153 offset:19456
	ds_read_b128 v[200:203], v153 offset:20480
	ds_read_b128 v[204:207], v153 offset:21504
	ds_read_b128 v[208:211], v153 offset:22528
	ds_read_b128 v[212:215], v153 offset:23552
	global_load_lds_dwordx4 v[0:1], off
	v_lshl_add_u64 v[216:217], s[40:41], 0, v[136:137]
	s_mov_b32 m0, s72
	v_lshl_add_u64 v[218:219], s[42:43], 0, v[132:133]
	global_load_lds_dwordx4 v[216:217], off
	s_mov_b32 m0, s76
	s_nop 0
	global_load_lds_dwordx4 v[218:219], off
	v_lshl_add_u64 v[218:219], s[42:43], 0, v[136:137]
	s_mov_b32 m0, s73
	s_nop 0
	global_load_lds_dwordx4 v[218:219], off
	v_lshl_add_u64 v[218:219], s[38:39], 0, v[130:131]
	s_mov_b32 m0, s55
	s_nop 0
	global_load_lds_dwordx4 v[218:219], off
	v_lshl_add_u64 v[218:219], s[38:39], 0, v[134:135]
	s_mov_b32 m0, s56
	s_nop 0
	global_load_lds_dwordx4 v[218:219], off
	s_waitcnt vmcnt(8)
	s_waitcnt lgkmcnt(0)
	s_barrier
; #define G8_STAGE(bufoff, gbase, voff) do { _Pragma("unroll") for (int _i = 0; _i < 2; ++_i) \
;         __builtin_amdgcn_global_load_lds((const unsigned*)((const char*)(gbase) + (voff)[_i]), (LAS unsigned*)(lds + (bufoff) + ldsw + _i * 8192), 16, 0, 0); } while (0)
; #define G8_LDA(dst, b, h) do { _Pragma("unroll") for (int m = 0; m < 4; ++m) _Pragma("unroll") for (int k = 0; k < 2; ++k) dst[m][k] = *(const LAS bf16x8*)(lds + G8_SA(b, h) + aoff + m * 2048 + k * 1024); } while (0)
; #define G8_LDB(dst, b, h) do { _Pragma("unroll") for (int n = 0; n < 2; ++n) _Pragma("unroll") for (int k = 0; k < 2; ++k) dst[n][k] = *(const LAS bf16x8*)(lds + G8_SB(b, h) + boff + n * 2048 + k * 1024); } while (0)
; #define G8_MMA(ai, bj, At, Bt) do { __builtin_amdgcn_s_setprio(1); _Pragma("unroll") for (int m = 0; m < 4; ++m) _Pragma("unroll") for (int n = 0; n < 2; ++n) _Pragma("unroll") for (int k = 0; k < 2; ++k) \
;         acc[ai][bj][m][n] = __builtin_amdgcn_mfma_f32_16x16x32_bf16(Bt[n][k], At[m][k], acc[ai][bj][m][n], 0, 0, 0); __builtin_amdgcn_s_setprio(0); } while (0)
; #define G8_WAIT_V(n) asm volatile("s_waitcnt vmcnt(" #n ")" ::: "memory")
; #define G8_WAIT_L(n) asm volatile("s_waitcnt lgkmcnt(" #n ")" ::: "memory")
; #define G8_BAR __builtin_amdgcn_s_barrier()
; #define G8_SCHED __builtin_amdgcn_sched_barrier(0)
; template <class Epi, class Sched>
; DEV void gemm_phase(LAS char* lds, const Sched& S, const Epi& E) {
;     ...
;             G8_WAIT_V(8); G8_WAIT_L(0); G8_BAR; G8_MMA(1, 0, At, B0); G8_MMA(1, 1, At, B1); G8_BAR; G8_SCHED;
;             G8_LDB(B0, 1, 0); G8_LDB(B1, 1, 1); G8_SCHED; G8_LDA(At, 1, 0); G8_STAGE(G8_SA(0, 1), a2 + hstepA, voffA);
;             G8_WAIT_V(8); G8_WAIT_L(0); G8_BAR; G8_MMA(0, 0, At, B0); G8_MMA(0, 1, At, B1); G8_BAR; G8_SCHED;
	s_nop 0
	s_waitcnt lgkmcnt(0)
	v_mfma_f32_16x16x32_bf16 v[62:65], v[144:147], v[184:187], v[62:65]
	v_mfma_f32_16x16x32_bf16 v[58:61], v[160:163], v[184:187], v[58:61]
	v_mfma_f32_16x16x32_bf16 v[54:57], v[144:147], v[192:195], v[54:57]
	v_mfma_f32_16x16x32_bf16 v[46:49], v[160:163], v[192:195], v[46:49]
	v_mfma_f32_16x16x32_bf16 v[38:41], v[144:147], v[200:203], v[38:41]
	v_mfma_f32_16x16x32_bf16 v[30:33], v[160:163], v[200:203], v[30:33]
	v_mfma_f32_16x16x32_bf16 v[22:25], v[144:147], v[208:211], v[22:25]
	v_mfma_f32_16x16x32_bf16 v[14:17], v[160:163], v[208:211], v[14:17]
	v_mfma_f32_16x16x32_bf16 v[62:65], v[156:159], v[188:191], v[62:65]
	v_mfma_f32_16x16x32_bf16 v[58:61], v[164:167], v[188:191], v[58:61]
	v_mfma_f32_16x16x32_bf16 v[54:57], v[156:159], v[196:199], v[54:57]
	v_mfma_f32_16x16x32_bf16 v[46:49], v[164:167], v[196:199], v[46:49]
	v_mfma_f32_16x16x32_bf16 v[38:41], v[156:159], v[204:207], v[38:41]
	v_mfma_f32_16x16x32_bf16 v[30:33], v[164:167], v[204:207], v[30:33]
	v_mfma_f32_16x16x32_bf16 v[22:25], v[156:159], v[212:215], v[22:25]
	v_mfma_f32_16x16x32_bf16 v[14:17], v[164:167], v[212:215], v[14:17]
	s_nop 0
	s_nop 0
	v_mfma_f32_16x16x32_bf16 v[50:53], v[168:171], v[184:187], v[50:53]
	v_mfma_f32_16x16x32_bf16 v[42:45], v[176:179], v[184:187], v[42:45]
	v_mfma_f32_16x16x32_bf16 v[34:37], v[168:171], v[192:195], v[34:37]
	v_mfma_f32_16x16x32_bf16 v[26:29], v[176:179], v[192:195], v[26:29]
	v_mfma_f32_16x16x32_bf16 v[18:21], v[168:171], v[200:203], v[18:21]
	v_mfma_f32_16x16x32_bf16 v[10:13], v[176:179], v[200:203], v[10:13]
	v_mfma_f32_16x16x32_bf16 v[6:9], v[168:171], v[208:211], v[6:9]
	v_mfma_f32_16x16x32_bf16 v[2:5], v[176:179], v[208:211], v[2:5]
	v_mfma_f32_16x16x32_bf16 v[50:53], v[172:175], v[188:191], v[50:53]
	v_mfma_f32_16x16x32_bf16 v[42:45], v[180:183], v[188:191], v[42:45]
	v_mfma_f32_16x16x32_bf16 v[34:37], v[172:175], v[196:199], v[34:37]
	v_mfma_f32_16x16x32_bf16 v[26:29], v[180:183], v[196:199], v[26:29]
	v_mfma_f32_16x16x32_bf16 v[18:21], v[172:175], v[204:207], v[18:21]
	v_mfma_f32_16x16x32_bf16 v[10:13], v[180:183], v[204:207], v[10:13]
	v_mfma_f32_16x16x32_bf16 v[6:9], v[172:175], v[212:215], v[6:9]
	v_mfma_f32_16x16x32_bf16 v[2:5], v[180:183], v[212:215], v[2:5]
	s_nop 0
	s_barrier
	v_add_u32_e32 v138, s50, v149
	ds_read_b128 v[144:147], v138
	ds_read_b128 v[156:159], v138 offset:1024
	ds_read_b128 v[160:163], v138 offset:2048
	ds_read_b128 v[164:167], v138 offset:3072
	v_add_u32_e32 v138, s51, v149
	ds_read_b128 v[168:171], v138
	ds_read_b128 v[172:175], v138 offset:1024
	ds_read_b128 v[176:179], v138 offset:2048
	ds_read_b128 v[180:183], v138 offset:3072
	s_mov_b32 m0, s57
	v_lshl_add_u64 v[218:219], s[36:37], 0, v[130:131]
	ds_read_b128 v[184:187], v153 offset:32768
	ds_read_b128 v[188:191], v153 offset:33792
	ds_read_b128 v[192:195], v153 offset:34816
	ds_read_b128 v[196:199], v153 offset:35840
	ds_read_b128 v[200:203], v153 offset:36864
	ds_read_b128 v[204:207], v153 offset:37888
	ds_read_b128 v[208:211], v153 offset:38912
	ds_read_b128 v[212:215], v153 offset:39936
	global_load_lds_dwordx4 v[218:219], off
	v_lshl_add_u64 v[218:219], s[36:37], 0, v[134:135]
	s_mov_b32 m0, s59
	s_nop 0
	global_load_lds_dwordx4 v[218:219], off
	s_waitcnt vmcnt(8)
	s_waitcnt lgkmcnt(0)
	s_barrier
	s_nop 0
	s_waitcnt lgkmcnt(0)
	v_mfma_f32_16x16x32_bf16 v[126:129], v[144:147], v[184:187], v[126:129]
	v_mfma_f32_16x16x32_bf16 v[122:125], v[160:163], v[184:187], v[122:125]
	v_mfma_f32_16x16x32_bf16 v[118:121], v[144:147], v[192:195], v[118:121]
	v_mfma_f32_16x16x32_bf16 v[114:117], v[160:163], v[192:195], v[114:117]
	v_mfma_f32_16x16x32_bf16 v[102:105], v[144:147], v[200:203], v[102:105]
	v_mfma_f32_16x16x32_bf16 v[98:101], v[160:163], v[200:203], v[98:101]
	v_mfma_f32_16x16x32_bf16 v[86:89], v[144:147], v[208:211], v[86:89]
	v_mfma_f32_16x16x32_bf16 v[82:85], v[160:163], v[208:211], v[82:85]
	v_mfma_f32_16x16x32_bf16 v[126:129], v[156:159], v[188:191], v[126:129]
	v_mfma_f32_16x16x32_bf16 v[122:125], v[164:167], v[188:191], v[122:125]
	v_mfma_f32_16x16x32_bf16 v[118:121], v[156:159], v[196:199], v[118:121]
	v_mfma_f32_16x16x32_bf16 v[114:117], v[164:167], v[196:199], v[114:117]
	v_mfma_f32_16x16x32_bf16 v[102:105], v[156:159], v[204:207], v[102:105]
	v_mfma_f32_16x16x32_bf16 v[98:101], v[164:167], v[204:207], v[98:101]
	v_mfma_f32_16x16x32_bf16 v[86:89], v[156:159], v[212:215], v[86:89]
	v_mfma_f32_16x16x32_bf16 v[82:85], v[164:167], v[212:215], v[82:85]
	s_nop 0
	s_nop 0
	v_mfma_f32_16x16x32_bf16 v[110:113], v[168:171], v[184:187], v[110:113]
	v_mfma_f32_16x16x32_bf16 v[106:109], v[176:179], v[184:187], v[106:109]
	v_mfma_f32_16x16x32_bf16 v[94:97], v[168:171], v[192:195], v[94:97]
	v_mfma_f32_16x16x32_bf16 v[90:93], v[176:179], v[192:195], v[90:93]
	v_mfma_f32_16x16x32_bf16 v[78:81], v[168:171], v[200:203], v[78:81]
	v_mfma_f32_16x16x32_bf16 v[74:77], v[176:179], v[200:203], v[74:77]
	v_mfma_f32_16x16x32_bf16 v[70:73], v[168:171], v[208:211], v[70:73]
	v_mfma_f32_16x16x32_bf16 v[66:69], v[176:179], v[208:211], v[66:69]
	v_mfma_f32_16x16x32_bf16 v[110:113], v[172:175], v[188:191], v[110:113]
	v_mfma_f32_16x16x32_bf16 v[106:109], v[180:183], v[188:191], v[106:109]
	v_mfma_f32_16x16x32_bf16 v[94:97], v[172:175], v[196:199], v[94:97]
	v_mfma_f32_16x16x32_bf16 v[90:93], v[180:183], v[196:199], v[90:93]
	v_mfma_f32_16x16x32_bf16 v[78:81], v[172:175], v[204:207], v[78:81]
	v_mfma_f32_16x16x32_bf16 v[74:77], v[180:183], v[204:207], v[74:77]
	v_mfma_f32_16x16x32_bf16 v[70:73], v[172:175], v[212:215], v[70:73]
	v_mfma_f32_16x16x32_bf16 v[66:69], v[180:183], v[212:215], v[66:69]
	s_nop 0
	s_barrier
; #define G8_STAGE(bufoff, gbase, voff) do { _Pragma("unroll") for (int _i = 0; _i < 2; ++_i) \
;         __builtin_amdgcn_global_load_lds((const unsigned*)((const char*)(gbase) + (voff)[_i]), (LAS unsigned*)(lds + (bufoff) + ldsw + _i * 8192), 16, 0, 0); } while (0)
; #define G8_LDA(dst, b, h) do { _Pragma("unroll") for (int m = 0; m < 4; ++m) _Pragma("unroll") for (int k = 0; k < 2; ++k) dst[m][k] = *(const LAS bf16x8*)(lds + G8_SA(b, h) + aoff + m * 2048 + k * 1024); } while (0)
; #define G8_MMA(ai, bj, At, Bt) do { __builtin_amdgcn_s_setprio(1); _Pragma("unroll") for (int m = 0; m < 4; ++m) _Pragma("unroll") for (int n = 0; n < 2; ++n) _Pragma("unroll") for (int k = 0; k < 2; ++k) \
;         acc[ai][bj][m][n] = __builtin_amdgcn_mfma_f32_16x16x32_bf16(Bt[n][k], At[m][k], acc[ai][bj][m][n], 0, 0, 0); __builtin_amdgcn_s_setprio(0); } while (0)
; #define G8_WAIT_V(n) asm volatile("s_waitcnt vmcnt(" #n ")" ::: "memory")
; #define G8_WAIT_L(n) asm volatile("s_waitcnt lgkmcnt(" #n ")" ::: "memory")
; #define G8_BAR __builtin_amdgcn_s_barrier()
; #define G8_SCHED __builtin_amdgcn_sched_barrier(0)
; template <class Epi, class Sched>
; DEV void gemm_phase(LAS char* lds, const Sched& S, const Epi& E) {
;     ...
;             G8_LDA(At, 1, 1); G8_STAGE(G8_SB(1, 0), b3, voffB); G8_STAGE(G8_SB(1, 1), b3 + hstepB, voffB); G8_STAGE(G8_SA(1, 0), a3, voffA);
;             G8_WAIT_V(8); G8_WAIT_L(0); G8_BAR; G8_MMA(1, 0, At, B0); G8_MMA(1, 1, At, B1); G8_BAR; G8_SCHED;
;         }
;         if (wr == 0) G8_BAR;
;         E(lds, acc, cur, wr, wc, fr, fq, wid, lane);
;         if (!has_next) break;
	s_mov_b32 m0, s58
	v_lshl_add_u64 v[0:1], v[0:1], 0, s[6:7]
	ds_read_b128 v[184:187], v153 offset:49152
	ds_read_b128 v[188:191], v153 offset:50176
	ds_read_b128 v[192:195], v153 offset:51200
	ds_read_b128 v[196:199], v153 offset:52224
	ds_read_b128 v[200:203], v153 offset:53248
	ds_read_b128 v[204:207], v153 offset:54272
	ds_read_b128 v[208:211], v153 offset:55296
	ds_read_b128 v[212:215], v153 offset:56320
	global_load_lds_dwordx4 v[0:1], off
	v_lshl_add_u64 v[0:1], v[216:217], 0, s[6:7]
	s_mov_b32 m0, s15
	s_nop 0
	global_load_lds_dwordx4 v[0:1], off
	v_lshl_add_u64 v[0:1], s[34:35], 0, v[132:133]
	s_mov_b32 m0, s17
	s_nop 0
	global_load_lds_dwordx4 v[0:1], off
	v_lshl_add_u64 v[0:1], s[34:35], 0, v[136:137]
	s_mov_b32 m0, s13
	s_nop 0
	global_load_lds_dwordx4 v[0:1], off
	v_lshl_add_u64 v[0:1], s[30:31], 0, v[130:131]
	s_mov_b32 m0, s52
	s_nop 0
	global_load_lds_dwordx4 v[0:1], off
	v_lshl_add_u64 v[0:1], s[30:31], 0, v[134:135]
	s_mov_b32 m0, s70
	s_nop 0
	global_load_lds_dwordx4 v[0:1], off
	s_waitcnt vmcnt(8)
	s_waitcnt lgkmcnt(0)
	s_barrier
	s_nop 0
	s_waitcnt lgkmcnt(0)
	v_mfma_f32_16x16x32_bf16 v[62:65], v[144:147], v[184:187], v[62:65]
	v_mfma_f32_16x16x32_bf16 v[58:61], v[160:163], v[184:187], v[58:61]
	v_mfma_f32_16x16x32_bf16 v[54:57], v[144:147], v[192:195], v[54:57]
	v_mfma_f32_16x16x32_bf16 v[46:49], v[160:163], v[192:195], v[46:49]
	v_mfma_f32_16x16x32_bf16 v[38:41], v[144:147], v[200:203], v[38:41]
	v_mfma_f32_16x16x32_bf16 v[30:33], v[160:163], v[200:203], v[30:33]
	v_mfma_f32_16x16x32_bf16 v[22:25], v[144:147], v[208:211], v[22:25]
	v_mfma_f32_16x16x32_bf16 v[14:17], v[160:163], v[208:211], v[14:17]
	v_mfma_f32_16x16x32_bf16 v[62:65], v[156:159], v[188:191], v[62:65]
	v_mfma_f32_16x16x32_bf16 v[58:61], v[164:167], v[188:191], v[58:61]
	v_mfma_f32_16x16x32_bf16 v[54:57], v[156:159], v[196:199], v[54:57]
	v_mfma_f32_16x16x32_bf16 v[46:49], v[164:167], v[196:199], v[46:49]
	v_mfma_f32_16x16x32_bf16 v[38:41], v[156:159], v[204:207], v[38:41]
	v_mfma_f32_16x16x32_bf16 v[30:33], v[164:167], v[204:207], v[30:33]
	v_mfma_f32_16x16x32_bf16 v[22:25], v[156:159], v[212:215], v[22:25]
	v_mfma_f32_16x16x32_bf16 v[14:17], v[164:167], v[212:215], v[14:17]
	s_nop 0
	s_nop 0
	v_mfma_f32_16x16x32_bf16 v[50:53], v[168:171], v[184:187], v[50:53]
	v_mfma_f32_16x16x32_bf16 v[42:45], v[176:179], v[184:187], v[42:45]
	v_mfma_f32_16x16x32_bf16 v[34:37], v[168:171], v[192:195], v[34:37]
	v_mfma_f32_16x16x32_bf16 v[26:29], v[176:179], v[192:195], v[26:29]
	v_mfma_f32_16x16x32_bf16 v[18:21], v[168:171], v[200:203], v[18:21]
	v_mfma_f32_16x16x32_bf16 v[10:13], v[176:179], v[200:203], v[10:13]
	v_mfma_f32_16x16x32_bf16 v[6:9], v[168:171], v[208:211], v[6:9]
	v_mfma_f32_16x16x32_bf16 v[2:5], v[176:179], v[208:211], v[2:5]
	v_mfma_f32_16x16x32_bf16 v[50:53], v[172:175], v[188:191], v[50:53]
	v_mfma_f32_16x16x32_bf16 v[42:45], v[180:183], v[188:191], v[42:45]
	v_mfma_f32_16x16x32_bf16 v[34:37], v[172:175], v[196:199], v[34:37]
	v_mfma_f32_16x16x32_bf16 v[26:29], v[180:183], v[196:199], v[26:29]
	v_mfma_f32_16x16x32_bf16 v[18:21], v[172:175], v[204:207], v[18:21]
	v_mfma_f32_16x16x32_bf16 v[10:13], v[180:183], v[204:207], v[10:13]
	v_mfma_f32_16x16x32_bf16 v[6:9], v[172:175], v[212:215], v[6:9]
	v_mfma_f32_16x16x32_bf16 v[2:5], v[180:183], v[212:215], v[2:5]
	s_nop 0
	s_barrier
	s_andn2_b64 vcc, exec, s[28:29]
	s_mov_b64 s[30:31], -1
	s_mov_b64 s[28:29], 0
	s_mov_b64 s[34:35], 0x100
	s_cbranch_vccz .LBB0_1373
	s_and_b64 vcc, exec, s[10:11]
	s_cbranch_vccnz .LBB0_1378
	s_cmp_gt_u32 s64, 3
	s_mov_b64 s[0:1], -1
	s_cbranch_scc1 .LBB0_1379

; #define G8_STAGE(bufoff, gbase, voff) do { _Pragma("unroll") for (int _i = 0; _i < 2; ++_i) \
;         __builtin_amdgcn_global_load_lds((const unsigned*)((const char*)(gbase) + (voff)[_i]), (LAS unsigned*)(lds + (bufoff) + ldsw + _i * 8192), 16, 0, 0); } while (0)
; #define G8_LDA(dst, b, h) do { _Pragma("unroll") for (int m = 0; m < 4; ++m) _Pragma("unroll") for (int k = 0; k < 2; ++k) dst[m][k] = *(const LAS bf16x8*)(lds + G8_SA(b, h) + aoff + m * 2048 + k * 1024); } while (0)
; #define G8_LDB(dst, b, h) do { _Pragma("unroll") for (int n = 0; n < 2; ++n) _Pragma("unroll") for (int k = 0; k < 2; ++k) dst[n][k] = *(const LAS bf16x8*)(lds + G8_SB(b, h) + boff + n * 2048 + k * 1024); } while (0)
; #define G8_MMA(ai, bj, At, Bt) do { __builtin_amdgcn_s_setprio(1); _Pragma("unroll") for (int m = 0; m < 4; ++m) _Pragma("unroll") for (int n = 0; n < 2; ++n) _Pragma("unroll") for (int k = 0; k < 2; ++k) \
;         acc[ai][bj][m][n] = __builtin_amdgcn_mfma_f32_16x16x32_bf16(Bt[n][k], At[m][k], acc[ai][bj][m][n], 0, 0, 0); __builtin_amdgcn_s_setprio(0); } while (0)
; #define G8_WAIT_V(n) asm volatile("s_waitcnt vmcnt(" #n ")" ::: "memory")
; #define G8_WAIT_L(n) asm volatile("s_waitcnt lgkmcnt(" #n ")" ::: "memory")
; #define G8_BAR __builtin_amdgcn_s_barrier()
; #define G8_SCHED __builtin_amdgcn_sched_barrier(0)
; template <class Epi, class Sched>
; DEV void gemm_phase(LAS char* lds, const Sched& S, const Epi& E) {
;     ...
;         for (int t = 0; t < nt; t += 2) {
;             const bool last = (t == nt - 2);
;             const char* a1 = G8_AK(t + 1);
;             const char* a2 = last ? nA : G8_AK(t + 2); const char* b2 = last ? nB : cB + (size_t)(t + 2) * kstep;
;             const char* a3 = last ? nA + kstepA : G8_AK(t + 3); const char* b3 = b2 + kstep;
;             G8_LDB(B0, 0, 0); G8_LDB(B1, 0, 1); G8_SCHED; G8_LDA(At, 0, 0); G8_STAGE(G8_SA(1, 1), a1 + hstepA, voffA);
;             G8_WAIT_V(8); G8_WAIT_L(0); G8_BAR; G8_MMA(0, 0, At, B0); G8_MMA(0, 1, At, B1); G8_BAR; G8_SCHED;
;             G8_LDA(At, 0, 1); G8_STAGE(G8_SB(0, 0), b2, voffB); G8_STAGE(G8_SB(0, 1), b2 + hstepB, voffB); G8_STAGE(G8_SA(0, 0), a2, voffA);
.LBB0_1565:
	ds_read_b128 v[146:149], v206
	ds_read_b128 v[150:153], v206 offset:1024
	ds_read_b128 v[154:157], v206 offset:2048
	ds_read_b128 v[158:161], v206 offset:3072
	ds_read_b128 v[162:165], v207
	ds_read_b128 v[166:169], v207 offset:1024
	ds_read_b128 v[170:173], v207 offset:2048
	ds_read_b128 v[174:177], v207 offset:3072
	s_add_u32 s42, s6, s40
	s_addc_u32 s43, s7, s41
	s_add_u32 s55, s42, 0x100
	s_addc_u32 s58, s43, 0
	s_add_u32 s56, s52, s40
	s_addc_u32 s57, s53, s41
	s_add_u32 s42, s42, 0x180
	s_addc_u32 s43, s43, 0
	s_cmpk_eq_i32 s40, 0x700
	s_cselect_b32 s43, s31, s43
	s_cselect_b32 s42, s24, s42
	s_cselect_b32 s57, s37, s57
	s_cselect_b32 s56, s36, s56
	s_cselect_b32 s65, s35, s58
	s_cselect_b32 s64, s34, s55
	v_lshl_add_u64 v[0:1], v[144:145], 0, s[40:41]
	s_add_i32 m0, s47, 0xc000
	ds_read_b128 v[178:181], v208
	ds_read_b128 v[182:185], v208 offset:1024
	ds_read_b128 v[186:189], v208 offset:2048
	ds_read_b128 v[190:193], v208 offset:3072
	ds_read_b128 v[194:197], v208 offset:4096
	ds_read_b128 v[198:201], v208 offset:5120
	ds_read_b128 v[214:217], v208 offset:6144
	ds_read_b128 v[218:221], v208 offset:7168
	global_load_lds_dwordx4 v[0:1], off
	v_lshl_add_u64 v[0:1], v[142:143], 0, s[40:41]
	s_add_i32 m0, s47, 0xe000
	s_nop 0
	global_load_lds_dwordx4 v[0:1], off
	s_waitcnt vmcnt(8)
	s_waitcnt lgkmcnt(0)
	s_barrier
	s_nop 0
	s_waitcnt lgkmcnt(0)
	v_mfma_f32_16x16x32_bf16 v[126:129], v[146:149], v[178:181], v[126:129]
	v_mfma_f32_16x16x32_bf16 v[122:125], v[154:157], v[178:181], v[122:125]
	v_mfma_f32_16x16x32_bf16 v[118:121], v[146:149], v[186:189], v[118:121]
	v_mfma_f32_16x16x32_bf16 v[114:117], v[154:157], v[186:189], v[114:117]
	v_mfma_f32_16x16x32_bf16 v[110:113], v[146:149], v[194:197], v[110:113]
	v_mfma_f32_16x16x32_bf16 v[106:109], v[154:157], v[194:197], v[106:109]
	v_mfma_f32_16x16x32_bf16 v[102:105], v[146:149], v[214:217], v[102:105]
	v_mfma_f32_16x16x32_bf16 v[98:101], v[154:157], v[214:217], v[98:101]
	v_mfma_f32_16x16x32_bf16 v[126:129], v[150:153], v[182:185], v[126:129]
	v_mfma_f32_16x16x32_bf16 v[122:125], v[158:161], v[182:185], v[122:125]
	v_mfma_f32_16x16x32_bf16 v[118:121], v[150:153], v[190:193], v[118:121]
	v_mfma_f32_16x16x32_bf16 v[114:117], v[158:161], v[190:193], v[114:117]
	v_mfma_f32_16x16x32_bf16 v[110:113], v[150:153], v[198:201], v[110:113]
	v_mfma_f32_16x16x32_bf16 v[106:109], v[158:161], v[198:201], v[106:109]
	v_mfma_f32_16x16x32_bf16 v[102:105], v[150:153], v[218:221], v[102:105]
	v_mfma_f32_16x16x32_bf16 v[98:101], v[158:161], v[218:221], v[98:101]
	s_nop 0
	s_nop 0
	v_mfma_f32_16x16x32_bf16 v[62:65], v[162:165], v[178:181], v[62:65]
	v_mfma_f32_16x16x32_bf16 v[58:61], v[170:173], v[178:181], v[58:61]
	v_mfma_f32_16x16x32_bf16 v[54:57], v[162:165], v[186:189], v[54:57]
	v_mfma_f32_16x16x32_bf16 v[50:53], v[170:173], v[186:189], v[50:53]
	v_mfma_f32_16x16x32_bf16 v[46:49], v[162:165], v[194:197], v[46:49]
	v_mfma_f32_16x16x32_bf16 v[42:45], v[170:173], v[194:197], v[42:45]
	v_mfma_f32_16x16x32_bf16 v[38:41], v[162:165], v[214:217], v[38:41]
	v_mfma_f32_16x16x32_bf16 v[34:37], v[170:173], v[214:217], v[34:37]
	v_mfma_f32_16x16x32_bf16 v[62:65], v[166:169], v[182:185], v[62:65]
	v_mfma_f32_16x16x32_bf16 v[58:61], v[174:177], v[182:185], v[58:61]
	v_mfma_f32_16x16x32_bf16 v[54:57], v[166:169], v[190:193], v[54:57]
	v_mfma_f32_16x16x32_bf16 v[50:53], v[174:177], v[190:193], v[50:53]
	v_mfma_f32_16x16x32_bf16 v[46:49], v[166:169], v[198:201], v[46:49]
	v_mfma_f32_16x16x32_bf16 v[42:45], v[174:177], v[198:201], v[42:45]
	v_mfma_f32_16x16x32_bf16 v[38:41], v[166:169], v[218:221], v[38:41]
	v_mfma_f32_16x16x32_bf16 v[34:37], v[174:177], v[218:221], v[34:37]
	s_nop 0
	s_barrier
	s_add_i32 s55, s62, s46
	v_lshl_add_u64 v[0:1], s[56:57], 0, v[132:133]
	s_mov_b32 m0, s55
	ds_read_b128 v[178:181], v208 offset:16384
	ds_read_b128 v[182:185], v208 offset:17408
	ds_read_b128 v[186:189], v208 offset:18432
	ds_read_b128 v[190:193], v208 offset:19456
	ds_read_b128 v[194:197], v208 offset:20480
	ds_read_b128 v[198:201], v208 offset:21504
	ds_read_b128 v[214:217], v208 offset:22528
	ds_read_b128 v[218:221], v208 offset:23552
	global_load_lds_dwordx4 v[0:1], off
	s_add_i32 m0, s55, 0x2000
	s_add_u32 s66, s56, 0x200000
	v_lshl_add_u64 v[222:223], s[56:57], 0, v[136:137]
	s_addc_u32 s67, s57, 0
	s_add_i32 s55, s63, s46
	global_load_lds_dwordx4 v[222:223], off
	v_lshl_add_u64 v[224:225], s[66:67], 0, v[132:133]
	s_mov_b32 m0, s55
	s_nop 0
	global_load_lds_dwordx4 v[224:225], off
	v_lshl_add_u64 v[224:225], s[66:67], 0, v[136:137]
	s_add_i32 m0, s55, 0x2000
	s_nop 0
	global_load_lds_dwordx4 v[224:225], off
	v_lshl_add_u64 v[224:225], s[64:65], 0, v[130:131]
	s_mov_b32 m0, s47
	s_nop 0
	global_load_lds_dwordx4 v[224:225], off
	v_lshl_add_u64 v[224:225], s[64:65], 0, v[134:135]
	s_mov_b32 m0, s59
	s_nop 0
	global_load_lds_dwordx4 v[224:225], off
	s_waitcnt vmcnt(8)
	s_waitcnt lgkmcnt(0)
	s_barrier
; #define G8_STAGE(bufoff, gbase, voff) do { _Pragma("unroll") for (int _i = 0; _i < 2; ++_i) \
;         __builtin_amdgcn_global_load_lds((const unsigned*)((const char*)(gbase) + (voff)[_i]), (LAS unsigned*)(lds + (bufoff) + ldsw + _i * 8192), 16, 0, 0); } while (0)
; #define G8_LDA(dst, b, h) do { _Pragma("unroll") for (int m = 0; m < 4; ++m) _Pragma("unroll") for (int k = 0; k < 2; ++k) dst[m][k] = *(const LAS bf16x8*)(lds + G8_SA(b, h) + aoff + m * 2048 + k * 1024); } while (0)
; #define G8_LDB(dst, b, h) do { _Pragma("unroll") for (int n = 0; n < 2; ++n) _Pragma("unroll") for (int k = 0; k < 2; ++k) dst[n][k] = *(const LAS bf16x8*)(lds + G8_SB(b, h) + boff + n * 2048 + k * 1024); } while (0)
; #define G8_MMA(ai, bj, At, Bt) do { __builtin_amdgcn_s_setprio(1); _Pragma("unroll") for (int m = 0; m < 4; ++m) _Pragma("unroll") for (int n = 0; n < 2; ++n) _Pragma("unroll") for (int k = 0; k < 2; ++k) \
;         acc[ai][bj][m][n] = __builtin_amdgcn_mfma_f32_16x16x32_bf16(Bt[n][k], At[m][k], acc[ai][bj][m][n], 0, 0, 0); __builtin_amdgcn_s_setprio(0); } while (0)
; #define G8_WAIT_V(n) asm volatile("s_waitcnt vmcnt(" #n ")" ::: "memory")
; #define G8_WAIT_L(n) asm volatile("s_waitcnt lgkmcnt(" #n ")" ::: "memory")
; #define G8_BAR __builtin_amdgcn_s_barrier()
; #define G8_SCHED __builtin_amdgcn_sched_barrier(0)
; template <class Epi, class Sched>
; DEV void gemm_phase(LAS char* lds, const Sched& S, const Epi& E) {
;     ...
;             G8_WAIT_V(8); G8_WAIT_L(0); G8_BAR; G8_MMA(1, 0, At, B0); G8_MMA(1, 1, At, B1); G8_BAR; G8_SCHED;
;             G8_LDB(B0, 1, 0); G8_LDB(B1, 1, 1); G8_SCHED; G8_LDA(At, 1, 0); G8_STAGE(G8_SA(0, 1), a2 + hstepA, voffA);
;             G8_WAIT_V(8); G8_WAIT_L(0); G8_BAR; G8_MMA(0, 0, At, B0); G8_MMA(0, 1, At, B1); G8_BAR; G8_SCHED;
	s_nop 0
	s_waitcnt lgkmcnt(0)
	v_mfma_f32_16x16x32_bf16 v[94:97], v[146:149], v[178:181], v[94:97]
	v_mfma_f32_16x16x32_bf16 v[90:93], v[154:157], v[178:181], v[90:93]
	v_mfma_f32_16x16x32_bf16 v[86:89], v[146:149], v[186:189], v[86:89]
	v_mfma_f32_16x16x32_bf16 v[82:85], v[154:157], v[186:189], v[82:85]
	v_mfma_f32_16x16x32_bf16 v[78:81], v[146:149], v[194:197], v[78:81]
	v_mfma_f32_16x16x32_bf16 v[74:77], v[154:157], v[194:197], v[74:77]
	v_mfma_f32_16x16x32_bf16 v[70:73], v[146:149], v[214:217], v[70:73]
	v_mfma_f32_16x16x32_bf16 v[66:69], v[154:157], v[214:217], v[66:69]
	v_mfma_f32_16x16x32_bf16 v[94:97], v[150:153], v[182:185], v[94:97]
	v_mfma_f32_16x16x32_bf16 v[90:93], v[158:161], v[182:185], v[90:93]
	v_mfma_f32_16x16x32_bf16 v[86:89], v[150:153], v[190:193], v[86:89]
	v_mfma_f32_16x16x32_bf16 v[82:85], v[158:161], v[190:193], v[82:85]
	v_mfma_f32_16x16x32_bf16 v[78:81], v[150:153], v[198:201], v[78:81]
	v_mfma_f32_16x16x32_bf16 v[74:77], v[158:161], v[198:201], v[74:77]
	v_mfma_f32_16x16x32_bf16 v[70:73], v[150:153], v[218:221], v[70:73]
	v_mfma_f32_16x16x32_bf16 v[66:69], v[158:161], v[218:221], v[66:69]
	s_nop 0
	s_nop 0
	v_mfma_f32_16x16x32_bf16 v[30:33], v[162:165], v[178:181], v[30:33]
	v_mfma_f32_16x16x32_bf16 v[26:29], v[170:173], v[178:181], v[26:29]
	v_mfma_f32_16x16x32_bf16 v[22:25], v[162:165], v[186:189], v[22:25]
	v_mfma_f32_16x16x32_bf16 v[18:21], v[170:173], v[186:189], v[18:21]
	v_mfma_f32_16x16x32_bf16 v[14:17], v[162:165], v[194:197], v[14:17]
	v_mfma_f32_16x16x32_bf16 v[10:13], v[170:173], v[194:197], v[10:13]
	v_mfma_f32_16x16x32_bf16 v[6:9], v[162:165], v[214:217], v[6:9]
	v_mfma_f32_16x16x32_bf16 v[2:5], v[170:173], v[214:217], v[2:5]
	v_mfma_f32_16x16x32_bf16 v[30:33], v[166:169], v[182:185], v[30:33]
	v_mfma_f32_16x16x32_bf16 v[26:29], v[174:177], v[182:185], v[26:29]
	v_mfma_f32_16x16x32_bf16 v[22:25], v[166:169], v[190:193], v[22:25]
	v_mfma_f32_16x16x32_bf16 v[18:21], v[174:177], v[190:193], v[18:21]
	v_mfma_f32_16x16x32_bf16 v[14:17], v[166:169], v[198:201], v[14:17]
	v_mfma_f32_16x16x32_bf16 v[10:13], v[174:177], v[198:201], v[10:13]
	v_mfma_f32_16x16x32_bf16 v[6:9], v[166:169], v[218:221], v[6:9]
	v_mfma_f32_16x16x32_bf16 v[2:5], v[174:177], v[218:221], v[2:5]
	s_nop 0
	s_barrier
	v_add_u32_e32 v158, s50, v204
	v_add_u32_e32 v174, s51, v204
	ds_read_b128 v[146:149], v158
	ds_read_b128 v[150:153], v158 offset:1024
	ds_read_b128 v[154:157], v158 offset:2048
	ds_read_b128 v[158:161], v158 offset:3072
	ds_read_b128 v[162:165], v174
	ds_read_b128 v[166:169], v174 offset:1024
	ds_read_b128 v[170:173], v174 offset:2048
	ds_read_b128 v[174:177], v174 offset:3072
	s_add_u32 s64, s64, 0x40000
	s_addc_u32 s65, s65, 0
	s_mov_b32 m0, s60
	v_lshl_add_u64 v[224:225], s[64:65], 0, v[130:131]
	ds_read_b128 v[178:181], v208 offset:32768
	ds_read_b128 v[182:185], v208 offset:33792
	ds_read_b128 v[186:189], v208 offset:34816
	ds_read_b128 v[190:193], v208 offset:35840
	ds_read_b128 v[194:197], v208 offset:36864
	ds_read_b128 v[198:201], v208 offset:37888
	ds_read_b128 v[214:217], v208 offset:38912
	ds_read_b128 v[218:221], v208 offset:39936
	global_load_lds_dwordx4 v[224:225], off
	v_lshl_add_u64 v[224:225], s[64:65], 0, v[134:135]
	s_mov_b32 m0, s61
	s_nop 0
	global_load_lds_dwordx4 v[224:225], off
	s_waitcnt vmcnt(8)
	s_waitcnt lgkmcnt(0)
	s_barrier
	s_nop 0
	s_waitcnt lgkmcnt(0)
	v_mfma_f32_16x16x32_bf16 v[126:129], v[146:149], v[178:181], v[126:129]
	v_mfma_f32_16x16x32_bf16 v[122:125], v[154:157], v[178:181], v[122:125]
	v_mfma_f32_16x16x32_bf16 v[118:121], v[146:149], v[186:189], v[118:121]
	v_mfma_f32_16x16x32_bf16 v[114:117], v[154:157], v[186:189], v[114:117]
	v_mfma_f32_16x16x32_bf16 v[110:113], v[146:149], v[194:197], v[110:113]
	v_mfma_f32_16x16x32_bf16 v[106:109], v[154:157], v[194:197], v[106:109]
	v_mfma_f32_16x16x32_bf16 v[102:105], v[146:149], v[214:217], v[102:105]
	v_mfma_f32_16x16x32_bf16 v[98:101], v[154:157], v[214:217], v[98:101]
	v_mfma_f32_16x16x32_bf16 v[126:129], v[150:153], v[182:185], v[126:129]
	v_mfma_f32_16x16x32_bf16 v[122:125], v[158:161], v[182:185], v[122:125]
	v_mfma_f32_16x16x32_bf16 v[118:121], v[150:153], v[190:193], v[118:121]
	v_mfma_f32_16x16x32_bf16 v[114:117], v[158:161], v[190:193], v[114:117]
	v_mfma_f32_16x16x32_bf16 v[110:113], v[150:153], v[198:201], v[110:113]
	v_mfma_f32_16x16x32_bf16 v[106:109], v[158:161], v[198:201], v[106:109]
	v_mfma_f32_16x16x32_bf16 v[102:105], v[150:153], v[218:221], v[102:105]
	v_mfma_f32_16x16x32_bf16 v[98:101], v[158:161], v[218:221], v[98:101]
	s_nop 0
	s_nop 0
	v_mfma_f32_16x16x32_bf16 v[62:65], v[162:165], v[178:181], v[62:65]
	v_mfma_f32_16x16x32_bf16 v[58:61], v[170:173], v[178:181], v[58:61]
	v_mfma_f32_16x16x32_bf16 v[54:57], v[162:165], v[186:189], v[54:57]
	v_mfma_f32_16x16x32_bf16 v[50:53], v[170:173], v[186:189], v[50:53]
	v_mfma_f32_16x16x32_bf16 v[46:49], v[162:165], v[194:197], v[46:49]
	v_mfma_f32_16x16x32_bf16 v[42:45], v[170:173], v[194:197], v[42:45]
	v_mfma_f32_16x16x32_bf16 v[38:41], v[162:165], v[214:217], v[38:41]
	v_mfma_f32_16x16x32_bf16 v[34:37], v[170:173], v[214:217], v[34:37]
	v_mfma_f32_16x16x32_bf16 v[62:65], v[166:169], v[182:185], v[62:65]
	v_mfma_f32_16x16x32_bf16 v[58:61], v[174:177], v[182:185], v[58:61]
	v_mfma_f32_16x16x32_bf16 v[54:57], v[166:169], v[190:193], v[54:57]
	v_mfma_f32_16x16x32_bf16 v[50:53], v[174:177], v[190:193], v[50:53]
	v_mfma_f32_16x16x32_bf16 v[46:49], v[166:169], v[198:201], v[46:49]
	v_mfma_f32_16x16x32_bf16 v[42:45], v[174:177], v[198:201], v[42:45]
	v_mfma_f32_16x16x32_bf16 v[38:41], v[166:169], v[218:221], v[38:41]
	v_mfma_f32_16x16x32_bf16 v[34:37], v[174:177], v[218:221], v[34:37]
	s_nop 0
	s_barrier
; #define G8_STAGE(bufoff, gbase, voff) do { _Pragma("unroll") for (int _i = 0; _i < 2; ++_i) \
;         __builtin_amdgcn_global_load_lds((const unsigned*)((const char*)(gbase) + (voff)[_i]), (LAS unsigned*)(lds + (bufoff) + ldsw + _i * 8192), 16, 0, 0); } while (0)
; #define G8_LDA(dst, b, h) do { _Pragma("unroll") for (int m = 0; m < 4; ++m) _Pragma("unroll") for (int k = 0; k < 2; ++k) dst[m][k] = *(const LAS bf16x8*)(lds + G8_SA(b, h) + aoff + m * 2048 + k * 1024); } while (0)
; #define G8_MMA(ai, bj, At, Bt) do { __builtin_amdgcn_s_setprio(1); _Pragma("unroll") for (int m = 0; m < 4; ++m) _Pragma("unroll") for (int n = 0; n < 2; ++n) _Pragma("unroll") for (int k = 0; k < 2; ++k) \
;         acc[ai][bj][m][n] = __builtin_amdgcn_mfma_f32_16x16x32_bf16(Bt[n][k], At[m][k], acc[ai][bj][m][n], 0, 0, 0); __builtin_amdgcn_s_setprio(0); } while (0)
; #define G8_WAIT_V(n) asm volatile("s_waitcnt vmcnt(" #n ")" ::: "memory")
; #define G8_WAIT_L(n) asm volatile("s_waitcnt lgkmcnt(" #n ")" ::: "memory")
; #define G8_BAR __builtin_amdgcn_s_barrier()
; #define G8_SCHED __builtin_amdgcn_sched_barrier(0)
; template <class Epi, class Sched>
; DEV void gemm_phase(LAS char* lds, const Sched& S, const Epi& E) {
;     ...
;             G8_LDA(At, 1, 1); G8_STAGE(G8_SB(1, 0), b3, voffB); G8_STAGE(G8_SB(1, 1), b3 + hstepB, voffB); G8_STAGE(G8_SA(1, 0), a3, voffA);
;             G8_WAIT_V(8); G8_WAIT_L(0); G8_BAR; G8_MMA(1, 0, At, B0); G8_MMA(1, 1, At, B1); G8_BAR; G8_SCHED;
;         }
;         if (wr == 0) G8_BAR;
	s_add_i32 s55, s50, s46
	v_lshl_add_u64 v[0:1], v[0:1], 0, s[22:23]
	s_mov_b32 m0, s55
	ds_read_b128 v[178:181], v208 offset:49152
	ds_read_b128 v[182:185], v208 offset:50176
	ds_read_b128 v[186:189], v208 offset:51200
	ds_read_b128 v[190:193], v208 offset:52224
	ds_read_b128 v[194:197], v208 offset:53248
	ds_read_b128 v[198:201], v208 offset:54272
	ds_read_b128 v[214:217], v208 offset:55296
	ds_read_b128 v[218:221], v208 offset:56320
	global_load_lds_dwordx4 v[0:1], off
	s_add_i32 m0, s55, 0x2000
	s_add_u32 s56, s56, 0x200080
	v_lshl_add_u64 v[0:1], v[222:223], 0, s[22:23]
	s_addc_u32 s57, s57, 0
	s_add_i32 s55, s51, s46
	global_load_lds_dwordx4 v[0:1], off
	v_lshl_add_u64 v[0:1], s[56:57], 0, v[132:133]
	s_mov_b32 m0, s55
	s_nop 0
	global_load_lds_dwordx4 v[0:1], off
	v_lshl_add_u64 v[0:1], s[56:57], 0, v[136:137]
	s_add_i32 m0, s55, 0x2000
	s_nop 0
	global_load_lds_dwordx4 v[0:1], off
	v_lshl_add_u64 v[0:1], s[42:43], 0, v[130:131]
	s_mov_b32 m0, s78
	s_nop 0
	global_load_lds_dwordx4 v[0:1], off
	v_lshl_add_u64 v[0:1], s[42:43], 0, v[134:135]
	s_mov_b32 m0, s79
	s_nop 0
	global_load_lds_dwordx4 v[0:1], off
	s_waitcnt vmcnt(8)
	s_waitcnt lgkmcnt(0)
	s_barrier
	s_nop 0
	s_waitcnt lgkmcnt(0)
	v_mfma_f32_16x16x32_bf16 v[94:97], v[146:149], v[178:181], v[94:97]
	v_mfma_f32_16x16x32_bf16 v[90:93], v[154:157], v[178:181], v[90:93]
	v_mfma_f32_16x16x32_bf16 v[86:89], v[146:149], v[186:189], v[86:89]
	v_mfma_f32_16x16x32_bf16 v[82:85], v[154:157], v[186:189], v[82:85]
	v_mfma_f32_16x16x32_bf16 v[78:81], v[146:149], v[194:197], v[78:81]
	v_mfma_f32_16x16x32_bf16 v[74:77], v[154:157], v[194:197], v[74:77]
	v_mfma_f32_16x16x32_bf16 v[70:73], v[146:149], v[214:217], v[70:73]
	v_mfma_f32_16x16x32_bf16 v[66:69], v[154:157], v[214:217], v[66:69]
	v_mfma_f32_16x16x32_bf16 v[94:97], v[150:153], v[182:185], v[94:97]
	v_mfma_f32_16x16x32_bf16 v[90:93], v[158:161], v[182:185], v[90:93]
	v_mfma_f32_16x16x32_bf16 v[86:89], v[150:153], v[190:193], v[86:89]
	v_mfma_f32_16x16x32_bf16 v[82:85], v[158:161], v[190:193], v[82:85]
	v_mfma_f32_16x16x32_bf16 v[78:81], v[150:153], v[198:201], v[78:81]
	v_mfma_f32_16x16x32_bf16 v[74:77], v[158:161], v[198:201], v[74:77]
	v_mfma_f32_16x16x32_bf16 v[70:73], v[150:153], v[218:221], v[70:73]
	v_mfma_f32_16x16x32_bf16 v[66:69], v[158:161], v[218:221], v[66:69]
	s_nop 0
	s_nop 0
	v_mfma_f32_16x16x32_bf16 v[30:33], v[162:165], v[178:181], v[30:33]
	v_mfma_f32_16x16x32_bf16 v[26:29], v[170:173], v[178:181], v[26:29]
	v_mfma_f32_16x16x32_bf16 v[22:25], v[162:165], v[186:189], v[22:25]
	v_mfma_f32_16x16x32_bf16 v[18:21], v[170:173], v[186:189], v[18:21]
	v_mfma_f32_16x16x32_bf16 v[14:17], v[162:165], v[194:197], v[14:17]
	v_mfma_f32_16x16x32_bf16 v[10:13], v[170:173], v[194:197], v[10:13]
	v_mfma_f32_16x16x32_bf16 v[6:9], v[162:165], v[214:217], v[6:9]
	v_mfma_f32_16x16x32_bf16 v[2:5], v[170:173], v[214:217], v[2:5]
	v_mfma_f32_16x16x32_bf16 v[30:33], v[166:169], v[182:185], v[30:33]
	v_mfma_f32_16x16x32_bf16 v[26:29], v[174:177], v[182:185], v[26:29]
	v_mfma_f32_16x16x32_bf16 v[22:25], v[166:169], v[190:193], v[22:25]
	v_mfma_f32_16x16x32_bf16 v[18:21], v[174:177], v[190:193], v[18:21]
	v_mfma_f32_16x16x32_bf16 v[14:17], v[166:169], v[198:201], v[14:17]
	v_mfma_f32_16x16x32_bf16 v[10:13], v[174:177], v[198:201], v[10:13]
	v_mfma_f32_16x16x32_bf16 v[6:9], v[166:169], v[218:221], v[6:9]
	v_mfma_f32_16x16x32_bf16 v[2:5], v[174:177], v[218:221], v[2:5]
	s_nop 0
	s_barrier
	s_add_i32 s54, s54, 2
	s_add_u32 s40, s40, 0x100
	s_addc_u32 s41, s41, 0
	s_cmp_gt_u32 s54, 13
	s_cbranch_scc0 .LBB0_1565
	s_and_b64 vcc, exec, s[26:27]
	s_cbranch_vccz .LBB0_1568
	s_barrier

; #define G8_STAGE(bufoff, gbase, voff) do { _Pragma("unroll") for (int _i = 0; _i < 2; ++_i) \
;         __builtin_amdgcn_global_load_lds((const unsigned*)((const char*)(gbase) + (voff)[_i]), (LAS unsigned*)(lds + (bufoff) + ldsw + _i * 8192), 16, 0, 0); } while (0)
; #define G8_LDA(dst, b, h) do { _Pragma("unroll") for (int m = 0; m < 4; ++m) _Pragma("unroll") for (int k = 0; k < 2; ++k) dst[m][k] = *(const LAS bf16x8*)(lds + G8_SA(b, h) + aoff + m * 2048 + k * 1024); } while (0)
; #define G8_LDB(dst, b, h) do { _Pragma("unroll") for (int n = 0; n < 2; ++n) _Pragma("unroll") for (int k = 0; k < 2; ++k) dst[n][k] = *(const LAS bf16x8*)(lds + G8_SB(b, h) + boff + n * 2048 + k * 1024); } while (0)
; #define G8_MMA(ai, bj, At, Bt) do { __builtin_amdgcn_s_setprio(1); _Pragma("unroll") for (int m = 0; m < 4; ++m) _Pragma("unroll") for (int n = 0; n < 2; ++n) _Pragma("unroll") for (int k = 0; k < 2; ++k) \
;         acc[ai][bj][m][n] = __builtin_amdgcn_mfma_f32_16x16x32_bf16(Bt[n][k], At[m][k], acc[ai][bj][m][n], 0, 0, 0); __builtin_amdgcn_s_setprio(0); } while (0)
; #define G8_WAIT_V(n) asm volatile("s_waitcnt vmcnt(" #n ")" ::: "memory")
; #define G8_WAIT_L(n) asm volatile("s_waitcnt lgkmcnt(" #n ")" ::: "memory")
; #define G8_BAR __builtin_amdgcn_s_barrier()
; #define G8_SCHED __builtin_amdgcn_sched_barrier(0)
; template <class Epi, class Sched>
; DEV void gemm_phase(LAS char* lds, const Sched& S, const Epi& E) {
;     ...
;             G8_LDB(B0, 0, 0); G8_LDB(B1, 0, 1); G8_SCHED; G8_LDA(At, 0, 0); G8_STAGE(G8_SA(1, 1), a1 + hstepA, voffA);
;             G8_WAIT_V(8); G8_WAIT_L(0); G8_BAR; G8_MMA(0, 0, At, B0); G8_MMA(0, 1, At, B1); G8_BAR; G8_SCHED;
;             G8_LDA(At, 0, 1); G8_STAGE(G8_SB(0, 0), b2, voffB); G8_STAGE(G8_SB(0, 1), b2 + hstepB, voffB); G8_STAGE(G8_SA(0, 0), a2, voffA);
.LBB0_1698:
	v_add_u32_e32 v140, s62, v186
	v_add_u32_e32 v164, s63, v186
	ds_read_b128 v[128:131], v140
	ds_read_b128 v[132:135], v140 offset:1024
	ds_read_b128 v[136:139], v140 offset:2048
	ds_read_b128 v[140:143], v140 offset:3072
	ds_read_b128 v[144:147], v164
	ds_read_b128 v[148:151], v164 offset:1024
	ds_read_b128 v[160:163], v164 offset:2048
	ds_read_b128 v[164:167], v164 offset:3072
	s_and_b64 s[46:47], exec, s[46:47]
	s_cselect_b32 s47, s31, s76
	s_cselect_b32 s46, s30, s25
	s_add_u32 s80, s58, 0x40000
	s_addc_u32 s81, s78, 0
	v_lshl_add_u64 v[210:211], s[80:81], 0, v[152:153]
	s_add_i32 m0, s53, 0xc000
	ds_read_b128 v[168:171], v190
	ds_read_b128 v[172:175], v190 offset:1024
	ds_read_b128 v[176:179], v190 offset:2048
	ds_read_b128 v[180:183], v190 offset:3072
	ds_read_b128 v[194:197], v190 offset:4096
	ds_read_b128 v[198:201], v190 offset:5120
	ds_read_b128 v[202:205], v190 offset:6144
	ds_read_b128 v[206:209], v190 offset:7168
	global_load_lds_dwordx4 v[210:211], off
	v_lshl_add_u64 v[210:211], s[80:81], 0, v[156:157]
	s_add_i32 m0, s53, 0xe000
	s_nop 0
	global_load_lds_dwordx4 v[210:211], off
	s_waitcnt vmcnt(8)
	s_waitcnt lgkmcnt(0)
	s_barrier
	s_nop 0
	s_waitcnt lgkmcnt(0)
	v_mfma_f32_16x16x32_bf16 v[124:127], v[128:131], v[168:171], v[124:127]
	v_mfma_f32_16x16x32_bf16 v[120:123], v[136:139], v[168:171], v[120:123]
	v_mfma_f32_16x16x32_bf16 v[108:111], v[128:131], v[176:179], v[108:111]
	v_mfma_f32_16x16x32_bf16 v[104:107], v[136:139], v[176:179], v[104:107]
	v_mfma_f32_16x16x32_bf16 v[92:95], v[128:131], v[194:197], v[92:95]
	v_mfma_f32_16x16x32_bf16 v[88:91], v[136:139], v[194:197], v[88:91]
	v_mfma_f32_16x16x32_bf16 v[76:79], v[128:131], v[202:205], v[76:79]
	v_mfma_f32_16x16x32_bf16 v[72:75], v[136:139], v[202:205], v[72:75]
	v_mfma_f32_16x16x32_bf16 v[124:127], v[132:135], v[172:175], v[124:127]
	v_mfma_f32_16x16x32_bf16 v[120:123], v[140:143], v[172:175], v[120:123]
	v_mfma_f32_16x16x32_bf16 v[108:111], v[132:135], v[180:183], v[108:111]
	v_mfma_f32_16x16x32_bf16 v[104:107], v[140:143], v[180:183], v[104:107]
	v_mfma_f32_16x16x32_bf16 v[92:95], v[132:135], v[198:201], v[92:95]
	v_mfma_f32_16x16x32_bf16 v[88:91], v[140:143], v[198:201], v[88:91]
	v_mfma_f32_16x16x32_bf16 v[76:79], v[132:135], v[206:209], v[76:79]
	v_mfma_f32_16x16x32_bf16 v[72:75], v[140:143], v[206:209], v[72:75]
	s_nop 0
	s_nop 0
	v_mfma_f32_16x16x32_bf16 v[116:119], v[144:147], v[168:171], v[116:119]
	v_mfma_f32_16x16x32_bf16 v[112:115], v[160:163], v[168:171], v[112:115]
	v_mfma_f32_16x16x32_bf16 v[100:103], v[144:147], v[176:179], v[100:103]
	v_mfma_f32_16x16x32_bf16 v[96:99], v[160:163], v[176:179], v[96:99]
	v_mfma_f32_16x16x32_bf16 v[84:87], v[144:147], v[194:197], v[84:87]
	v_mfma_f32_16x16x32_bf16 v[80:83], v[160:163], v[194:197], v[80:83]
	v_mfma_f32_16x16x32_bf16 v[68:71], v[144:147], v[202:205], v[68:71]
	v_mfma_f32_16x16x32_bf16 v[64:67], v[160:163], v[202:205], v[64:67]
	v_mfma_f32_16x16x32_bf16 v[116:119], v[148:151], v[172:175], v[116:119]
	v_mfma_f32_16x16x32_bf16 v[112:115], v[164:167], v[172:175], v[112:115]
	v_mfma_f32_16x16x32_bf16 v[100:103], v[148:151], v[180:183], v[100:103]
	v_mfma_f32_16x16x32_bf16 v[96:99], v[164:167], v[180:183], v[96:99]
	v_mfma_f32_16x16x32_bf16 v[84:87], v[148:151], v[198:201], v[84:87]
	v_mfma_f32_16x16x32_bf16 v[80:83], v[164:167], v[198:201], v[80:83]
	v_mfma_f32_16x16x32_bf16 v[68:71], v[148:151], v[206:209], v[68:71]
	v_mfma_f32_16x16x32_bf16 v[64:67], v[164:167], v[206:209], v[64:67]
	s_nop 0
	s_barrier
	s_add_i32 s18, s62, s52
	v_lshl_add_u64 v[210:211], s[46:47], 0, v[154:155]
	s_mov_b32 m0, s18
	ds_read_b128 v[168:171], v190 offset:16384
	ds_read_b128 v[172:175], v190 offset:17408
	ds_read_b128 v[176:179], v190 offset:18432
	ds_read_b128 v[180:183], v190 offset:19456
	ds_read_b128 v[194:197], v190 offset:20480
	ds_read_b128 v[198:201], v190 offset:21504
	ds_read_b128 v[202:205], v190 offset:22528
	ds_read_b128 v[206:209], v190 offset:23552
	global_load_lds_dwordx4 v[210:211], off
	s_add_i32 m0, s18, 0x2000
	s_add_u32 s78, s46, 0x80000
	v_lshl_add_u64 v[212:213], s[46:47], 0, v[158:159]
	s_addc_u32 s79, s47, 0
	s_add_i32 s18, s63, s52
	global_load_lds_dwordx4 v[212:213], off
	v_lshl_add_u64 v[214:215], s[78:79], 0, v[154:155]
	s_mov_b32 m0, s18
	s_nop 0
	global_load_lds_dwordx4 v[214:215], off
	v_lshl_add_u64 v[214:215], s[78:79], 0, v[158:159]
	s_add_i32 m0, s18, 0x2000
	s_nop 0
	global_load_lds_dwordx4 v[214:215], off
	v_lshl_add_u64 v[214:215], s[44:45], 0, v[152:153]
	s_mov_b32 m0, s53
	s_nop 0
	global_load_lds_dwordx4 v[214:215], off
	v_lshl_add_u64 v[214:215], s[44:45], 0, v[156:157]
	s_mov_b32 m0, s54
	s_nop 0
	global_load_lds_dwordx4 v[214:215], off
	s_waitcnt vmcnt(8)
	s_waitcnt lgkmcnt(0)
	s_barrier
; #define G8_STAGE(bufoff, gbase, voff) do { _Pragma("unroll") for (int _i = 0; _i < 2; ++_i) \
;         __builtin_amdgcn_global_load_lds((const unsigned*)((const char*)(gbase) + (voff)[_i]), (LAS unsigned*)(lds + (bufoff) + ldsw + _i * 8192), 16, 0, 0); } while (0)
; #define G8_LDA(dst, b, h) do { _Pragma("unroll") for (int m = 0; m < 4; ++m) _Pragma("unroll") for (int k = 0; k < 2; ++k) dst[m][k] = *(const LAS bf16x8*)(lds + G8_SA(b, h) + aoff + m * 2048 + k * 1024); } while (0)
; #define G8_LDB(dst, b, h) do { _Pragma("unroll") for (int n = 0; n < 2; ++n) _Pragma("unroll") for (int k = 0; k < 2; ++k) dst[n][k] = *(const LAS bf16x8*)(lds + G8_SB(b, h) + boff + n * 2048 + k * 1024); } while (0)
; #define G8_MMA(ai, bj, At, Bt) do { __builtin_amdgcn_s_setprio(1); _Pragma("unroll") for (int m = 0; m < 4; ++m) _Pragma("unroll") for (int n = 0; n < 2; ++n) _Pragma("unroll") for (int k = 0; k < 2; ++k) \
;         acc[ai][bj][m][n] = __builtin_amdgcn_mfma_f32_16x16x32_bf16(Bt[n][k], At[m][k], acc[ai][bj][m][n], 0, 0, 0); __builtin_amdgcn_s_setprio(0); } while (0)
; #define G8_WAIT_V(n) asm volatile("s_waitcnt vmcnt(" #n ")" ::: "memory")
; #define G8_WAIT_L(n) asm volatile("s_waitcnt lgkmcnt(" #n ")" ::: "memory")
; #define G8_BAR __builtin_amdgcn_s_barrier()
; #define G8_SCHED __builtin_amdgcn_sched_barrier(0)
; template <class Epi, class Sched>
; DEV void gemm_phase(LAS char* lds, const Sched& S, const Epi& E) {
;     ...
;             G8_WAIT_V(8); G8_WAIT_L(0); G8_BAR; G8_MMA(1, 0, At, B0); G8_MMA(1, 1, At, B1); G8_BAR; G8_SCHED;
;             G8_LDB(B0, 1, 0); G8_LDB(B1, 1, 1); G8_SCHED; G8_LDA(At, 1, 0); G8_STAGE(G8_SA(0, 1), a2 + hstepA, voffA);
;             G8_WAIT_V(8); G8_WAIT_L(0); G8_BAR; G8_MMA(0, 0, At, B0); G8_MMA(0, 1, At, B1); G8_BAR; G8_SCHED;
	s_nop 0
	s_waitcnt lgkmcnt(0)
	v_mfma_f32_16x16x32_bf16 v[60:63], v[128:131], v[168:171], v[60:63]
	v_mfma_f32_16x16x32_bf16 v[56:59], v[136:139], v[168:171], v[56:59]
	v_mfma_f32_16x16x32_bf16 v[44:47], v[128:131], v[176:179], v[44:47]
	v_mfma_f32_16x16x32_bf16 v[40:43], v[136:139], v[176:179], v[40:43]
	v_mfma_f32_16x16x32_bf16 v[28:31], v[128:131], v[194:197], v[28:31]
	v_mfma_f32_16x16x32_bf16 v[24:27], v[136:139], v[194:197], v[24:27]
	v_mfma_f32_16x16x32_bf16 v[12:15], v[128:131], v[202:205], v[12:15]
	v_mfma_f32_16x16x32_bf16 v[8:11], v[136:139], v[202:205], v[8:11]
	v_mfma_f32_16x16x32_bf16 v[60:63], v[132:135], v[172:175], v[60:63]
	v_mfma_f32_16x16x32_bf16 v[56:59], v[140:143], v[172:175], v[56:59]
	v_mfma_f32_16x16x32_bf16 v[44:47], v[132:135], v[180:183], v[44:47]
	v_mfma_f32_16x16x32_bf16 v[40:43], v[140:143], v[180:183], v[40:43]
	v_mfma_f32_16x16x32_bf16 v[28:31], v[132:135], v[198:201], v[28:31]
	v_mfma_f32_16x16x32_bf16 v[24:27], v[140:143], v[198:201], v[24:27]
	v_mfma_f32_16x16x32_bf16 v[12:15], v[132:135], v[206:209], v[12:15]
	v_mfma_f32_16x16x32_bf16 v[8:11], v[140:143], v[206:209], v[8:11]
	s_nop 0
	s_nop 0
	v_mfma_f32_16x16x32_bf16 v[52:55], v[144:147], v[168:171], v[52:55]
	v_mfma_f32_16x16x32_bf16 v[48:51], v[160:163], v[168:171], v[48:51]
	v_mfma_f32_16x16x32_bf16 v[36:39], v[144:147], v[176:179], v[36:39]
	v_mfma_f32_16x16x32_bf16 v[32:35], v[160:163], v[176:179], v[32:35]
	v_mfma_f32_16x16x32_bf16 v[20:23], v[144:147], v[194:197], v[20:23]
	v_mfma_f32_16x16x32_bf16 v[16:19], v[160:163], v[194:197], v[16:19]
	v_mfma_f32_16x16x32_bf16 v[4:7], v[144:147], v[202:205], v[4:7]
	v_mfma_f32_16x16x32_bf16 v[0:3], v[160:163], v[202:205], v[0:3]
	v_mfma_f32_16x16x32_bf16 v[52:55], v[148:151], v[172:175], v[52:55]
	v_mfma_f32_16x16x32_bf16 v[48:51], v[164:167], v[172:175], v[48:51]
	v_mfma_f32_16x16x32_bf16 v[36:39], v[148:151], v[180:183], v[36:39]
	v_mfma_f32_16x16x32_bf16 v[32:35], v[164:167], v[180:183], v[32:35]
	v_mfma_f32_16x16x32_bf16 v[20:23], v[148:151], v[198:201], v[20:23]
	v_mfma_f32_16x16x32_bf16 v[16:19], v[164:167], v[198:201], v[16:19]
	v_mfma_f32_16x16x32_bf16 v[4:7], v[148:151], v[206:209], v[4:7]
	v_mfma_f32_16x16x32_bf16 v[0:3], v[164:167], v[206:209], v[0:3]
	s_nop 0
	s_barrier
	v_add_u32_e32 v140, s50, v186
	v_add_u32_e32 v164, s51, v186
	ds_read_b128 v[128:131], v140
	ds_read_b128 v[132:135], v140 offset:1024
	ds_read_b128 v[136:139], v140 offset:2048
	ds_read_b128 v[140:143], v140 offset:3072
	ds_read_b128 v[144:147], v164
	ds_read_b128 v[148:151], v164 offset:1024
	ds_read_b128 v[160:163], v164 offset:2048
	ds_read_b128 v[164:167], v164 offset:3072
	s_add_u32 s44, s44, 0x40000
	s_addc_u32 s45, s45, 0
	s_mov_b32 m0, s55
	v_lshl_add_u64 v[214:215], s[44:45], 0, v[152:153]
	ds_read_b128 v[168:171], v190 offset:32768
	ds_read_b128 v[172:175], v190 offset:33792
	ds_read_b128 v[176:179], v190 offset:34816
	ds_read_b128 v[180:183], v190 offset:35840
	ds_read_b128 v[194:197], v190 offset:36864
	ds_read_b128 v[198:201], v190 offset:37888
	ds_read_b128 v[202:205], v190 offset:38912
	ds_read_b128 v[206:209], v190 offset:39936
	global_load_lds_dwordx4 v[214:215], off
	v_lshl_add_u64 v[214:215], s[44:45], 0, v[156:157]
	s_mov_b32 m0, s56
	s_nop 0
	global_load_lds_dwordx4 v[214:215], off
	s_waitcnt vmcnt(8)
	s_waitcnt lgkmcnt(0)
	s_barrier
	s_nop 0
	s_waitcnt lgkmcnt(0)
	v_mfma_f32_16x16x32_bf16 v[124:127], v[128:131], v[168:171], v[124:127]
	v_mfma_f32_16x16x32_bf16 v[120:123], v[136:139], v[168:171], v[120:123]
	v_mfma_f32_16x16x32_bf16 v[108:111], v[128:131], v[176:179], v[108:111]
	v_mfma_f32_16x16x32_bf16 v[104:107], v[136:139], v[176:179], v[104:107]
	v_mfma_f32_16x16x32_bf16 v[92:95], v[128:131], v[194:197], v[92:95]
	v_mfma_f32_16x16x32_bf16 v[88:91], v[136:139], v[194:197], v[88:91]
	v_mfma_f32_16x16x32_bf16 v[76:79], v[128:131], v[202:205], v[76:79]
	v_mfma_f32_16x16x32_bf16 v[72:75], v[136:139], v[202:205], v[72:75]
	v_mfma_f32_16x16x32_bf16 v[124:127], v[132:135], v[172:175], v[124:127]
	v_mfma_f32_16x16x32_bf16 v[120:123], v[140:143], v[172:175], v[120:123]
	v_mfma_f32_16x16x32_bf16 v[108:111], v[132:135], v[180:183], v[108:111]
	v_mfma_f32_16x16x32_bf16 v[104:107], v[140:143], v[180:183], v[104:107]
	v_mfma_f32_16x16x32_bf16 v[92:95], v[132:135], v[198:201], v[92:95]
	v_mfma_f32_16x16x32_bf16 v[88:91], v[140:143], v[198:201], v[88:91]
	v_mfma_f32_16x16x32_bf16 v[76:79], v[132:135], v[206:209], v[76:79]
	v_mfma_f32_16x16x32_bf16 v[72:75], v[140:143], v[206:209], v[72:75]
	s_nop 0
	s_nop 0
	v_mfma_f32_16x16x32_bf16 v[116:119], v[144:147], v[168:171], v[116:119]
	v_mfma_f32_16x16x32_bf16 v[112:115], v[160:163], v[168:171], v[112:115]
	v_mfma_f32_16x16x32_bf16 v[100:103], v[144:147], v[176:179], v[100:103]
	v_mfma_f32_16x16x32_bf16 v[96:99], v[160:163], v[176:179], v[96:99]
	v_mfma_f32_16x16x32_bf16 v[84:87], v[144:147], v[194:197], v[84:87]
	v_mfma_f32_16x16x32_bf16 v[80:83], v[160:163], v[194:197], v[80:83]
	v_mfma_f32_16x16x32_bf16 v[68:71], v[144:147], v[202:205], v[68:71]
	v_mfma_f32_16x16x32_bf16 v[64:67], v[160:163], v[202:205], v[64:67]
	v_mfma_f32_16x16x32_bf16 v[116:119], v[148:151], v[172:175], v[116:119]
	v_mfma_f32_16x16x32_bf16 v[112:115], v[164:167], v[172:175], v[112:115]
	v_mfma_f32_16x16x32_bf16 v[100:103], v[148:151], v[180:183], v[100:103]
	v_mfma_f32_16x16x32_bf16 v[96:99], v[164:167], v[180:183], v[96:99]
	v_mfma_f32_16x16x32_bf16 v[84:87], v[148:151], v[198:201], v[84:87]
	v_mfma_f32_16x16x32_bf16 v[80:83], v[164:167], v[198:201], v[80:83]
	v_mfma_f32_16x16x32_bf16 v[68:71], v[148:151], v[206:209], v[68:71]
	v_mfma_f32_16x16x32_bf16 v[64:67], v[164:167], v[206:209], v[64:67]
	s_nop 0
	s_barrier
; #define G8_STAGE(bufoff, gbase, voff) do { _Pragma("unroll") for (int _i = 0; _i < 2; ++_i) \
;         __builtin_amdgcn_global_load_lds((const unsigned*)((const char*)(gbase) + (voff)[_i]), (LAS unsigned*)(lds + (bufoff) + ldsw + _i * 8192), 16, 0, 0); } while (0)
; #define G8_LDA(dst, b, h) do { _Pragma("unroll") for (int m = 0; m < 4; ++m) _Pragma("unroll") for (int k = 0; k < 2; ++k) dst[m][k] = *(const LAS bf16x8*)(lds + G8_SA(b, h) + aoff + m * 2048 + k * 1024); } while (0)
; #define G8_MMA(ai, bj, At, Bt) do { __builtin_amdgcn_s_setprio(1); _Pragma("unroll") for (int m = 0; m < 4; ++m) _Pragma("unroll") for (int n = 0; n < 2; ++n) _Pragma("unroll") for (int k = 0; k < 2; ++k) \
;         acc[ai][bj][m][n] = __builtin_amdgcn_mfma_f32_16x16x32_bf16(Bt[n][k], At[m][k], acc[ai][bj][m][n], 0, 0, 0); __builtin_amdgcn_s_setprio(0); } while (0)
; #define G8_WAIT_V(n) asm volatile("s_waitcnt vmcnt(" #n ")" ::: "memory")
; #define G8_WAIT_L(n) asm volatile("s_waitcnt lgkmcnt(" #n ")" ::: "memory")
; #define G8_BAR __builtin_amdgcn_s_barrier()
; #define G8_SCHED __builtin_amdgcn_sched_barrier(0)
; template <class Epi, class Sched>
; DEV void gemm_phase(LAS char* lds, const Sched& S, const Epi& E) {
;     ...
;             G8_LDA(At, 1, 1); G8_STAGE(G8_SB(1, 0), b3, voffB); G8_STAGE(G8_SB(1, 1), b3 + hstepB, voffB); G8_STAGE(G8_SA(1, 0), a3, voffA);
;             G8_WAIT_V(8); G8_WAIT_L(0); G8_BAR; G8_MMA(1, 0, At, B0); G8_MMA(1, 1, At, B1); G8_BAR; G8_SCHED;
;         }
	s_add_i32 s18, s50, s52
	v_lshl_add_u64 v[210:211], v[210:211], 0, s[16:17]
	s_mov_b32 m0, s18
	ds_read_b128 v[168:171], v190 offset:49152
	ds_read_b128 v[172:175], v190 offset:50176
	ds_read_b128 v[176:179], v190 offset:51200
	ds_read_b128 v[180:183], v190 offset:52224
	ds_read_b128 v[194:197], v190 offset:53248
	ds_read_b128 v[198:201], v190 offset:54272
	ds_read_b128 v[202:205], v190 offset:55296
	ds_read_b128 v[206:209], v190 offset:56320
	global_load_lds_dwordx4 v[210:211], off
	s_add_i32 m0, s18, 0x2000
	s_add_u32 s44, s46, 0x80080
	v_lshl_add_u64 v[210:211], v[212:213], 0, s[16:17]
	s_addc_u32 s45, s47, 0
	s_add_i32 s18, s51, s52
	global_load_lds_dwordx4 v[210:211], off
	v_lshl_add_u64 v[210:211], s[44:45], 0, v[154:155]
	s_mov_b32 m0, s18
	s_nop 0
	global_load_lds_dwordx4 v[210:211], off
	v_lshl_add_u64 v[210:211], s[44:45], 0, v[158:159]
	s_add_i32 m0, s18, 0x2000
	s_nop 0
	global_load_lds_dwordx4 v[210:211], off
	v_lshl_add_u64 v[210:211], s[42:43], 0, v[152:153]
	s_mov_b32 m0, s68
	s_nop 0
	global_load_lds_dwordx4 v[210:211], off
	v_lshl_add_u64 v[210:211], s[42:43], 0, v[156:157]
	s_mov_b32 m0, s69
	s_nop 0
	global_load_lds_dwordx4 v[210:211], off
	s_waitcnt vmcnt(8)
	s_waitcnt lgkmcnt(0)
	s_barrier
	s_nop 0
	s_waitcnt lgkmcnt(0)
	v_mfma_f32_16x16x32_bf16 v[60:63], v[128:131], v[168:171], v[60:63]
	v_mfma_f32_16x16x32_bf16 v[56:59], v[136:139], v[168:171], v[56:59]
	v_mfma_f32_16x16x32_bf16 v[44:47], v[128:131], v[176:179], v[44:47]
	v_mfma_f32_16x16x32_bf16 v[40:43], v[136:139], v[176:179], v[40:43]
	v_mfma_f32_16x16x32_bf16 v[28:31], v[128:131], v[194:197], v[28:31]
	v_mfma_f32_16x16x32_bf16 v[24:27], v[136:139], v[194:197], v[24:27]
	v_mfma_f32_16x16x32_bf16 v[12:15], v[128:131], v[202:205], v[12:15]
	v_mfma_f32_16x16x32_bf16 v[8:11], v[136:139], v[202:205], v[8:11]
	v_mfma_f32_16x16x32_bf16 v[60:63], v[132:135], v[172:175], v[60:63]
	v_mfma_f32_16x16x32_bf16 v[56:59], v[140:143], v[172:175], v[56:59]
	v_mfma_f32_16x16x32_bf16 v[44:47], v[132:135], v[180:183], v[44:47]
	v_mfma_f32_16x16x32_bf16 v[40:43], v[140:143], v[180:183], v[40:43]
	v_mfma_f32_16x16x32_bf16 v[28:31], v[132:135], v[198:201], v[28:31]
	v_mfma_f32_16x16x32_bf16 v[24:27], v[140:143], v[198:201], v[24:27]
	v_mfma_f32_16x16x32_bf16 v[12:15], v[132:135], v[206:209], v[12:15]
	v_mfma_f32_16x16x32_bf16 v[8:11], v[140:143], v[206:209], v[8:11]
	s_nop 0
	s_nop 0
	v_mfma_f32_16x16x32_bf16 v[52:55], v[144:147], v[168:171], v[52:55]
	v_mfma_f32_16x16x32_bf16 v[48:51], v[160:163], v[168:171], v[48:51]
	v_mfma_f32_16x16x32_bf16 v[36:39], v[144:147], v[176:179], v[36:39]
	v_mfma_f32_16x16x32_bf16 v[32:35], v[160:163], v[176:179], v[32:35]
	v_mfma_f32_16x16x32_bf16 v[20:23], v[144:147], v[194:197], v[20:23]
	v_mfma_f32_16x16x32_bf16 v[16:19], v[160:163], v[194:197], v[16:19]
	v_mfma_f32_16x16x32_bf16 v[4:7], v[144:147], v[202:205], v[4:7]
	v_mfma_f32_16x16x32_bf16 v[0:3], v[160:163], v[202:205], v[0:3]
	v_mfma_f32_16x16x32_bf16 v[52:55], v[148:151], v[172:175], v[52:55]
	v_mfma_f32_16x16x32_bf16 v[48:51], v[164:167], v[172:175], v[48:51]
	v_mfma_f32_16x16x32_bf16 v[36:39], v[148:151], v[180:183], v[36:39]
	v_mfma_f32_16x16x32_bf16 v[32:35], v[164:167], v[180:183], v[32:35]
	v_mfma_f32_16x16x32_bf16 v[20:23], v[148:151], v[198:201], v[20:23]
	v_mfma_f32_16x16x32_bf16 v[16:19], v[164:167], v[198:201], v[16:19]
	v_mfma_f32_16x16x32_bf16 v[4:7], v[148:151], v[206:209], v[4:7]
	v_mfma_f32_16x16x32_bf16 v[0:3], v[164:167], v[206:209], v[0:3]
	s_nop 0
	s_barrier
	s_add_i32 s18, s77, 2
	s_add_u32 s40, s40, 0x100
	s_addc_u32 s41, s41, 0
	s_add_u32 s25, s25, 0x100
	s_addc_u32 s76, s76, 0
	s_cmp_gt_u32 s77, 29
	s_mov_b32 s77, s18
	s_cbranch_scc1 .LBB0_1707
